# DFT GEMM output-side folding: rows sp and S-sp share cos/sin partial sums (f32 snapshot), half the Fourier units skipped
# speedup vs baseline: 1.0301x; 1.0301x over previous
.LBB0_562:
	s_or_b64 exec, exec, s[0:1]
	v_mov_b32_e32 v0, s11
	s_waitcnt lgkmcnt(0)
	s_barrier
	ds_read_b32 v0, v0
	s_movk_i32 s0, 0x4ff
	s_waitcnt lgkmcnt(0)
	v_cmp_lt_i32_e32 vcc, s0, v0
	v_readfirstlane_b32 s77, v0
	s_mov_b64 s[0:1], -1
	s_cbranch_vccnz .LBB0_559
	s_cmpk_gt_i32 s77, 0x1ff
	s_cbranch_scc0 .LBB0_612
	s_cmpk_gt_u32 s77, 0x27f
	s_cbranch_scc0 .LBB0_603
	s_cmpk_gt_u32 s77, 0x47f
	s_cbranch_scc0 .LBB0_573
	s_add_i32 s0, s77, 0xfffffb80
	s_lshr_b32 s52, s0, 4
	s_lshl_b32 s0, s77, 7
	s_and_b32 s58, s0, 0x700
	s_cmpk_gt_u32 s58, 0x400
	s_cbranch_scc1 .Ldfs_skip
	s_movk_i32 s100, 0x100
	s_mov_b32 s101, 0
	s_mov_b64 s[42:43], s[94:95]
	s_lshl_b32 s0, s58, 14
	s_add_u32 s48, s42, s0
	s_addc_u32 s49, s43, 0
	s_add_u32 s34, s48, 0x2b00000
	s_mov_b64 s[0:1], s[94:95]
	s_addc_u32 s35, s49, 0
	s_lshl_b64 s[36:37], s[52:53], 21
	s_add_u32 s0, s0, s36
	s_addc_u32 s1, s1, s37
	s_lshl_b32 s3, s77, 8
	s_and_b32 s3, s3, 0x100
	s_lshl_b32 s36, s3, 12
	s_add_u32 s62, s0, s36
	s_addc_u32 s63, s1, 0
	s_mov_b64 s[36:37], s[94:95]
	s_mov_b64 s[0:1], s[94:95]
	v_mov_b32_e32 v140, v226
	s_mov_b32 s7, 0xfffe0
	v_ashrrev_i32_e32 v1, 31, v140
	v_lshrrev_b32_e32 v1, 26, v1
	v_add_u32_e32 v1, v140, v1
	v_ashrrev_i32_e32 v8, 6, v1
	v_bfe_i32 v1, v140, 27, 1
	v_lshlrev_b32_e32 v0, 4, v140
	v_lshrrev_b32_e32 v1, 22, v1
	v_add_u32_e32 v1, v0, v1
	v_and_b32_e32 v1, 0xfffffc00, v1
	v_sub_u32_e32 v1, v0, v1
	v_lshrrev_b32_e32 v2, 4, v1
	v_bitop3_b32 v2, v2, v1, 32 bitop3:0x6c
	v_ashrrev_i32_e32 v1, 31, v1
	v_lshrrev_b32_e32 v1, 26, v1
	v_add_u32_e32 v1, v2, v1
	v_ashrrev_i32_e32 v9, 6, v1
	v_lshlrev_b32_e32 v3, 3, v8
	v_mul_i32_i24_e32 v4, 64, v9
	v_and_b32_e32 v3, -16, v3
	v_sub_u32_e32 v2, v2, v4
	v_add_u32_e32 v1, v9, v3
	v_lshlrev_b32_e32 v3, 5, v8
	v_ashrrev_i16_sdwa v2, v230, sext(v2) dst_sel:DWORD dst_unused:UNUSED_PAD src0_sel:DWORD src1_sel:BYTE_0
	v_and_b32_e32 v3, 32, v3
	v_bfe_i32 v10, v2, 0, 16
	v_and_b32_e32 v5, 3, v9
	v_add_lshl_u32 v3, v3, v10, 1
	v_add_u32_e32 v0, 0x2000, v0
	v_lshlrev_b32_e32 v2, 1, v1
	v_lshrrev_b32_e32 v4, 2, v1
	v_and_or_b32 v5, v1, s7, v5
	v_lshl_add_u32 v130, v1, 14, v3
	v_ashrrev_i32_e32 v1, 31, v0
	v_lshrrev_b32_e32 v1, 22, v1
	v_add_u32_e32 v1, v0, v1
	v_ashrrev_i32_e32 v11, 10, v1
	v_mul_i32_i24_e32 v1, 0x400, v11
	v_sub_u32_e32 v0, v0, v1
	v_and_b32_e32 v2, 24, v2
	v_and_b32_e32 v4, 4, v4
	v_lshrrev_b32_e32 v1, 4, v0
	v_or3_b32 v2, v5, v4, v2
	v_bitop3_b32 v0, v1, v0, 32 bitop3:0x6c
	v_lshl_add_u32 v176, v2, 12, v3
	v_ashrrev_i32_e32 v2, 31, v0
	v_lshrrev_b32_e32 v2, 26, v2
	v_add_u32_e32 v2, v0, v2
	s_add_u32 s40, s62, 0xfb00000
	v_readfirstlane_b32 s59, v140
	v_lshlrev_b32_e32 v1, 3, v11
	v_ashrrev_i32_e32 v12, 6, v2
	v_and_b32_e32 v2, 0xc0, v2
	s_addc_u32 s41, s63, 0
	s_ashr_i32 s46, s59, 6
	v_and_b32_e32 v1, -16, v1
	v_sub_u32_e32 v0, v0, v2
	v_add_u32_e32 v1, v12, v1
	v_ashrrev_i16_sdwa v0, v230, sext(v0) dst_sel:DWORD dst_unused:UNUSED_PAD src0_sel:DWORD src1_sel:BYTE_0
	s_lshl_b32 s60, s46, 10
	v_lshlrev_b32_e32 v3, 5, v11
	v_bfe_i32 v13, v0, 0, 16
	v_lshlrev_b32_e32 v0, 1, v1
	v_lshrrev_b32_e32 v2, 2, v1
	v_and_b32_e32 v4, 3, v12
	s_add_i32 s61, s60, 0
	v_and_b32_e32 v3, 32, v3
	v_and_b32_e32 v0, 24, v0
	v_and_b32_e32 v2, 4, v2
	v_and_or_b32 v4, v1, s7, v4
	s_add_i32 m0, s61, 0x10000
	v_or3_b32 v0, v4, v2, v0
	v_add_lshl_u32 v2, v3, v13, 1
	s_ashr_i32 s47, s59, 8
	global_load_lds_dwordx4 v176, s[40:41]
	s_add_i32 m0, s61, 0x12000
	v_lshl_add_u32 v134, v0, 12, v2
	s_add_u32 s62, s62, 0xfb80000
	global_load_lds_dwordx4 v134, s[40:41]
	s_addc_u32 s63, s63, 0
	s_add_i32 m0, s61, 0x14000
	v_lshl_add_u32 v132, v1, 14, v2
	global_load_lds_dwordx4 v176, s[62:63]
	s_add_i32 m0, s61, 0x16000
	v_mov_b32_e32 v135, v177
	global_load_lds_dwordx4 v134, s[62:63]
	s_add_i32 s62, s61, 0x2000
	s_mov_b32 m0, s61
	s_add_u32 s68, s48, 0x2d00000
	global_load_lds_dwordx4 v130, s[34:35]
	s_mov_b32 m0, s62
	s_addc_u32 s69, s49, 0
	s_add_i32 s63, s61, 0x4000
	global_load_lds_dwordx4 v132, s[34:35]
	s_mov_b32 m0, s63
	s_add_i32 s70, s61, 0x6000
	global_load_lds_dwordx4 v130, s[68:69]
	s_mov_b32 m0, s70
	v_mov_b32_e32 v131, v177
	global_load_lds_dwordx4 v132, s[68:69]
	v_mov_b32_e32 v133, v177
	v_lshl_add_u64 v[6:7], s[40:41], 0, v[176:177]
	v_lshl_add_u64 v[4:5], s[40:41], 0, v[134:135]
	v_lshl_add_u64 v[2:3], s[34:35], 0, v[130:131]
	s_cmp_lg_u32 s47, 1
	v_lshl_add_u64 v[0:1], s[34:35], 0, v[132:133]
	s_cbranch_scc1 .LBB0_568
	s_barrier
.LBB0_568:
	v_lshrrev_b32_e32 v15, 1, v140
	v_and_b32_e32 v129, 24, v15
	v_and_b32_e32 v14, 15, v140
	v_lshlrev_b32_e32 v15, 1, v129
	s_lshl_b32 s46, s46, 5
	v_lshl_or_b32 v128, s47, 6, v14
	v_lshl_or_b32 v14, v14, 6, v15
	v_lshlrev_b32_e32 v15, 2, v140
	s_and_b32 s71, s46, 0x60
	s_add_i32 m0, s61, 0x18000
	v_lshl_add_u64 v[6:7], v[6:7], 0, s[100:101]
	v_and_b32_e32 v15, 32, v15
	s_lshl_b32 s47, s47, 13
	s_lshl_b32 s46, s71, 7
	s_waitcnt vmcnt(2)
	s_barrier
	global_load_lds_dwordx4 v[6:7], off
	v_lshl_add_u64 v[4:5], v[4:5], 0, s[100:101]
	s_add_i32 m0, s61, 0x1a000
	s_add_i32 s72, s61, 0x8000
	s_add_i32 s73, s61, 0xa000
	v_bitop3_b32 v141, v14, s46, v15 bitop3:0xde
	global_load_lds_dwordx4 v[4:5], off
	v_lshl_add_u64 v[2:3], v[2:3], 0, s[100:101]
	s_mov_b32 m0, s72
	s_add_u32 s46, s40, 0x80100
	v_bitop3_b32 v16, v14, s47, v15 bitop3:0xde
	global_load_lds_dwordx4 v[2:3], off
	v_lshl_add_u64 v[0:1], v[0:1], 0, s[100:101]
	s_mov_b32 m0, s73
	s_addc_u32 s47, s41, 0
	global_load_lds_dwordx4 v[0:1], off
	s_add_i32 m0, s61, 0x1c000
	v_lshl_add_u64 v[0:1], s[46:47], 0, v[176:177]
	global_load_lds_dwordx4 v[0:1], off
	v_lshl_add_u64 v[0:1], s[46:47], 0, v[134:135]
	s_add_i32 m0, s61, 0x1e000
	s_lshl_b32 s46, s77, 21
	global_load_lds_dwordx4 v[0:1], off
	v_lshlrev_b32_e32 v0, 17, v11
	v_and_b32_e32 v0, 0xfffc0000, v0
	s_and_b32 s46, s46, 0x1c00000
	v_lshl_add_u32 v0, v12, 14, v0
	v_and_b32_e32 v1, 1, v11
	v_lshl_or_b32 v0, v1, 6, v0
	s_add_u32 s42, s42, s46
	v_lshl_add_u32 v0, v13, 1, v0
	v_mov_b32_e32 v1, v177
	s_addc_u32 s43, s43, 0
	v_lshl_add_u64 v[136:137], s[42:43], 0, v[0:1]
	v_lshlrev_b32_e32 v0, 17, v8
	v_and_b32_e32 v0, 0xfffc0000, v0
	v_lshl_add_u32 v0, v9, 14, v0
	v_and_b32_e32 v1, 1, v8
	v_lshl_or_b32 v0, v1, 6, v0
	s_waitcnt vmcnt(6)
	v_lshl_add_u32 v0, v10, 1, v0
	v_mov_b32_e32 v1, v177
	v_lshl_add_u64 v[138:139], s[42:43], 0, v[0:1]
	v_mov_b32_e32 v0, 0
	s_mov_b32 s78, -2
	s_mov_b64 s[42:43], 0x2d00100
	v_add_u32_e32 v142, 0, v16
	v_mov_b32_e32 v1, v0
	v_mov_b32_e32 v2, v0
	v_mov_b32_e32 v3, v0
	v_mov_b32_e32 v4, v0
	v_mov_b32_e32 v5, v0
	v_mov_b32_e32 v6, v0
	v_mov_b32_e32 v7, v0
	v_mov_b32_e32 v8, v0
	v_mov_b32_e32 v9, v0
	v_mov_b32_e32 v10, v0
	v_mov_b32_e32 v11, v0
	v_mov_b32_e32 v16, v0
	v_mov_b32_e32 v17, v0
	v_mov_b32_e32 v18, v0
	v_mov_b32_e32 v19, v0
	v_mov_b32_e32 v24, v0
	v_mov_b32_e32 v25, v0
	v_mov_b32_e32 v26, v0
	v_mov_b32_e32 v27, v0
	v_mov_b32_e32 v32, v0
	v_mov_b32_e32 v33, v0
	v_mov_b32_e32 v34, v0
	v_mov_b32_e32 v35, v0
	v_mov_b32_e32 v40, v0
	v_mov_b32_e32 v41, v0
	v_mov_b32_e32 v42, v0
	v_mov_b32_e32 v43, v0
	v_mov_b32_e32 v48, v0
	v_mov_b32_e32 v49, v0
	v_mov_b32_e32 v50, v0
	v_mov_b32_e32 v51, v0
	v_mov_b32_e32 v12, v0
	v_mov_b32_e32 v13, v0
	v_mov_b32_e32 v14, v0
	v_mov_b32_e32 v15, v0
	v_mov_b32_e32 v20, v0
	v_mov_b32_e32 v21, v0
	v_mov_b32_e32 v22, v0
	v_mov_b32_e32 v23, v0
	v_mov_b32_e32 v28, v0
	v_mov_b32_e32 v29, v0
	v_mov_b32_e32 v30, v0
	v_mov_b32_e32 v31, v0
	v_mov_b32_e32 v36, v0
	v_mov_b32_e32 v37, v0
	v_mov_b32_e32 v38, v0
	v_mov_b32_e32 v39, v0
	v_mov_b32_e32 v44, v0
	v_mov_b32_e32 v45, v0
	v_mov_b32_e32 v46, v0
	v_mov_b32_e32 v47, v0
	v_mov_b32_e32 v52, v0
	v_mov_b32_e32 v53, v0
	v_mov_b32_e32 v54, v0
	v_mov_b32_e32 v55, v0
	v_mov_b32_e32 v56, v0
	v_mov_b32_e32 v57, v0
	v_mov_b32_e32 v58, v0
	v_mov_b32_e32 v59, v0
	v_mov_b32_e32 v60, v0
	v_mov_b32_e32 v61, v0
	v_mov_b32_e32 v62, v0
	v_mov_b32_e32 v63, v0
	v_mov_b32_e32 v64, v0
	v_mov_b32_e32 v65, v0
	v_mov_b32_e32 v66, v0
	v_mov_b32_e32 v67, v0
	v_mov_b32_e32 v68, v0
	v_mov_b32_e32 v69, v0
	v_mov_b32_e32 v70, v0
	v_mov_b32_e32 v71, v0
	v_mov_b32_e32 v72, v0
	v_mov_b32_e32 v73, v0
	v_mov_b32_e32 v74, v0
	v_mov_b32_e32 v75, v0
	v_mov_b32_e32 v80, v0
	v_mov_b32_e32 v81, v0
	v_mov_b32_e32 v82, v0
	v_mov_b32_e32 v83, v0
	v_mov_b32_e32 v88, v0
	v_mov_b32_e32 v89, v0
	v_mov_b32_e32 v90, v0
	v_mov_b32_e32 v91, v0
	s_waitcnt vmcnt(0)
	v_mov_b32_e32 v96, v0
	v_mov_b32_e32 v97, v0
	v_mov_b32_e32 v98, v0
	v_mov_b32_e32 v99, v0
	v_mov_b32_e32 v112, v0
	v_mov_b32_e32 v113, v0
	v_mov_b32_e32 v114, v0
	v_mov_b32_e32 v115, v0
	v_mov_b32_e32 v116, v0
	v_mov_b32_e32 v117, v0
	v_mov_b32_e32 v118, v0
	v_mov_b32_e32 v119, v0
	v_mov_b32_e32 v76, v0
	v_mov_b32_e32 v77, v0
	v_mov_b32_e32 v78, v0
	v_mov_b32_e32 v79, v0
	v_mov_b32_e32 v84, v0
	v_mov_b32_e32 v85, v0
	v_mov_b32_e32 v86, v0
	v_mov_b32_e32 v87, v0
	v_mov_b32_e32 v92, v0
	v_mov_b32_e32 v93, v0
	v_mov_b32_e32 v94, v0
	v_mov_b32_e32 v95, v0
	v_mov_b32_e32 v100, v0
	v_mov_b32_e32 v101, v0
	v_mov_b32_e32 v102, v0
	v_mov_b32_e32 v103, v0
	v_mov_b32_e32 v104, v0
	v_mov_b32_e32 v105, v0
	v_mov_b32_e32 v106, v0
	v_mov_b32_e32 v107, v0
	v_mov_b32_e32 v108, v0
	v_mov_b32_e32 v109, v0
	v_mov_b32_e32 v110, v0
	v_mov_b32_e32 v111, v0
	v_mov_b32_e32 v120, v0
	v_mov_b32_e32 v121, v0
	v_mov_b32_e32 v122, v0
	v_mov_b32_e32 v123, v0
	v_mov_b32_e32 v124, v0
	v_mov_b32_e32 v125, v0
	v_mov_b32_e32 v126, v0
	v_mov_b32_e32 v127, v0
	s_barrier
.LBB0_569:
	s_add_u32 s46, s42, 0xfd300100
	s_addc_u32 s47, s43, -1
	s_andn2_b32 s48, 0x80, s42
	s_cmp_lg_u32 s78, 12
	s_cselect_b32 s46, s46, s48
	s_cselect_b32 s47, s47, 0
	s_add_u32 s68, s34, s46
	s_addc_u32 s69, s35, s47
	s_add_i32 s48, 0, 0x10000
	s_add_u32 s46, s40, s46
	v_add_u32_e32 v143, s48, v141
	s_addc_u32 s47, s41, s47
	s_add_i32 s49, 0, 0x14000
	ds_read_b128 v[144:147], v143
	ds_read_b128 v[148:151], v143 offset:1024
	ds_read_b128 v[152:155], v143 offset:2048
	ds_read_b128 v[156:159], v143 offset:3072
	v_add_u32_e32 v143, s49, v141
	ds_read_b128 v[160:163], v143
	ds_read_b128 v[164:167], v143 offset:1024
	ds_read_b128 v[168:171], v143 offset:2048
	ds_read_b128 v[172:175], v143 offset:3072
	v_lshl_add_u64 v[186:187], v[138:139], 0, s[42:43]
	s_add_i32 m0, s61, 0xc000
	ds_read_b128 v[190:193], v142
	ds_read_b128 v[194:197], v142 offset:1024
	ds_read_b128 v[198:201], v142 offset:2048
	ds_read_b128 v[202:205], v142 offset:3072
	ds_read_b128 v[206:209], v142 offset:4096
	ds_read_b128 v[210:213], v142 offset:5120
	ds_read_b128 v[214:217], v142 offset:6144
	ds_read_b128 v[218:221], v142 offset:7168
	global_load_lds_dwordx4 v[186:187], off
	v_lshl_add_u64 v[186:187], v[136:137], 0, s[42:43]
	s_add_i32 m0, s61, 0xe000
	s_nop 0
	global_load_lds_dwordx4 v[186:187], off
	s_waitcnt vmcnt(8)
	s_waitcnt lgkmcnt(0)
	s_barrier
	s_setprio 1
	s_waitcnt lgkmcnt(0)
	v_mfma_f32_16x16x32_bf16 v[124:127], v[144:147], v[190:193], v[124:127]
	v_mfma_f32_16x16x32_bf16 v[120:123], v[152:155], v[190:193], v[120:123]
	v_mfma_f32_16x16x32_bf16 v[108:111], v[144:147], v[198:201], v[108:111]
	v_mfma_f32_16x16x32_bf16 v[104:107], v[152:155], v[198:201], v[104:107]
	v_mfma_f32_16x16x32_bf16 v[100:103], v[144:147], v[206:209], v[100:103]
	v_mfma_f32_16x16x32_bf16 v[92:95], v[152:155], v[206:209], v[92:95]
	v_mfma_f32_16x16x32_bf16 v[84:87], v[144:147], v[214:217], v[84:87]
	v_mfma_f32_16x16x32_bf16 v[76:79], v[152:155], v[214:217], v[76:79]
	v_mfma_f32_16x16x32_bf16 v[124:127], v[148:151], v[194:197], v[124:127]
	v_mfma_f32_16x16x32_bf16 v[120:123], v[156:159], v[194:197], v[120:123]
	v_mfma_f32_16x16x32_bf16 v[108:111], v[148:151], v[202:205], v[108:111]
	v_mfma_f32_16x16x32_bf16 v[104:107], v[156:159], v[202:205], v[104:107]
	v_mfma_f32_16x16x32_bf16 v[100:103], v[148:151], v[210:213], v[100:103]
	v_mfma_f32_16x16x32_bf16 v[92:95], v[156:159], v[210:213], v[92:95]
	v_mfma_f32_16x16x32_bf16 v[84:87], v[148:151], v[218:221], v[84:87]
	v_mfma_f32_16x16x32_bf16 v[76:79], v[156:159], v[218:221], v[76:79]
	s_setprio 0
	s_setprio 1
	v_mfma_f32_16x16x32_bf16 v[116:119], v[160:163], v[190:193], v[116:119]
	v_mfma_f32_16x16x32_bf16 v[112:115], v[168:171], v[190:193], v[112:115]
	v_mfma_f32_16x16x32_bf16 v[96:99], v[160:163], v[198:201], v[96:99]
	v_mfma_f32_16x16x32_bf16 v[88:91], v[168:171], v[198:201], v[88:91]
	v_mfma_f32_16x16x32_bf16 v[80:83], v[160:163], v[206:209], v[80:83]
	v_mfma_f32_16x16x32_bf16 v[72:75], v[168:171], v[206:209], v[72:75]
	v_mfma_f32_16x16x32_bf16 v[68:71], v[160:163], v[214:217], v[68:71]
	v_mfma_f32_16x16x32_bf16 v[64:67], v[168:171], v[214:217], v[64:67]
	v_mfma_f32_16x16x32_bf16 v[116:119], v[164:167], v[194:197], v[116:119]
	v_mfma_f32_16x16x32_bf16 v[112:115], v[172:175], v[194:197], v[112:115]
	v_mfma_f32_16x16x32_bf16 v[96:99], v[164:167], v[202:205], v[96:99]
	v_mfma_f32_16x16x32_bf16 v[88:91], v[172:175], v[202:205], v[88:91]
	v_mfma_f32_16x16x32_bf16 v[80:83], v[164:167], v[210:213], v[80:83]
	v_mfma_f32_16x16x32_bf16 v[72:75], v[172:175], v[210:213], v[72:75]
	v_mfma_f32_16x16x32_bf16 v[68:71], v[164:167], v[218:221], v[68:71]
	v_mfma_f32_16x16x32_bf16 v[64:67], v[172:175], v[218:221], v[64:67]
	s_setprio 0
	s_barrier
	s_add_i32 s48, s48, s60
	v_lshl_add_u64 v[186:187], s[46:47], 0, v[176:177]
	s_mov_b32 m0, s48
	ds_read_b128 v[190:193], v142 offset:16384
	ds_read_b128 v[194:197], v142 offset:17408
	ds_read_b128 v[198:201], v142 offset:18432
	ds_read_b128 v[202:205], v142 offset:19456
	ds_read_b128 v[206:209], v142 offset:20480
	ds_read_b128 v[210:213], v142 offset:21504
	ds_read_b128 v[214:217], v142 offset:22528
	ds_read_b128 v[218:221], v142 offset:23552
	global_load_lds_dwordx4 v[186:187], off
	s_add_i32 m0, s48, 0x2000
	s_add_u32 s80, s46, 0x80000
	v_lshl_add_u64 v[222:223], s[46:47], 0, v[134:135]
	s_addc_u32 s81, s47, 0
	s_add_i32 s48, s49, s60
	global_load_lds_dwordx4 v[222:223], off
	v_lshl_add_u64 v[224:225], s[80:81], 0, v[176:177]
	s_mov_b32 m0, s48
	v_lshl_add_u64 v[234:235], s[68:69], 0, v[132:133]
	global_load_lds_dwordx4 v[224:225], off
	v_lshl_add_u64 v[224:225], s[80:81], 0, v[134:135]
	s_add_i32 m0, s48, 0x2000
	s_nop 0
	global_load_lds_dwordx4 v[224:225], off
	v_lshl_add_u64 v[224:225], s[68:69], 0, v[130:131]
	s_mov_b32 m0, s61
	s_nop 0
	global_load_lds_dwordx4 v[224:225], off
	s_mov_b32 m0, s62
	s_nop 0
	global_load_lds_dwordx4 v[234:235], off
	s_waitcnt vmcnt(8)
	s_waitcnt lgkmcnt(0)
	s_barrier
	s_setprio 1
	s_waitcnt lgkmcnt(0)
	v_mfma_f32_16x16x32_bf16 v[60:63], v[144:147], v[190:193], v[60:63]
	v_mfma_f32_16x16x32_bf16 v[56:59], v[152:155], v[190:193], v[56:59]
	v_mfma_f32_16x16x32_bf16 v[52:55], v[144:147], v[198:201], v[52:55]
	v_mfma_f32_16x16x32_bf16 v[44:47], v[152:155], v[198:201], v[44:47]
	v_mfma_f32_16x16x32_bf16 v[36:39], v[144:147], v[206:209], v[36:39]
	v_mfma_f32_16x16x32_bf16 v[28:31], v[152:155], v[206:209], v[28:31]
	v_mfma_f32_16x16x32_bf16 v[20:23], v[144:147], v[214:217], v[20:23]
	v_mfma_f32_16x16x32_bf16 v[12:15], v[152:155], v[214:217], v[12:15]
	v_mfma_f32_16x16x32_bf16 v[60:63], v[148:151], v[194:197], v[60:63]
	v_mfma_f32_16x16x32_bf16 v[56:59], v[156:159], v[194:197], v[56:59]
	v_mfma_f32_16x16x32_bf16 v[52:55], v[148:151], v[202:205], v[52:55]
	v_mfma_f32_16x16x32_bf16 v[44:47], v[156:159], v[202:205], v[44:47]
	v_mfma_f32_16x16x32_bf16 v[36:39], v[148:151], v[210:213], v[36:39]
	v_mfma_f32_16x16x32_bf16 v[28:31], v[156:159], v[210:213], v[28:31]
	v_mfma_f32_16x16x32_bf16 v[20:23], v[148:151], v[218:221], v[20:23]
	v_mfma_f32_16x16x32_bf16 v[12:15], v[156:159], v[218:221], v[12:15]
	s_setprio 0
	s_setprio 1
	v_mfma_f32_16x16x32_bf16 v[48:51], v[160:163], v[190:193], v[48:51]
	v_mfma_f32_16x16x32_bf16 v[40:43], v[168:171], v[190:193], v[40:43]
	v_mfma_f32_16x16x32_bf16 v[32:35], v[160:163], v[198:201], v[32:35]
	v_mfma_f32_16x16x32_bf16 v[24:27], v[168:171], v[198:201], v[24:27]
	v_mfma_f32_16x16x32_bf16 v[16:19], v[160:163], v[206:209], v[16:19]
	v_mfma_f32_16x16x32_bf16 v[8:11], v[168:171], v[206:209], v[8:11]
	v_mfma_f32_16x16x32_bf16 v[4:7], v[160:163], v[214:217], v[4:7]
	v_mfma_f32_16x16x32_bf16 v[0:3], v[168:171], v[214:217], v[0:3]
	v_mfma_f32_16x16x32_bf16 v[48:51], v[164:167], v[194:197], v[48:51]
	v_mfma_f32_16x16x32_bf16 v[40:43], v[172:175], v[194:197], v[40:43]
	v_mfma_f32_16x16x32_bf16 v[32:35], v[164:167], v[202:205], v[32:35]
	v_mfma_f32_16x16x32_bf16 v[24:27], v[172:175], v[202:205], v[24:27]
	v_mfma_f32_16x16x32_bf16 v[16:19], v[164:167], v[210:213], v[16:19]
	v_mfma_f32_16x16x32_bf16 v[8:11], v[172:175], v[210:213], v[8:11]
	v_mfma_f32_16x16x32_bf16 v[4:7], v[164:167], v[218:221], v[4:7]
	v_mfma_f32_16x16x32_bf16 v[0:3], v[172:175], v[218:221], v[0:3]
	s_setprio 0
	s_barrier
	s_add_i32 s48, 0, 0x18000
	v_add_u32_e32 v143, s48, v141
	s_add_i32 s49, 0, 0x1c000
	ds_read_b128 v[144:147], v143
	ds_read_b128 v[148:151], v143 offset:1024
	ds_read_b128 v[152:155], v143 offset:2048
	ds_read_b128 v[156:159], v143 offset:3072
	v_add_u32_e32 v143, s49, v141
	ds_read_b128 v[160:163], v143
	ds_read_b128 v[164:167], v143 offset:1024
	ds_read_b128 v[168:171], v143 offset:2048
	ds_read_b128 v[172:175], v143 offset:3072
	s_add_u32 s68, s68, 0x200000
	s_addc_u32 s69, s69, 0
	s_mov_b32 m0, s63
	v_lshl_add_u64 v[236:237], s[68:69], 0, v[130:131]
	ds_read_b128 v[190:193], v142 offset:32768
	ds_read_b128 v[194:197], v142 offset:33792
	ds_read_b128 v[198:201], v142 offset:34816
	ds_read_b128 v[202:205], v142 offset:35840
	ds_read_b128 v[206:209], v142 offset:36864
	ds_read_b128 v[210:213], v142 offset:37888
	ds_read_b128 v[214:217], v142 offset:38912
	ds_read_b128 v[218:221], v142 offset:39936
	global_load_lds_dwordx4 v[236:237], off
	v_lshl_add_u64 v[236:237], s[68:69], 0, v[132:133]
	s_mov_b32 m0, s70
	s_nop 0
	global_load_lds_dwordx4 v[236:237], off
	s_waitcnt vmcnt(8)
	s_waitcnt lgkmcnt(0)
	s_barrier
	s_setprio 1
	s_waitcnt lgkmcnt(0)
	v_mfma_f32_16x16x32_bf16 v[124:127], v[144:147], v[190:193], v[124:127]
	v_mfma_f32_16x16x32_bf16 v[120:123], v[152:155], v[190:193], v[120:123]
	v_mfma_f32_16x16x32_bf16 v[108:111], v[144:147], v[198:201], v[108:111]
	v_mfma_f32_16x16x32_bf16 v[104:107], v[152:155], v[198:201], v[104:107]
	v_mfma_f32_16x16x32_bf16 v[100:103], v[144:147], v[206:209], v[100:103]
	v_mfma_f32_16x16x32_bf16 v[92:95], v[152:155], v[206:209], v[92:95]
	v_mfma_f32_16x16x32_bf16 v[84:87], v[144:147], v[214:217], v[84:87]
	v_mfma_f32_16x16x32_bf16 v[76:79], v[152:155], v[214:217], v[76:79]
	v_mfma_f32_16x16x32_bf16 v[124:127], v[148:151], v[194:197], v[124:127]
	v_mfma_f32_16x16x32_bf16 v[120:123], v[156:159], v[194:197], v[120:123]
	v_mfma_f32_16x16x32_bf16 v[108:111], v[148:151], v[202:205], v[108:111]
	v_mfma_f32_16x16x32_bf16 v[104:107], v[156:159], v[202:205], v[104:107]
	v_mfma_f32_16x16x32_bf16 v[100:103], v[148:151], v[210:213], v[100:103]
	v_mfma_f32_16x16x32_bf16 v[92:95], v[156:159], v[210:213], v[92:95]
	v_mfma_f32_16x16x32_bf16 v[84:87], v[148:151], v[218:221], v[84:87]
	v_mfma_f32_16x16x32_bf16 v[76:79], v[156:159], v[218:221], v[76:79]
	s_setprio 0
	s_setprio 1
	v_mfma_f32_16x16x32_bf16 v[116:119], v[160:163], v[190:193], v[116:119]
	v_mfma_f32_16x16x32_bf16 v[112:115], v[168:171], v[190:193], v[112:115]
	v_mfma_f32_16x16x32_bf16 v[96:99], v[160:163], v[198:201], v[96:99]
	v_mfma_f32_16x16x32_bf16 v[88:91], v[168:171], v[198:201], v[88:91]
	v_mfma_f32_16x16x32_bf16 v[80:83], v[160:163], v[206:209], v[80:83]
	v_mfma_f32_16x16x32_bf16 v[72:75], v[168:171], v[206:209], v[72:75]
	v_mfma_f32_16x16x32_bf16 v[68:71], v[160:163], v[214:217], v[68:71]
	v_mfma_f32_16x16x32_bf16 v[64:67], v[168:171], v[214:217], v[64:67]
	v_mfma_f32_16x16x32_bf16 v[116:119], v[164:167], v[194:197], v[116:119]
	v_mfma_f32_16x16x32_bf16 v[112:115], v[172:175], v[194:197], v[112:115]
	v_mfma_f32_16x16x32_bf16 v[96:99], v[164:167], v[202:205], v[96:99]
	v_mfma_f32_16x16x32_bf16 v[88:91], v[172:175], v[202:205], v[88:91]
	v_mfma_f32_16x16x32_bf16 v[80:83], v[164:167], v[210:213], v[80:83]
	v_mfma_f32_16x16x32_bf16 v[72:75], v[172:175], v[210:213], v[72:75]
	v_mfma_f32_16x16x32_bf16 v[68:71], v[164:167], v[218:221], v[68:71]
	v_mfma_f32_16x16x32_bf16 v[64:67], v[172:175], v[218:221], v[64:67]
	s_setprio 0
	s_barrier
	s_add_i32 s48, s48, s60
	v_lshl_add_u64 v[186:187], v[186:187], 0, s[100:101]
	s_mov_b32 m0, s48
	ds_read_b128 v[190:193], v142 offset:49152
	ds_read_b128 v[194:197], v142 offset:50176
	ds_read_b128 v[198:201], v142 offset:51200
	ds_read_b128 v[202:205], v142 offset:52224
	ds_read_b128 v[206:209], v142 offset:53248
	ds_read_b128 v[210:213], v142 offset:54272
	ds_read_b128 v[214:217], v142 offset:55296
	ds_read_b128 v[218:221], v142 offset:56320
	global_load_lds_dwordx4 v[186:187], off
	s_add_i32 m0, s48, 0x2000
	s_add_u32 s46, s46, 0x80100
	v_lshl_add_u64 v[186:187], v[222:223], 0, s[100:101]
	s_addc_u32 s47, s47, 0
	s_add_i32 s48, s49, s60
	global_load_lds_dwordx4 v[186:187], off
	v_lshl_add_u64 v[186:187], s[46:47], 0, v[176:177]
	s_mov_b32 m0, s48
	s_nop 0
	global_load_lds_dwordx4 v[186:187], off
	v_lshl_add_u64 v[186:187], s[46:47], 0, v[134:135]
	s_add_i32 m0, s48, 0x2000
	s_nop 0
	global_load_lds_dwordx4 v[186:187], off
	v_lshl_add_u64 v[186:187], v[224:225], 0, s[100:101]
	s_mov_b32 m0, s72
	s_nop 0
	global_load_lds_dwordx4 v[186:187], off
	v_lshl_add_u64 v[186:187], v[234:235], 0, s[100:101]
	s_mov_b32 m0, s73
	s_nop 0
	global_load_lds_dwordx4 v[186:187], off
	s_waitcnt vmcnt(8)
	s_waitcnt lgkmcnt(0)
	s_barrier
	s_setprio 1
	s_waitcnt lgkmcnt(0)
	v_mfma_f32_16x16x32_bf16 v[60:63], v[144:147], v[190:193], v[60:63]
	v_mfma_f32_16x16x32_bf16 v[56:59], v[152:155], v[190:193], v[56:59]
	v_mfma_f32_16x16x32_bf16 v[52:55], v[144:147], v[198:201], v[52:55]
	v_mfma_f32_16x16x32_bf16 v[44:47], v[152:155], v[198:201], v[44:47]
	v_mfma_f32_16x16x32_bf16 v[36:39], v[144:147], v[206:209], v[36:39]
	v_mfma_f32_16x16x32_bf16 v[28:31], v[152:155], v[206:209], v[28:31]
	v_mfma_f32_16x16x32_bf16 v[20:23], v[144:147], v[214:217], v[20:23]
	v_mfma_f32_16x16x32_bf16 v[12:15], v[152:155], v[214:217], v[12:15]
	v_mfma_f32_16x16x32_bf16 v[60:63], v[148:151], v[194:197], v[60:63]
	v_mfma_f32_16x16x32_bf16 v[56:59], v[156:159], v[194:197], v[56:59]
	v_mfma_f32_16x16x32_bf16 v[52:55], v[148:151], v[202:205], v[52:55]
	v_mfma_f32_16x16x32_bf16 v[44:47], v[156:159], v[202:205], v[44:47]
	v_mfma_f32_16x16x32_bf16 v[36:39], v[148:151], v[210:213], v[36:39]
	v_mfma_f32_16x16x32_bf16 v[28:31], v[156:159], v[210:213], v[28:31]
	v_mfma_f32_16x16x32_bf16 v[20:23], v[148:151], v[218:221], v[20:23]
	v_mfma_f32_16x16x32_bf16 v[12:15], v[156:159], v[218:221], v[12:15]
	s_setprio 0
	s_setprio 1
	v_mfma_f32_16x16x32_bf16 v[48:51], v[160:163], v[190:193], v[48:51]
	v_mfma_f32_16x16x32_bf16 v[40:43], v[168:171], v[190:193], v[40:43]
	v_mfma_f32_16x16x32_bf16 v[32:35], v[160:163], v[198:201], v[32:35]
	v_mfma_f32_16x16x32_bf16 v[24:27], v[168:171], v[198:201], v[24:27]
	v_mfma_f32_16x16x32_bf16 v[16:19], v[160:163], v[206:209], v[16:19]
	v_mfma_f32_16x16x32_bf16 v[8:11], v[168:171], v[206:209], v[8:11]
	v_mfma_f32_16x16x32_bf16 v[4:7], v[160:163], v[214:217], v[4:7]
	v_mfma_f32_16x16x32_bf16 v[0:3], v[168:171], v[214:217], v[0:3]
	v_mfma_f32_16x16x32_bf16 v[48:51], v[164:167], v[194:197], v[48:51]
	v_mfma_f32_16x16x32_bf16 v[40:43], v[172:175], v[194:197], v[40:43]
	v_mfma_f32_16x16x32_bf16 v[32:35], v[164:167], v[202:205], v[32:35]
	v_mfma_f32_16x16x32_bf16 v[24:27], v[172:175], v[202:205], v[24:27]
	v_mfma_f32_16x16x32_bf16 v[16:19], v[164:167], v[210:213], v[16:19]
	v_mfma_f32_16x16x32_bf16 v[8:11], v[172:175], v[210:213], v[8:11]
	v_mfma_f32_16x16x32_bf16 v[4:7], v[164:167], v[218:221], v[4:7]
	v_mfma_f32_16x16x32_bf16 v[0:3], v[172:175], v[218:221], v[0:3]
	s_setprio 0
	s_barrier
	s_add_i32 s78, s78, 2
	s_add_u32 s42, s42, 0x200
	s_addc_u32 s43, s43, 0
	s_cmp_gt_u32 s78, 13
	s_cbranch_scc0 .LBB0_569
	s_cmpk_lt_u32 s59, 0x100
	s_cbranch_scc0 .Ldfs_a
	s_barrier
.Ldfs_a:
	s_bitcmp1_b32 s42, 7
	s_cbranch_scc1 .Ldfs_epi
	s_cmpk_eq_u32 s58, 0x400
	s_cbranch_scc1 .Ldfs_xepi
	s_add_i32 s46, s77, 0xfffffb80
	s_lshl_b32 s46, s46, 18
	s_add_u32 s48, s94, s46
	s_addc_u32 s49, s95, 0
	s_add_u32 s48, s48, 0x11b00000
	s_addc_u32 s49, s49, 0
	v_lshrrev_b32_e32 v144, 6, v140
	v_and_b32_e32 v145, 63, v140
	v_lshlrev_b32_e32 v145, 4, v145
	v_lshl_add_u32 v144, v144, 15, v145
	global_store_dwordx4 v144, v[0:3], s[48:49] offset:0
	global_store_dwordx4 v144, v[4:7], s[48:49] offset:1024
	global_store_dwordx4 v144, v[8:11], s[48:49] offset:2048
	global_store_dwordx4 v144, v[12:15], s[48:49] offset:3072
	s_add_u32 s48, s48, 0x1000
	s_addc_u32 s49, s49, 0
	global_store_dwordx4 v144, v[16:19], s[48:49] offset:0
	global_store_dwordx4 v144, v[20:23], s[48:49] offset:1024
	global_store_dwordx4 v144, v[24:27], s[48:49] offset:2048
	global_store_dwordx4 v144, v[28:31], s[48:49] offset:3072
	s_add_u32 s48, s48, 0x1000
	s_addc_u32 s49, s49, 0
	global_store_dwordx4 v144, v[32:35], s[48:49] offset:0
	global_store_dwordx4 v144, v[36:39], s[48:49] offset:1024
	global_store_dwordx4 v144, v[40:43], s[48:49] offset:2048
	global_store_dwordx4 v144, v[44:47], s[48:49] offset:3072
	s_add_u32 s48, s48, 0x1000
	s_addc_u32 s49, s49, 0
	global_store_dwordx4 v144, v[48:51], s[48:49] offset:0
	global_store_dwordx4 v144, v[52:55], s[48:49] offset:1024
	global_store_dwordx4 v144, v[56:59], s[48:49] offset:2048
	global_store_dwordx4 v144, v[60:63], s[48:49] offset:3072
	s_add_u32 s48, s48, 0x1000
	s_addc_u32 s49, s49, 0
	global_store_dwordx4 v144, v[64:67], s[48:49] offset:0
	global_store_dwordx4 v144, v[68:71], s[48:49] offset:1024
	global_store_dwordx4 v144, v[72:75], s[48:49] offset:2048
	global_store_dwordx4 v144, v[76:79], s[48:49] offset:3072
	s_add_u32 s48, s48, 0x1000
	s_addc_u32 s49, s49, 0
	global_store_dwordx4 v144, v[80:83], s[48:49] offset:0
	global_store_dwordx4 v144, v[84:87], s[48:49] offset:1024
	global_store_dwordx4 v144, v[88:91], s[48:49] offset:2048
	global_store_dwordx4 v144, v[92:95], s[48:49] offset:3072
	s_add_u32 s48, s48, 0x1000
	s_addc_u32 s49, s49, 0
	global_store_dwordx4 v144, v[96:99], s[48:49] offset:0
	global_store_dwordx4 v144, v[100:103], s[48:49] offset:1024
	global_store_dwordx4 v144, v[104:107], s[48:49] offset:2048
	global_store_dwordx4 v144, v[108:111], s[48:49] offset:3072
	s_add_u32 s48, s48, 0x1000
	s_addc_u32 s49, s49, 0
	global_store_dwordx4 v144, v[112:115], s[48:49] offset:0
	global_store_dwordx4 v144, v[116:119], s[48:49] offset:1024
	global_store_dwordx4 v144, v[120:123], s[48:49] offset:2048
	global_store_dwordx4 v144, v[124:127], s[48:49] offset:3072
	s_cmpk_lt_u32 s59, 0x100
	s_cbranch_scc1 .Ldfs_b
	s_barrier
.Ldfs_b:
	s_mov_b32 s78, -2
	s_mov_b64 s[42:43], 0x2d00180
	s_branch .LBB0_569
.Ldfs_epi:
	s_add_i32 s46, s77, 0xfffffb80
	s_lshl_b32 s46, s46, 18
	s_add_u32 s48, s94, s46
	s_addc_u32 s49, s95, 0
	s_add_u32 s48, s48, 0x11b00000
	s_addc_u32 s49, s49, 0
	v_lshrrev_b32_e32 v144, 6, v140
	v_and_b32_e32 v145, 63, v140
	v_lshlrev_b32_e32 v145, 4, v145
	v_lshl_add_u32 v144, v144, 15, v145
	s_lshl_b32 s46, s52, 11
	s_lshl_b32 s47, s3, 2
	s_add_i32 s46, s46, s47
	s_add_i32 s46, s46, 0x30000
	s_add_u32 s46, s94, s46
	s_addc_u32 s47, s95, 0
	v_or_b32_e32 v145, s71, v129
	v_lshlrev_b32_e32 v146, 2, v145
	global_load_dwordx4 v[152:155], v146, s[46:47] offset:0
	global_load_dwordx4 v[156:159], v146, s[46:47] offset:16
	global_load_dwordx4 v[160:163], v146, s[46:47] offset:512
	global_load_dwordx4 v[164:167], v146, s[46:47] offset:528
	v_and_b32_e32 v147, 1, v140
	v_lshlrev_b32_e32 v147, 31, v147
	v_lshlrev_b32_e32 v148, 11, v128
	v_lshl_add_u32 v148, v145, 1, v148
	s_lshl_b32 s34, s52, 11
	s_add_i32 s36, s34, 0x781
	s_sub_i32 s36, s36, s58
	s_or_b32 s34, s34, s58
	s_lshl_b32 s34, s34, 11
	s_lshl_b32 s36, s36, 11
	s_lshl_b32 s0, s3, 1
	s_add_i32 s0, s0, 0x4b00400
	s_add_i32 s34, s34, s0
	s_add_i32 s36, s36, s0
	s_add_u32 s34, s94, s34
	s_addc_u32 s35, s95, 0
	s_add_u32 s36, s94, s36
	s_addc_u32 s37, s95, 0
	v_sub_u32_e32 v149, 127, v128
	v_lshlrev_b32_e32 v149, 11, v149
	v_lshl_add_u32 v149, v145, 1, v149
	v_or_b32_e32 v150, s58, v128
	v_cmp_ne_u32_e32 vcc, 0, v150
	s_mov_b64 s[68:69], vcc
	s_add_u32 s46, s48, 0x7000
	s_addc_u32 s47, s49, 0
	global_load_dwordx4 v[190:193], v144, s[46:47] offset:3072 sc1
	global_load_dwordx4 v[194:197], v144, s[46:47] offset:2048 sc1
	global_load_dwordx4 v[198:201], v144, s[46:47] offset:1024 sc1
	global_load_dwordx4 v[202:205], v144, s[46:47] offset:0 sc1
	s_add_u32 s46, s48, 0x6000
	s_addc_u32 s47, s49, 0
	global_load_dwordx4 v[206:209], v144, s[46:47] offset:3072 sc1
	global_load_dwordx4 v[210:213], v144, s[46:47] offset:2048 sc1
	global_load_dwordx4 v[214:217], v144, s[46:47] offset:0 sc1
	s_add_u32 s46, s48, 0x5000
	s_addc_u32 s47, s49, 0
	global_load_dwordx4 v[218:221], v144, s[46:47] offset:2048 sc1
	s_add_u32 s46, s48, 0x6000
	s_addc_u32 s47, s49, 0
	global_load_dwordx4 v[168:171], v144, s[46:47] offset:1024 sc1
	s_add_u32 s46, s48, 0x5000
	s_addc_u32 s47, s49, 0
	global_load_dwordx4 v[172:175], v144, s[46:47] offset:3072 sc1
	global_load_dwordx4 v[222:225], v144, s[46:47] offset:0 sc1
	s_add_u32 s46, s48, 0x4000
	s_addc_u32 s47, s49, 0
	global_load_dwordx4 v[234:237], v144, s[46:47] offset:2048 sc1
	s_waitcnt vmcnt(10)
	v_xor_b32_e32 v152, v147, v152
	v_xor_b32_e32 v153, v147, v153
	v_xor_b32_e32 v154, v147, v154
	v_xor_b32_e32 v155, v147, v155
	v_xor_b32_e32 v156, v147, v156
	v_xor_b32_e32 v157, v147, v157
	v_xor_b32_e32 v158, v147, v158
	v_xor_b32_e32 v159, v147, v159
	v_xor_b32_e32 v160, v147, v160
	v_xor_b32_e32 v161, v147, v161
	v_xor_b32_e32 v162, v147, v162
	v_xor_b32_e32 v163, v147, v163
	v_xor_b32_e32 v164, v147, v164
	v_xor_b32_e32 v165, v147, v165
	v_xor_b32_e32 v166, v147, v166
	v_xor_b32_e32 v167, v147, v167
	s_mov_b64 s[40:41], s[34:35]
	s_mov_b64 s[42:43], s[36:37]
	v_fma_f32 v190, v190, 2.0, -v124
	v_fma_f32 v191, v191, 2.0, -v125
	v_fma_f32 v192, v192, 2.0, -v126
	v_fma_f32 v193, v193, 2.0, -v127
	v_fma_f32 v194, v194, 2.0, -v120
	v_fma_f32 v195, v195, 2.0, -v121
	v_fma_f32 v196, v196, 2.0, -v122
	v_fma_f32 v197, v197, 2.0, -v123
	v_add_f32_e32 v190, v190, v152
	v_add_f32_e32 v191, v191, v153
	v_add_f32_e32 v192, v192, v154
	v_add_f32_e32 v193, v193, v155
	v_add_f32_e32 v194, v194, v156
	v_add_f32_e32 v195, v195, v157
	v_add_f32_e32 v196, v196, v158
	v_add_f32_e32 v197, v197, v159
	v_mul_f32_e32 v190, s88, v190
	v_mul_f32_e32 v191, s88, v191
	v_mul_f32_e32 v192, s88, v192
	v_mul_f32_e32 v193, s88, v193
	v_mul_f32_e32 v194, s88, v194
	v_mul_f32_e32 v195, s88, v195
	v_mul_f32_e32 v196, s88, v196
	v_mul_f32_e32 v197, s88, v197
	v_cvt_pk_bf16_f32 v190, v190, v191
	v_cvt_pk_bf16_f32 v191, v192, v193
	v_cvt_pk_bf16_f32 v192, v194, v195
	v_cvt_pk_bf16_f32 v193, v196, v197
	s_and_saveexec_b64 s[80:81], s[68:69]
	global_store_dwordx4 v149, v[190:193], s[42:43] offset:0
	s_mov_b64 exec, s[80:81]
	v_add_f32_e32 v124, v124, v152
	v_add_f32_e32 v125, v125, v153
	v_add_f32_e32 v126, v126, v154
	v_add_f32_e32 v127, v127, v155
	v_add_f32_e32 v120, v120, v156
	v_add_f32_e32 v121, v121, v157
	v_add_f32_e32 v122, v122, v158
	v_add_f32_e32 v123, v123, v159
	v_mul_f32_e32 v124, s88, v124
	v_mul_f32_e32 v125, s88, v125
	v_mul_f32_e32 v126, s88, v126
	v_mul_f32_e32 v127, s88, v127
	v_mul_f32_e32 v120, s88, v120
	v_mul_f32_e32 v121, s88, v121
	v_mul_f32_e32 v122, s88, v122
	v_mul_f32_e32 v123, s88, v123
	v_cvt_pk_bf16_f32 v124, v124, v125
	v_cvt_pk_bf16_f32 v125, v126, v127
	v_cvt_pk_bf16_f32 v126, v120, v121
	v_cvt_pk_bf16_f32 v127, v122, v123
	global_store_dwordx4 v148, v[124:127], s[40:41] offset:0
	s_add_u32 s46, s48, 0x5000
	s_addc_u32 s47, s49, 0
	global_load_dwordx4 v[190:193], v144, s[46:47] offset:1024 sc1
	s_add_u32 s46, s48, 0x4000
	s_addc_u32 s47, s49, 0
	global_load_dwordx4 v[194:197], v144, s[46:47] offset:3072 sc1
	s_waitcnt vmcnt(12)
	v_fma_f32 v198, v198, 2.0, -v116
	v_fma_f32 v199, v199, 2.0, -v117
	v_fma_f32 v200, v200, 2.0, -v118
	v_fma_f32 v201, v201, 2.0, -v119
	v_fma_f32 v202, v202, 2.0, -v112
	v_fma_f32 v203, v203, 2.0, -v113
	v_fma_f32 v204, v204, 2.0, -v114
	v_fma_f32 v205, v205, 2.0, -v115
	v_add_f32_e32 v198, v198, v160
	v_add_f32_e32 v199, v199, v161
	v_add_f32_e32 v200, v200, v162
	v_add_f32_e32 v201, v201, v163
	v_add_f32_e32 v202, v202, v164
	v_add_f32_e32 v203, v203, v165
	v_add_f32_e32 v204, v204, v166
	v_add_f32_e32 v205, v205, v167
	v_mul_f32_e32 v198, s88, v198
	v_mul_f32_e32 v199, s88, v199
	v_mul_f32_e32 v200, s88, v200
	v_mul_f32_e32 v201, s88, v201
	v_mul_f32_e32 v202, s88, v202
	v_mul_f32_e32 v203, s88, v203
	v_mul_f32_e32 v204, s88, v204
	v_mul_f32_e32 v205, s88, v205
	v_cvt_pk_bf16_f32 v198, v198, v199
	v_cvt_pk_bf16_f32 v199, v200, v201
	v_cvt_pk_bf16_f32 v200, v202, v203
	v_cvt_pk_bf16_f32 v201, v204, v205
	s_and_saveexec_b64 s[80:81], s[68:69]
	global_store_dwordx4 v149, v[198:201], s[42:43] offset:256
	s_mov_b64 exec, s[80:81]
	v_add_f32_e32 v116, v116, v160
	v_add_f32_e32 v117, v117, v161
	v_add_f32_e32 v118, v118, v162
	v_add_f32_e32 v119, v119, v163
	v_add_f32_e32 v112, v112, v164
	v_add_f32_e32 v113, v113, v165
	v_add_f32_e32 v114, v114, v166
	v_add_f32_e32 v115, v115, v167
	v_mul_f32_e32 v116, s88, v116
	v_mul_f32_e32 v117, s88, v117
	v_mul_f32_e32 v118, s88, v118
	v_mul_f32_e32 v119, s88, v119
	v_mul_f32_e32 v112, s88, v112
	v_mul_f32_e32 v113, s88, v113
	v_mul_f32_e32 v114, s88, v114
	v_mul_f32_e32 v115, s88, v115
	v_cvt_pk_bf16_f32 v116, v116, v117
	v_cvt_pk_bf16_f32 v117, v118, v119
	v_cvt_pk_bf16_f32 v118, v112, v113
	v_cvt_pk_bf16_f32 v119, v114, v115
	global_store_dwordx4 v148, v[116:119], s[40:41] offset:256
	global_load_dwordx4 v[124:127], v144, s[46:47] offset:1024 sc1
	global_load_dwordx4 v[120:123], v144, s[46:47] offset:0 sc1
	s_waitcnt vmcnt(14)
	s_add_u32 s40, s34, 0x8000
	s_addc_u32 s41, s35, 0
	s_sub_u32 s42, s36, 0x8000
	s_subb_u32 s43, s37, 0
	v_fma_f32 v206, v206, 2.0, -v108
	v_fma_f32 v207, v207, 2.0, -v109
	v_fma_f32 v208, v208, 2.0, -v110
	v_fma_f32 v209, v209, 2.0, -v111
	v_fma_f32 v210, v210, 2.0, -v104
	v_fma_f32 v211, v211, 2.0, -v105
	v_fma_f32 v212, v212, 2.0, -v106
	v_fma_f32 v213, v213, 2.0, -v107
	v_add_f32_e32 v206, v206, v152
	v_add_f32_e32 v207, v207, v153
	v_add_f32_e32 v208, v208, v154
	v_add_f32_e32 v209, v209, v155
	v_add_f32_e32 v210, v210, v156
	v_add_f32_e32 v211, v211, v157
	v_add_f32_e32 v212, v212, v158
	v_add_f32_e32 v213, v213, v159
	v_mul_f32_e32 v206, s88, v206
	v_mul_f32_e32 v207, s88, v207
	v_mul_f32_e32 v208, s88, v208
	v_mul_f32_e32 v209, s88, v209
	v_mul_f32_e32 v210, s88, v210
	v_mul_f32_e32 v211, s88, v211
	v_mul_f32_e32 v212, s88, v212
	v_mul_f32_e32 v213, s88, v213
	v_cvt_pk_bf16_f32 v206, v206, v207
	v_cvt_pk_bf16_f32 v207, v208, v209
	v_cvt_pk_bf16_f32 v208, v210, v211
	v_cvt_pk_bf16_f32 v209, v212, v213
	global_store_dwordx4 v149, v[206:209], s[42:43] offset:0
	v_add_f32_e32 v108, v108, v152
	v_add_f32_e32 v109, v109, v153
	v_add_f32_e32 v110, v110, v154
	v_add_f32_e32 v111, v111, v155
	v_add_f32_e32 v104, v104, v156
	v_add_f32_e32 v105, v105, v157
	v_add_f32_e32 v106, v106, v158
	v_add_f32_e32 v107, v107, v159
	v_mul_f32_e32 v108, s88, v108
	v_mul_f32_e32 v109, s88, v109
	v_mul_f32_e32 v110, s88, v110
	v_mul_f32_e32 v111, s88, v111
	v_mul_f32_e32 v104, s88, v104
	v_mul_f32_e32 v105, s88, v105
	v_mul_f32_e32 v106, s88, v106
	v_mul_f32_e32 v107, s88, v107
	v_cvt_pk_bf16_f32 v108, v108, v109
	v_cvt_pk_bf16_f32 v109, v110, v111
	v_cvt_pk_bf16_f32 v110, v104, v105
	v_cvt_pk_bf16_f32 v111, v106, v107
	global_store_dwordx4 v148, v[108:111], s[40:41] offset:0
	s_add_u32 s46, s48, 0x3000
	s_addc_u32 s47, s49, 0
	global_load_dwordx4 v[198:201], v144, s[46:47] offset:3072 sc1
	global_load_dwordx4 v[202:205], v144, s[46:47] offset:2048 sc1
	s_waitcnt vmcnt(16)
	v_fma_f32 v214, v214, 2.0, -v96
	v_fma_f32 v215, v215, 2.0, -v97
	v_fma_f32 v216, v216, 2.0, -v98
	v_fma_f32 v217, v217, 2.0, -v99
	v_fma_f32 v218, v218, 2.0, -v88
	v_fma_f32 v219, v219, 2.0, -v89
	v_fma_f32 v220, v220, 2.0, -v90
	v_fma_f32 v221, v221, 2.0, -v91
	v_add_f32_e32 v214, v214, v160
	v_add_f32_e32 v215, v215, v161
	v_add_f32_e32 v216, v216, v162
	v_add_f32_e32 v217, v217, v163
	v_add_f32_e32 v218, v218, v164
	v_add_f32_e32 v219, v219, v165
	v_add_f32_e32 v220, v220, v166
	v_add_f32_e32 v221, v221, v167
	v_mul_f32_e32 v214, s88, v214
	v_mul_f32_e32 v215, s88, v215
	v_mul_f32_e32 v216, s88, v216
	v_mul_f32_e32 v217, s88, v217
	v_mul_f32_e32 v218, s88, v218
	v_mul_f32_e32 v219, s88, v219
	v_mul_f32_e32 v220, s88, v220
	v_mul_f32_e32 v221, s88, v221
	v_cvt_pk_bf16_f32 v214, v214, v215
	v_cvt_pk_bf16_f32 v215, v216, v217
	v_cvt_pk_bf16_f32 v216, v218, v219
	v_cvt_pk_bf16_f32 v217, v220, v221
	global_store_dwordx4 v149, v[214:217], s[42:43] offset:256
	v_add_f32_e32 v96, v96, v160
	v_add_f32_e32 v97, v97, v161
	v_add_f32_e32 v98, v98, v162
	v_add_f32_e32 v99, v99, v163
	v_add_f32_e32 v88, v88, v164
	v_add_f32_e32 v89, v89, v165
	v_add_f32_e32 v90, v90, v166
	v_add_f32_e32 v91, v91, v167
	v_mul_f32_e32 v96, s88, v96
	v_mul_f32_e32 v97, s88, v97
	v_mul_f32_e32 v98, s88, v98
	v_mul_f32_e32 v99, s88, v99
	v_mul_f32_e32 v88, s88, v88
	v_mul_f32_e32 v89, s88, v89
	v_mul_f32_e32 v90, s88, v90
	v_mul_f32_e32 v91, s88, v91
	v_cvt_pk_bf16_f32 v96, v96, v97
	v_cvt_pk_bf16_f32 v97, v98, v99
	v_cvt_pk_bf16_f32 v98, v88, v89
	v_cvt_pk_bf16_f32 v99, v90, v91
	global_store_dwordx4 v148, v[96:99], s[40:41] offset:256
	global_load_dwordx4 v[116:119], v144, s[46:47] offset:0 sc1
	s_add_u32 s46, s48, 0x2000
	s_addc_u32 s47, s49, 0
	global_load_dwordx4 v[112:115], v144, s[46:47] offset:2048 sc1
	s_waitcnt vmcnt(18)
	s_add_u32 s40, s34, 0x10000
	s_addc_u32 s41, s35, 0
	s_sub_u32 s42, s36, 0x10000
	s_subb_u32 s43, s37, 0
	v_fma_f32 v168, v168, 2.0, -v100
	v_fma_f32 v169, v169, 2.0, -v101
	v_fma_f32 v170, v170, 2.0, -v102
	v_fma_f32 v171, v171, 2.0, -v103
	v_fma_f32 v172, v172, 2.0, -v92
	v_fma_f32 v173, v173, 2.0, -v93
	v_fma_f32 v174, v174, 2.0, -v94
	v_fma_f32 v175, v175, 2.0, -v95
	v_add_f32_e32 v168, v168, v152
	v_add_f32_e32 v169, v169, v153
	v_add_f32_e32 v170, v170, v154
	v_add_f32_e32 v171, v171, v155
	v_add_f32_e32 v172, v172, v156
	v_add_f32_e32 v173, v173, v157
	v_add_f32_e32 v174, v174, v158
	v_add_f32_e32 v175, v175, v159
	v_mul_f32_e32 v168, s88, v168
	v_mul_f32_e32 v169, s88, v169
	v_mul_f32_e32 v170, s88, v170
	v_mul_f32_e32 v171, s88, v171
	v_mul_f32_e32 v172, s88, v172
	v_mul_f32_e32 v173, s88, v173
	v_mul_f32_e32 v174, s88, v174
	v_mul_f32_e32 v175, s88, v175
	v_cvt_pk_bf16_f32 v168, v168, v169
	v_cvt_pk_bf16_f32 v169, v170, v171
	v_cvt_pk_bf16_f32 v170, v172, v173
	v_cvt_pk_bf16_f32 v171, v174, v175
	global_store_dwordx4 v149, v[168:171], s[42:43] offset:0
	v_add_f32_e32 v100, v100, v152
	v_add_f32_e32 v101, v101, v153
	v_add_f32_e32 v102, v102, v154
	v_add_f32_e32 v103, v103, v155
	v_add_f32_e32 v92, v92, v156
	v_add_f32_e32 v93, v93, v157
	v_add_f32_e32 v94, v94, v158
	v_add_f32_e32 v95, v95, v159
	v_mul_f32_e32 v100, s88, v100
	v_mul_f32_e32 v101, s88, v101
	v_mul_f32_e32 v102, s88, v102
	v_mul_f32_e32 v103, s88, v103
	v_mul_f32_e32 v92, s88, v92
	v_mul_f32_e32 v93, s88, v93
	v_mul_f32_e32 v94, s88, v94
	v_mul_f32_e32 v95, s88, v95
	v_cvt_pk_bf16_f32 v100, v100, v101
	v_cvt_pk_bf16_f32 v101, v102, v103
	v_cvt_pk_bf16_f32 v102, v92, v93
	v_cvt_pk_bf16_f32 v103, v94, v95
	global_store_dwordx4 v148, v[100:103], s[40:41] offset:0
	s_add_u32 s46, s48, 0x3000
	s_addc_u32 s47, s49, 0
	global_load_dwordx4 v[206:209], v144, s[46:47] offset:1024 sc1
	s_add_u32 s46, s48, 0x2000
	s_addc_u32 s47, s49, 0
	global_load_dwordx4 v[210:213], v144, s[46:47] offset:3072 sc1
	s_waitcnt vmcnt(20)
	v_fma_f32 v222, v222, 2.0, -v80
	v_fma_f32 v223, v223, 2.0, -v81
	v_fma_f32 v224, v224, 2.0, -v82
	v_fma_f32 v225, v225, 2.0, -v83
	v_fma_f32 v234, v234, 2.0, -v72
	v_fma_f32 v235, v235, 2.0, -v73
	v_fma_f32 v236, v236, 2.0, -v74
	v_fma_f32 v237, v237, 2.0, -v75
	v_add_f32_e32 v222, v222, v160
	v_add_f32_e32 v223, v223, v161
	v_add_f32_e32 v224, v224, v162
	v_add_f32_e32 v225, v225, v163
	v_add_f32_e32 v234, v234, v164
	v_add_f32_e32 v235, v235, v165
	v_add_f32_e32 v236, v236, v166
	v_add_f32_e32 v237, v237, v167
	v_mul_f32_e32 v222, s88, v222
	v_mul_f32_e32 v223, s88, v223
	v_mul_f32_e32 v224, s88, v224
	v_mul_f32_e32 v225, s88, v225
	v_mul_f32_e32 v234, s88, v234
	v_mul_f32_e32 v235, s88, v235
	v_mul_f32_e32 v236, s88, v236
	v_mul_f32_e32 v237, s88, v237
	v_cvt_pk_bf16_f32 v222, v222, v223
	v_cvt_pk_bf16_f32 v223, v224, v225
	v_cvt_pk_bf16_f32 v224, v234, v235
	v_cvt_pk_bf16_f32 v225, v236, v237
	global_store_dwordx4 v149, v[222:225], s[42:43] offset:256
	v_add_f32_e32 v80, v80, v160
	v_add_f32_e32 v81, v81, v161
	v_add_f32_e32 v82, v82, v162
	v_add_f32_e32 v83, v83, v163
	v_add_f32_e32 v72, v72, v164
	v_add_f32_e32 v73, v73, v165
	v_add_f32_e32 v74, v74, v166
	v_add_f32_e32 v75, v75, v167
	v_mul_f32_e32 v80, s88, v80
	v_mul_f32_e32 v81, s88, v81
	v_mul_f32_e32 v82, s88, v82
	v_mul_f32_e32 v83, s88, v83
	v_mul_f32_e32 v72, s88, v72
	v_mul_f32_e32 v73, s88, v73
	v_mul_f32_e32 v74, s88, v74
	v_mul_f32_e32 v75, s88, v75
	v_cvt_pk_bf16_f32 v80, v80, v81
	v_cvt_pk_bf16_f32 v81, v82, v83
	v_cvt_pk_bf16_f32 v82, v72, v73
	v_cvt_pk_bf16_f32 v83, v74, v75
	global_store_dwordx4 v148, v[80:83], s[40:41] offset:256
	global_load_dwordx4 v[108:111], v144, s[46:47] offset:0 sc1
	s_add_u32 s46, s48, 0x1000
	s_addc_u32 s47, s49, 0
	global_load_dwordx4 v[104:107], v144, s[46:47] offset:2048 sc1
	s_waitcnt vmcnt(20)
	s_add_u32 s40, s34, 0x18000
	s_addc_u32 s41, s35, 0
	s_sub_u32 s42, s36, 0x18000
	s_subb_u32 s43, s37, 0
	v_fma_f32 v190, v190, 2.0, -v84
	v_fma_f32 v191, v191, 2.0, -v85
	v_fma_f32 v192, v192, 2.0, -v86
	v_fma_f32 v193, v193, 2.0, -v87
	v_fma_f32 v194, v194, 2.0, -v76
	v_fma_f32 v195, v195, 2.0, -v77
	v_fma_f32 v196, v196, 2.0, -v78
	v_fma_f32 v197, v197, 2.0, -v79
	v_add_f32_e32 v190, v190, v152
	v_add_f32_e32 v191, v191, v153
	v_add_f32_e32 v192, v192, v154
	v_add_f32_e32 v193, v193, v155
	v_add_f32_e32 v194, v194, v156
	v_add_f32_e32 v195, v195, v157
	v_add_f32_e32 v196, v196, v158
	v_add_f32_e32 v197, v197, v159
	v_mul_f32_e32 v190, s88, v190
	v_mul_f32_e32 v191, s88, v191
	v_mul_f32_e32 v192, s88, v192
	v_mul_f32_e32 v193, s88, v193
	v_mul_f32_e32 v194, s88, v194
	v_mul_f32_e32 v195, s88, v195
	v_mul_f32_e32 v196, s88, v196
	v_mul_f32_e32 v197, s88, v197
	v_cvt_pk_bf16_f32 v190, v190, v191
	v_cvt_pk_bf16_f32 v191, v192, v193
	v_cvt_pk_bf16_f32 v192, v194, v195
	v_cvt_pk_bf16_f32 v193, v196, v197
	global_store_dwordx4 v149, v[190:193], s[42:43] offset:0
	v_add_f32_e32 v84, v84, v152
	v_add_f32_e32 v85, v85, v153
	v_add_f32_e32 v86, v86, v154
	v_add_f32_e32 v87, v87, v155
	v_add_f32_e32 v76, v76, v156
	v_add_f32_e32 v77, v77, v157
	v_add_f32_e32 v78, v78, v158
	v_add_f32_e32 v79, v79, v159
	v_mul_f32_e32 v84, s88, v84
	v_mul_f32_e32 v85, s88, v85
	v_mul_f32_e32 v86, s88, v86
	v_mul_f32_e32 v87, s88, v87
	v_mul_f32_e32 v76, s88, v76
	v_mul_f32_e32 v77, s88, v77
	v_mul_f32_e32 v78, s88, v78
	v_mul_f32_e32 v79, s88, v79
	v_cvt_pk_bf16_f32 v84, v84, v85
	v_cvt_pk_bf16_f32 v85, v86, v87
	v_cvt_pk_bf16_f32 v86, v76, v77
	v_cvt_pk_bf16_f32 v87, v78, v79
	global_store_dwordx4 v148, v[84:87], s[40:41] offset:0
	s_add_u32 s46, s48, 0x2000
	s_addc_u32 s47, s49, 0
	global_load_dwordx4 v[214:217], v144, s[46:47] offset:1024 sc1
	s_add_u32 s46, s48, 0x1000
	s_addc_u32 s47, s49, 0
	global_load_dwordx4 v[218:221], v144, s[46:47] offset:3072 sc1
	s_waitcnt vmcnt(20)
	v_fma_f32 v124, v124, 2.0, -v68
	v_fma_f32 v125, v125, 2.0, -v69
	v_fma_f32 v126, v126, 2.0, -v70
	v_fma_f32 v127, v127, 2.0, -v71
	v_fma_f32 v120, v120, 2.0, -v64
	v_fma_f32 v121, v121, 2.0, -v65
	v_fma_f32 v122, v122, 2.0, -v66
	v_fma_f32 v123, v123, 2.0, -v67
	v_add_f32_e32 v124, v124, v160
	v_add_f32_e32 v125, v125, v161
	v_add_f32_e32 v126, v126, v162
	v_add_f32_e32 v127, v127, v163
	v_add_f32_e32 v120, v120, v164
	v_add_f32_e32 v121, v121, v165
	v_add_f32_e32 v122, v122, v166
	v_add_f32_e32 v123, v123, v167
	v_mul_f32_e32 v124, s88, v124
	v_mul_f32_e32 v125, s88, v125
	v_mul_f32_e32 v126, s88, v126
	v_mul_f32_e32 v127, s88, v127
	v_mul_f32_e32 v120, s88, v120
	v_mul_f32_e32 v121, s88, v121
	v_mul_f32_e32 v122, s88, v122
	v_mul_f32_e32 v123, s88, v123
	v_cvt_pk_bf16_f32 v124, v124, v125
	v_cvt_pk_bf16_f32 v125, v126, v127
	v_cvt_pk_bf16_f32 v126, v120, v121
	v_cvt_pk_bf16_f32 v127, v122, v123
	global_store_dwordx4 v149, v[124:127], s[42:43] offset:256
	v_add_f32_e32 v68, v68, v160
	v_add_f32_e32 v69, v69, v161
	v_add_f32_e32 v70, v70, v162
	v_add_f32_e32 v71, v71, v163
	v_add_f32_e32 v64, v64, v164
	v_add_f32_e32 v65, v65, v165
	v_add_f32_e32 v66, v66, v166
	v_add_f32_e32 v67, v67, v167
	v_mul_f32_e32 v68, s88, v68
	v_mul_f32_e32 v69, s88, v69
	v_mul_f32_e32 v70, s88, v70
	v_mul_f32_e32 v71, s88, v71
	v_mul_f32_e32 v64, s88, v64
	v_mul_f32_e32 v65, s88, v65
	v_mul_f32_e32 v66, s88, v66
	v_mul_f32_e32 v67, s88, v67
	v_cvt_pk_bf16_f32 v68, v68, v69
	v_cvt_pk_bf16_f32 v69, v70, v71
	v_cvt_pk_bf16_f32 v70, v64, v65
	v_cvt_pk_bf16_f32 v71, v66, v67
	global_store_dwordx4 v148, v[68:71], s[40:41] offset:256
	global_load_dwordx4 v[96:99], v144, s[46:47] offset:0 sc1
	s_add_u32 s46, s48, 0x0
	s_addc_u32 s47, s49, 0
	global_load_dwordx4 v[88:91], v144, s[46:47] offset:2048 sc1
	s_waitcnt vmcnt(20)
	s_add_u32 s40, s34, 0x40000
	s_addc_u32 s41, s35, 0
	s_sub_u32 s42, s36, 0x40000
	s_subb_u32 s43, s37, 0
	v_fma_f32 v198, v198, 2.0, -v60
	v_fma_f32 v199, v199, 2.0, -v61
	v_fma_f32 v200, v200, 2.0, -v62
	v_fma_f32 v201, v201, 2.0, -v63
	v_fma_f32 v202, v202, 2.0, -v56
	v_fma_f32 v203, v203, 2.0, -v57
	v_fma_f32 v204, v204, 2.0, -v58
	v_fma_f32 v205, v205, 2.0, -v59
	v_add_f32_e32 v198, v198, v152
	v_add_f32_e32 v199, v199, v153
	v_add_f32_e32 v200, v200, v154
	v_add_f32_e32 v201, v201, v155
	v_add_f32_e32 v202, v202, v156
	v_add_f32_e32 v203, v203, v157
	v_add_f32_e32 v204, v204, v158
	v_add_f32_e32 v205, v205, v159
	v_mul_f32_e32 v198, s88, v198
	v_mul_f32_e32 v199, s88, v199
	v_mul_f32_e32 v200, s88, v200
	v_mul_f32_e32 v201, s88, v201
	v_mul_f32_e32 v202, s88, v202
	v_mul_f32_e32 v203, s88, v203
	v_mul_f32_e32 v204, s88, v204
	v_mul_f32_e32 v205, s88, v205
	v_cvt_pk_bf16_f32 v198, v198, v199
	v_cvt_pk_bf16_f32 v199, v200, v201
	v_cvt_pk_bf16_f32 v200, v202, v203
	v_cvt_pk_bf16_f32 v201, v204, v205
	global_store_dwordx4 v149, v[198:201], s[42:43] offset:0
	v_add_f32_e32 v60, v60, v152
	v_add_f32_e32 v61, v61, v153
	v_add_f32_e32 v62, v62, v154
	v_add_f32_e32 v63, v63, v155
	v_add_f32_e32 v56, v56, v156
	v_add_f32_e32 v57, v57, v157
	v_add_f32_e32 v58, v58, v158
	v_add_f32_e32 v59, v59, v159
	v_mul_f32_e32 v60, s88, v60
	v_mul_f32_e32 v61, s88, v61
	v_mul_f32_e32 v62, s88, v62
	v_mul_f32_e32 v63, s88, v63
	v_mul_f32_e32 v56, s88, v56
	v_mul_f32_e32 v57, s88, v57
	v_mul_f32_e32 v58, s88, v58
	v_mul_f32_e32 v59, s88, v59
	v_cvt_pk_bf16_f32 v60, v60, v61
	v_cvt_pk_bf16_f32 v61, v62, v63
	v_cvt_pk_bf16_f32 v62, v56, v57
	v_cvt_pk_bf16_f32 v63, v58, v59
	global_store_dwordx4 v148, v[60:63], s[40:41] offset:0
	s_add_u32 s46, s48, 0x1000
	s_addc_u32 s47, s49, 0
	global_load_dwordx4 v[168:171], v144, s[46:47] offset:1024 sc1
	s_add_u32 s46, s48, 0x0
	s_addc_u32 s47, s49, 0
	global_load_dwordx4 v[172:175], v144, s[46:47] offset:3072 sc1
	s_waitcnt vmcnt(20)
	v_fma_f32 v116, v116, 2.0, -v48
	v_fma_f32 v117, v117, 2.0, -v49
	v_fma_f32 v118, v118, 2.0, -v50
	v_fma_f32 v119, v119, 2.0, -v51
	v_fma_f32 v112, v112, 2.0, -v40
	v_fma_f32 v113, v113, 2.0, -v41
	v_fma_f32 v114, v114, 2.0, -v42
	v_fma_f32 v115, v115, 2.0, -v43
	v_add_f32_e32 v116, v116, v160
	v_add_f32_e32 v117, v117, v161
	v_add_f32_e32 v118, v118, v162
	v_add_f32_e32 v119, v119, v163
	v_add_f32_e32 v112, v112, v164
	v_add_f32_e32 v113, v113, v165
	v_add_f32_e32 v114, v114, v166
	v_add_f32_e32 v115, v115, v167
	v_mul_f32_e32 v116, s88, v116
	v_mul_f32_e32 v117, s88, v117
	v_mul_f32_e32 v118, s88, v118
	v_mul_f32_e32 v119, s88, v119
	v_mul_f32_e32 v112, s88, v112
	v_mul_f32_e32 v113, s88, v113
	v_mul_f32_e32 v114, s88, v114
	v_mul_f32_e32 v115, s88, v115
	v_cvt_pk_bf16_f32 v116, v116, v117
	v_cvt_pk_bf16_f32 v117, v118, v119
	v_cvt_pk_bf16_f32 v118, v112, v113
	v_cvt_pk_bf16_f32 v119, v114, v115
	global_store_dwordx4 v149, v[116:119], s[42:43] offset:256
	v_add_f32_e32 v48, v48, v160
	v_add_f32_e32 v49, v49, v161
	v_add_f32_e32 v50, v50, v162
	v_add_f32_e32 v51, v51, v163
	v_add_f32_e32 v40, v40, v164
	v_add_f32_e32 v41, v41, v165
	v_add_f32_e32 v42, v42, v166
	v_add_f32_e32 v43, v43, v167
	v_mul_f32_e32 v48, s88, v48
	v_mul_f32_e32 v49, s88, v49
	v_mul_f32_e32 v50, s88, v50
	v_mul_f32_e32 v51, s88, v51
	v_mul_f32_e32 v40, s88, v40
	v_mul_f32_e32 v41, s88, v41
	v_mul_f32_e32 v42, s88, v42
	v_mul_f32_e32 v43, s88, v43
	v_cvt_pk_bf16_f32 v48, v48, v49
	v_cvt_pk_bf16_f32 v49, v50, v51
	v_cvt_pk_bf16_f32 v50, v40, v41
	v_cvt_pk_bf16_f32 v51, v42, v43
	global_store_dwordx4 v148, v[48:51], s[40:41] offset:256
	global_load_dwordx4 v[100:103], v144, s[46:47] offset:1024 sc1
	global_load_dwordx4 v[92:95], v144, s[46:47] offset:0 sc1
	s_waitcnt vmcnt(20)
	s_add_u32 s40, s34, 0x48000
	s_addc_u32 s41, s35, 0
	s_sub_u32 s42, s36, 0x48000
	s_subb_u32 s43, s37, 0
	v_fma_f32 v206, v206, 2.0, -v52
	v_fma_f32 v207, v207, 2.0, -v53
	v_fma_f32 v208, v208, 2.0, -v54
	v_fma_f32 v209, v209, 2.0, -v55
	v_fma_f32 v210, v210, 2.0, -v44
	v_fma_f32 v211, v211, 2.0, -v45
	v_fma_f32 v212, v212, 2.0, -v46
	v_fma_f32 v213, v213, 2.0, -v47
	v_add_f32_e32 v206, v206, v152
	v_add_f32_e32 v207, v207, v153
	v_add_f32_e32 v208, v208, v154
	v_add_f32_e32 v209, v209, v155
	v_add_f32_e32 v210, v210, v156
	v_add_f32_e32 v211, v211, v157
	v_add_f32_e32 v212, v212, v158
	v_add_f32_e32 v213, v213, v159
	v_mul_f32_e32 v206, s88, v206
	v_mul_f32_e32 v207, s88, v207
	v_mul_f32_e32 v208, s88, v208
	v_mul_f32_e32 v209, s88, v209
	v_mul_f32_e32 v210, s88, v210
	v_mul_f32_e32 v211, s88, v211
	v_mul_f32_e32 v212, s88, v212
	v_mul_f32_e32 v213, s88, v213
	v_cvt_pk_bf16_f32 v206, v206, v207
	v_cvt_pk_bf16_f32 v207, v208, v209
	v_cvt_pk_bf16_f32 v208, v210, v211
	v_cvt_pk_bf16_f32 v209, v212, v213
	global_store_dwordx4 v149, v[206:209], s[42:43] offset:0
	v_add_f32_e32 v52, v52, v152
	v_add_f32_e32 v53, v53, v153
	v_add_f32_e32 v54, v54, v154
	v_add_f32_e32 v55, v55, v155
	v_add_f32_e32 v44, v44, v156
	v_add_f32_e32 v45, v45, v157
	v_add_f32_e32 v46, v46, v158
	v_add_f32_e32 v47, v47, v159
	v_mul_f32_e32 v52, s88, v52
	v_mul_f32_e32 v53, s88, v53
	v_mul_f32_e32 v54, s88, v54
	v_mul_f32_e32 v55, s88, v55
	v_mul_f32_e32 v44, s88, v44
	v_mul_f32_e32 v45, s88, v45
	v_mul_f32_e32 v46, s88, v46
	v_mul_f32_e32 v47, s88, v47
	v_cvt_pk_bf16_f32 v52, v52, v53
	v_cvt_pk_bf16_f32 v53, v54, v55
	v_cvt_pk_bf16_f32 v54, v44, v45
	v_cvt_pk_bf16_f32 v55, v46, v47
	global_store_dwordx4 v148, v[52:55], s[40:41] offset:0
	s_waitcnt vmcnt(18)
	v_fma_f32 v108, v108, 2.0, -v32
	v_fma_f32 v109, v109, 2.0, -v33
	v_fma_f32 v110, v110, 2.0, -v34
	v_fma_f32 v111, v111, 2.0, -v35
	v_fma_f32 v104, v104, 2.0, -v24
	v_fma_f32 v105, v105, 2.0, -v25
	v_fma_f32 v106, v106, 2.0, -v26
	v_fma_f32 v107, v107, 2.0, -v27
	v_add_f32_e32 v108, v108, v160
	v_add_f32_e32 v109, v109, v161
	v_add_f32_e32 v110, v110, v162
	v_add_f32_e32 v111, v111, v163
	v_add_f32_e32 v104, v104, v164
	v_add_f32_e32 v105, v105, v165
	v_add_f32_e32 v106, v106, v166
	v_add_f32_e32 v107, v107, v167
	v_mul_f32_e32 v108, s88, v108
	v_mul_f32_e32 v109, s88, v109
	v_mul_f32_e32 v110, s88, v110
	v_mul_f32_e32 v111, s88, v111
	v_mul_f32_e32 v104, s88, v104
	v_mul_f32_e32 v105, s88, v105
	v_mul_f32_e32 v106, s88, v106
	v_mul_f32_e32 v107, s88, v107
	v_cvt_pk_bf16_f32 v108, v108, v109
	v_cvt_pk_bf16_f32 v109, v110, v111
	v_cvt_pk_bf16_f32 v110, v104, v105
	v_cvt_pk_bf16_f32 v111, v106, v107
	global_store_dwordx4 v149, v[108:111], s[42:43] offset:256
	v_add_f32_e32 v32, v32, v160
	v_add_f32_e32 v33, v33, v161
	v_add_f32_e32 v34, v34, v162
	v_add_f32_e32 v35, v35, v163
	v_add_f32_e32 v24, v24, v164
	v_add_f32_e32 v25, v25, v165
	v_add_f32_e32 v26, v26, v166
	v_add_f32_e32 v27, v27, v167
	v_mul_f32_e32 v32, s88, v32
	v_mul_f32_e32 v33, s88, v33
	v_mul_f32_e32 v34, s88, v34
	v_mul_f32_e32 v35, s88, v35
	v_mul_f32_e32 v24, s88, v24
	v_mul_f32_e32 v25, s88, v25
	v_mul_f32_e32 v26, s88, v26
	v_mul_f32_e32 v27, s88, v27
	v_cvt_pk_bf16_f32 v32, v32, v33
	v_cvt_pk_bf16_f32 v33, v34, v35
	v_cvt_pk_bf16_f32 v34, v24, v25
	v_cvt_pk_bf16_f32 v35, v26, v27
	global_store_dwordx4 v148, v[32:35], s[40:41] offset:256
	s_waitcnt vmcnt(16)
	s_add_u32 s40, s34, 0x50000
	s_addc_u32 s41, s35, 0
	s_sub_u32 s42, s36, 0x50000
	s_subb_u32 s43, s37, 0
	v_fma_f32 v214, v214, 2.0, -v36
	v_fma_f32 v215, v215, 2.0, -v37
	v_fma_f32 v216, v216, 2.0, -v38
	v_fma_f32 v217, v217, 2.0, -v39
	v_fma_f32 v218, v218, 2.0, -v28
	v_fma_f32 v219, v219, 2.0, -v29
	v_fma_f32 v220, v220, 2.0, -v30
	v_fma_f32 v221, v221, 2.0, -v31
	v_add_f32_e32 v214, v214, v152
	v_add_f32_e32 v215, v215, v153
	v_add_f32_e32 v216, v216, v154
	v_add_f32_e32 v217, v217, v155
	v_add_f32_e32 v218, v218, v156
	v_add_f32_e32 v219, v219, v157
	v_add_f32_e32 v220, v220, v158
	v_add_f32_e32 v221, v221, v159
	v_mul_f32_e32 v214, s88, v214
	v_mul_f32_e32 v215, s88, v215
	v_mul_f32_e32 v216, s88, v216
	v_mul_f32_e32 v217, s88, v217
	v_mul_f32_e32 v218, s88, v218
	v_mul_f32_e32 v219, s88, v219
	v_mul_f32_e32 v220, s88, v220
	v_mul_f32_e32 v221, s88, v221
	v_cvt_pk_bf16_f32 v214, v214, v215
	v_cvt_pk_bf16_f32 v215, v216, v217
	v_cvt_pk_bf16_f32 v216, v218, v219
	v_cvt_pk_bf16_f32 v217, v220, v221
	global_store_dwordx4 v149, v[214:217], s[42:43] offset:0
	v_add_f32_e32 v36, v36, v152
	v_add_f32_e32 v37, v37, v153
	v_add_f32_e32 v38, v38, v154
	v_add_f32_e32 v39, v39, v155
	v_add_f32_e32 v28, v28, v156
	v_add_f32_e32 v29, v29, v157
	v_add_f32_e32 v30, v30, v158
	v_add_f32_e32 v31, v31, v159
	v_mul_f32_e32 v36, s88, v36
	v_mul_f32_e32 v37, s88, v37
	v_mul_f32_e32 v38, s88, v38
	v_mul_f32_e32 v39, s88, v39
	v_mul_f32_e32 v28, s88, v28
	v_mul_f32_e32 v29, s88, v29
	v_mul_f32_e32 v30, s88, v30
	v_mul_f32_e32 v31, s88, v31
	v_cvt_pk_bf16_f32 v36, v36, v37
	v_cvt_pk_bf16_f32 v37, v38, v39
	v_cvt_pk_bf16_f32 v38, v28, v29
	v_cvt_pk_bf16_f32 v39, v30, v31
	global_store_dwordx4 v148, v[36:39], s[40:41] offset:0
	s_waitcnt vmcnt(14)
	v_fma_f32 v96, v96, 2.0, -v16
	v_fma_f32 v97, v97, 2.0, -v17
	v_fma_f32 v98, v98, 2.0, -v18
	v_fma_f32 v99, v99, 2.0, -v19
	v_fma_f32 v88, v88, 2.0, -v8
	v_fma_f32 v89, v89, 2.0, -v9
	v_fma_f32 v90, v90, 2.0, -v10
	v_fma_f32 v91, v91, 2.0, -v11
	v_add_f32_e32 v96, v96, v160
	v_add_f32_e32 v97, v97, v161
	v_add_f32_e32 v98, v98, v162
	v_add_f32_e32 v99, v99, v163
	v_add_f32_e32 v88, v88, v164
	v_add_f32_e32 v89, v89, v165
	v_add_f32_e32 v90, v90, v166
	v_add_f32_e32 v91, v91, v167
	v_mul_f32_e32 v96, s88, v96
	v_mul_f32_e32 v97, s88, v97
	v_mul_f32_e32 v98, s88, v98
	v_mul_f32_e32 v99, s88, v99
	v_mul_f32_e32 v88, s88, v88
	v_mul_f32_e32 v89, s88, v89
	v_mul_f32_e32 v90, s88, v90
	v_mul_f32_e32 v91, s88, v91
	v_cvt_pk_bf16_f32 v96, v96, v97
	v_cvt_pk_bf16_f32 v97, v98, v99
	v_cvt_pk_bf16_f32 v98, v88, v89
	v_cvt_pk_bf16_f32 v99, v90, v91
	global_store_dwordx4 v149, v[96:99], s[42:43] offset:256
	v_add_f32_e32 v16, v16, v160
	v_add_f32_e32 v17, v17, v161
	v_add_f32_e32 v18, v18, v162
	v_add_f32_e32 v19, v19, v163
	v_add_f32_e32 v8, v8, v164
	v_add_f32_e32 v9, v9, v165
	v_add_f32_e32 v10, v10, v166
	v_add_f32_e32 v11, v11, v167
	v_mul_f32_e32 v16, s88, v16
	v_mul_f32_e32 v17, s88, v17
	v_mul_f32_e32 v18, s88, v18
	v_mul_f32_e32 v19, s88, v19
	v_mul_f32_e32 v8, s88, v8
	v_mul_f32_e32 v9, s88, v9
	v_mul_f32_e32 v10, s88, v10
	v_mul_f32_e32 v11, s88, v11
	v_cvt_pk_bf16_f32 v16, v16, v17
	v_cvt_pk_bf16_f32 v17, v18, v19
	v_cvt_pk_bf16_f32 v18, v8, v9
	v_cvt_pk_bf16_f32 v19, v10, v11
	global_store_dwordx4 v148, v[16:19], s[40:41] offset:256
	s_waitcnt vmcnt(12)
	s_add_u32 s40, s34, 0x58000
	s_addc_u32 s41, s35, 0
	s_sub_u32 s42, s36, 0x58000
	s_subb_u32 s43, s37, 0
	v_fma_f32 v168, v168, 2.0, -v20
	v_fma_f32 v169, v169, 2.0, -v21
	v_fma_f32 v170, v170, 2.0, -v22
	v_fma_f32 v171, v171, 2.0, -v23
	v_fma_f32 v172, v172, 2.0, -v12
	v_fma_f32 v173, v173, 2.0, -v13
	v_fma_f32 v174, v174, 2.0, -v14
	v_fma_f32 v175, v175, 2.0, -v15
	v_add_f32_e32 v168, v168, v152
	v_add_f32_e32 v169, v169, v153
	v_add_f32_e32 v170, v170, v154
	v_add_f32_e32 v171, v171, v155
	v_add_f32_e32 v172, v172, v156
	v_add_f32_e32 v173, v173, v157
	v_add_f32_e32 v174, v174, v158
	v_add_f32_e32 v175, v175, v159
	v_mul_f32_e32 v168, s88, v168
	v_mul_f32_e32 v169, s88, v169
	v_mul_f32_e32 v170, s88, v170
	v_mul_f32_e32 v171, s88, v171
	v_mul_f32_e32 v172, s88, v172
	v_mul_f32_e32 v173, s88, v173
	v_mul_f32_e32 v174, s88, v174
	v_mul_f32_e32 v175, s88, v175
	v_cvt_pk_bf16_f32 v168, v168, v169
	v_cvt_pk_bf16_f32 v169, v170, v171
	v_cvt_pk_bf16_f32 v170, v172, v173
	v_cvt_pk_bf16_f32 v171, v174, v175
	global_store_dwordx4 v149, v[168:171], s[42:43] offset:0
	v_add_f32_e32 v20, v20, v152
	v_add_f32_e32 v21, v21, v153
	v_add_f32_e32 v22, v22, v154
	v_add_f32_e32 v23, v23, v155
	v_add_f32_e32 v12, v12, v156
	v_add_f32_e32 v13, v13, v157
	v_add_f32_e32 v14, v14, v158
	v_add_f32_e32 v15, v15, v159
	v_mul_f32_e32 v20, s88, v20
	v_mul_f32_e32 v21, s88, v21
	v_mul_f32_e32 v22, s88, v22
	v_mul_f32_e32 v23, s88, v23
	v_mul_f32_e32 v12, s88, v12
	v_mul_f32_e32 v13, s88, v13
	v_mul_f32_e32 v14, s88, v14
	v_mul_f32_e32 v15, s88, v15
	v_cvt_pk_bf16_f32 v20, v20, v21
	v_cvt_pk_bf16_f32 v21, v22, v23
	v_cvt_pk_bf16_f32 v22, v12, v13
	v_cvt_pk_bf16_f32 v23, v14, v15
	global_store_dwordx4 v148, v[20:23], s[40:41] offset:0
	s_waitcnt vmcnt(10)
	v_fma_f32 v100, v100, 2.0, -v4
	v_fma_f32 v101, v101, 2.0, -v5
	v_fma_f32 v102, v102, 2.0, -v6
	v_fma_f32 v103, v103, 2.0, -v7
	v_fma_f32 v92, v92, 2.0, -v0
	v_fma_f32 v93, v93, 2.0, -v1
	v_fma_f32 v94, v94, 2.0, -v2
	v_fma_f32 v95, v95, 2.0, -v3
	v_add_f32_e32 v100, v100, v160
	v_add_f32_e32 v101, v101, v161
	v_add_f32_e32 v102, v102, v162
	v_add_f32_e32 v103, v103, v163
	v_add_f32_e32 v92, v92, v164
	v_add_f32_e32 v93, v93, v165
	v_add_f32_e32 v94, v94, v166
	v_add_f32_e32 v95, v95, v167
	v_mul_f32_e32 v100, s88, v100
	v_mul_f32_e32 v101, s88, v101
	v_mul_f32_e32 v102, s88, v102
	v_mul_f32_e32 v103, s88, v103
	v_mul_f32_e32 v92, s88, v92
	v_mul_f32_e32 v93, s88, v93
	v_mul_f32_e32 v94, s88, v94
	v_mul_f32_e32 v95, s88, v95
	v_cvt_pk_bf16_f32 v100, v100, v101
	v_cvt_pk_bf16_f32 v101, v102, v103
	v_cvt_pk_bf16_f32 v102, v92, v93
	v_cvt_pk_bf16_f32 v103, v94, v95
	global_store_dwordx4 v149, v[100:103], s[42:43] offset:256
	v_add_f32_e32 v4, v4, v160
	v_add_f32_e32 v5, v5, v161
	v_add_f32_e32 v6, v6, v162
	v_add_f32_e32 v7, v7, v163
	v_add_f32_e32 v0, v0, v164
	v_add_f32_e32 v1, v1, v165
	v_add_f32_e32 v2, v2, v166
	v_add_f32_e32 v3, v3, v167
	v_mul_f32_e32 v4, s88, v4
	v_mul_f32_e32 v5, s88, v5
	v_mul_f32_e32 v6, s88, v6
	v_mul_f32_e32 v7, s88, v7
	v_mul_f32_e32 v0, s88, v0
	v_mul_f32_e32 v1, s88, v1
	v_mul_f32_e32 v2, s88, v2
	v_mul_f32_e32 v3, s88, v3
	v_cvt_pk_bf16_f32 v4, v4, v5
	v_cvt_pk_bf16_f32 v5, v6, v7
	v_cvt_pk_bf16_f32 v6, v0, v1
	v_cvt_pk_bf16_f32 v7, v2, v3
	global_store_dwordx4 v148, v[4:7], s[40:41] offset:256
	s_branch .Ldfs_end
.Ldfs_xepi:
	s_lshl_b32 s46, s52, 11
	s_lshl_b32 s47, s3, 2
	s_add_i32 s46, s46, s47
	s_add_i32 s46, s46, 0x30000
	s_add_u32 s46, s94, s46
	s_addc_u32 s47, s95, 0
	v_or_b32_e32 v145, s71, v129
	v_lshlrev_b32_e32 v146, 2, v145
	global_load_dwordx4 v[152:155], v146, s[46:47] offset:0
	global_load_dwordx4 v[156:159], v146, s[46:47] offset:16
	global_load_dwordx4 v[160:163], v146, s[46:47] offset:512
	global_load_dwordx4 v[164:167], v146, s[46:47] offset:528
	v_and_b32_e32 v147, 1, v140
	v_lshlrev_b32_e32 v147, 31, v147
	v_lshlrev_b32_e32 v148, 11, v128
	v_lshl_add_u32 v148, v145, 1, v148
	s_lshl_b32 s34, s52, 11
	s_add_i32 s36, s34, 0x781
	s_sub_i32 s36, s36, s58
	s_or_b32 s34, s34, s58
	s_lshl_b32 s34, s34, 11
	s_lshl_b32 s36, s36, 11
	s_lshl_b32 s0, s3, 1
	s_add_i32 s0, s0, 0x4b00400
	s_add_i32 s34, s34, s0
	s_add_i32 s36, s36, s0
	s_add_u32 s34, s94, s34
	s_addc_u32 s35, s95, 0
	s_add_u32 s36, s94, s36
	s_addc_u32 s37, s95, 0
	s_waitcnt vmcnt(0)
	v_xor_b32_e32 v152, v147, v152
	v_xor_b32_e32 v153, v147, v153
	v_xor_b32_e32 v154, v147, v154
	v_xor_b32_e32 v155, v147, v155
	v_xor_b32_e32 v156, v147, v156
	v_xor_b32_e32 v157, v147, v157
	v_xor_b32_e32 v158, v147, v158
	v_xor_b32_e32 v159, v147, v159
	v_xor_b32_e32 v160, v147, v160
	v_xor_b32_e32 v161, v147, v161
	v_xor_b32_e32 v162, v147, v162
	v_xor_b32_e32 v163, v147, v163
	v_xor_b32_e32 v164, v147, v164
	v_xor_b32_e32 v165, v147, v165
	v_xor_b32_e32 v166, v147, v166
	v_xor_b32_e32 v167, v147, v167
	v_cmp_eq_u32_e32 vcc, 0, v128
	s_and_saveexec_b64 s[80:81], vcc
	v_add_f32_e32 v124, v124, v152
	v_add_f32_e32 v125, v125, v153
	v_add_f32_e32 v126, v126, v154
	v_add_f32_e32 v127, v127, v155
	v_add_f32_e32 v120, v120, v156
	v_add_f32_e32 v121, v121, v157
	v_add_f32_e32 v122, v122, v158
	v_add_f32_e32 v123, v123, v159
	v_mul_f32_e32 v124, s88, v124
	v_mul_f32_e32 v125, s88, v125
	v_mul_f32_e32 v126, s88, v126
	v_mul_f32_e32 v127, s88, v127
	v_mul_f32_e32 v120, s88, v120
	v_mul_f32_e32 v121, s88, v121
	v_mul_f32_e32 v122, s88, v122
	v_mul_f32_e32 v123, s88, v123
	v_cvt_pk_bf16_f32 v124, v124, v125
	v_cvt_pk_bf16_f32 v125, v126, v127
	v_cvt_pk_bf16_f32 v126, v120, v121
	v_cvt_pk_bf16_f32 v127, v122, v123
	global_store_dwordx4 v148, v[124:127], s[34:35] offset:0
	v_add_f32_e32 v116, v116, v160
	v_add_f32_e32 v117, v117, v161
	v_add_f32_e32 v118, v118, v162
	v_add_f32_e32 v119, v119, v163
	v_add_f32_e32 v112, v112, v164
	v_add_f32_e32 v113, v113, v165
	v_add_f32_e32 v114, v114, v166
	v_add_f32_e32 v115, v115, v167
	v_mul_f32_e32 v116, s88, v116
	v_mul_f32_e32 v117, s88, v117
	v_mul_f32_e32 v118, s88, v118
	v_mul_f32_e32 v119, s88, v119
	v_mul_f32_e32 v112, s88, v112
	v_mul_f32_e32 v113, s88, v113
	v_mul_f32_e32 v114, s88, v114
	v_mul_f32_e32 v115, s88, v115
	v_cvt_pk_bf16_f32 v116, v116, v117
	v_cvt_pk_bf16_f32 v117, v118, v119
	v_cvt_pk_bf16_f32 v118, v112, v113
	v_cvt_pk_bf16_f32 v119, v114, v115
	global_store_dwordx4 v148, v[116:119], s[34:35] offset:256
	s_mov_b64 exec, s[80:81]
.Ldfs_end:
	v_readlane_b32 s11, v255, 22
	s_movk_i32 s12, 0x110
	s_waitcnt vmcnt(0)
	s_barrier
.Ldfs_skip:
	s_mov_b64 s[0:1], 0
.LBB0_573:
	s_and_b64 vcc, exec, s[0:1]
	s_cbranch_vccz .LBB0_602
	s_mov_b64 s[58:59], s[94:95]
	s_mov_b64 s[46:47], s[94:95]
	s_mov_b64 s[42:43], s[94:95]
	s_mov_b64 s[34:35], s[94:95]
	s_mov_b64 s[0:1], s[94:95]
	s_add_u32 s0, s0, s76
	s_addc_u32 s1, s1, 0
	s_add_u32 s0, s0, 0x20000
	s_addc_u32 s1, s1, 0
	s_lshl_b32 s22, s77, 5
	s_and_b32 s22, s22, 0xf800
	s_add_i32 s40, s22, 0xffffb000
	s_lshl_b32 s22, s77, 7
	s_and_b32 s73, s22, 0x780
	s_or_b32 s36, s40, s73
	s_mov_b32 s37, s53
	s_bfe_u32 s3, s77, 0x20004
	s_lshl_b64 s[60:61], s[36:37], 10
	s_add_u32 s22, s58, s60
	v_mov_b32_e32 v18, v226
	s_addc_u32 s37, s59, s61
	s_lshl_b32 s41, s3, 8
	s_add_u32 s58, s22, s41
	v_lshlrev_b32_e32 v0, 4, v18
	v_add_u32_e32 v30, 0x200, v18
	v_add_u32_e32 v10, 0x400, v18
	v_add_u32_e32 v12, 0x600, v18
	s_addc_u32 s59, s37, 0
	v_and_b32_e32 v20, 0xf0, v0
	v_mov_b32_e32 v21, v177
	v_ashrrev_i32_e32 v22, 4, v18
	v_ashrrev_i32_e32 v24, 4, v30
	v_ashrrev_i32_e32 v26, 4, v10
	v_ashrrev_i32_e32 v28, 4, v12
	s_mul_i32 s22, s3, 0x208
	v_lshl_add_u64 v[0:1], s[58:59], 0, v[20:21]
	s_mov_b64 s[14:15], 0x8b00000
	v_ashrrev_i32_e32 v23, 31, v22
	v_ashrrev_i32_e32 v25, 31, v24
	v_ashrrev_i32_e32 v27, 31, v26
	v_ashrrev_i32_e32 v29, 31, v28
	v_add_u32_e32 v32, s22, v18
	v_lshl_add_u64 v[8:9], v[0:1], 0, s[14:15]
	v_lshlrev_b64 v[16:17], 10, v[22:23]
	v_lshlrev_b64 v[2:3], 10, v[24:25]
	v_lshlrev_b64 v[10:11], 10, v[26:27]
	v_lshlrev_b64 v[12:13], 10, v[28:29]
	v_ashrrev_i32_e32 v33, 31, v32
	v_lshl_add_u64 v[0:1], v[8:9], 0, v[16:17]
	v_lshl_add_u64 v[2:3], v[8:9], 0, v[2:3]
	v_lshl_add_u64 v[10:11], v[8:9], 0, v[10:11]
	v_lshl_add_u64 v[8:9], v[8:9], 0, v[12:13]
	v_lshl_add_u64 v[32:33], v[32:33], 2, s[0:1]
	flat_load_dwordx4 v[4:7], v[0:1]
	s_nop 0
	flat_load_dwordx4 v[0:3], v[2:3]
	s_nop 0
	flat_load_dwordx4 v[12:15], v[10:11]
	s_nop 0
	flat_load_dwordx4 v[8:11], v[8:9]
	v_readfirstlane_b32 s58, v18
	flat_load_dword v21, v[32:33]
	v_mov_b32_e32 v80, 0x100
	v_cmp_lt_u32_e32 vcc, 0x1c0, v18
	s_nop 1
	v_cndmask_b32_e64 v81, 0, 1, vcc
	v_mul_u32_u24_e32 v84, 0x1c1, v81
	v_sub_u32_e32 v82, v18, v84
	v_add_u32_e32 v82, 0xffffffa0, v82
	v_med3_i32 v82, v82, 0, v80
	v_mul_u32_u24_e32 v84, 0x104, v81
	v_add3_u32 v82, v82, v84, s22
	v_mov_b32_e32 v83, 0
	v_lshl_add_u64 v[82:83], v[82:83], 2, s[0:1]
	global_load_dword v88, v[82:83], off
	v_add_u32_e32 v85, 0x200, v18
	v_min_u32_e32 v85, 0x381, v85
	v_add_u32_e32 v86, 0xfffffddf, v85
	v_med3_i32 v86, v86, 0, v80
	v_add_u32_e32 v86, 0x104, v86
	v_add_u32_e32 v86, s22, v86
	v_mov_b32_e32 v87, 0
	v_lshl_add_u64 v[86:87], v[86:87], 2, s[0:1]
	global_load_dword v89, v[86:87], off
	v_cmp_gt_i32_e32 vcc, 8, v18
	v_mov_b32_e32 v19, 0
	v_mov_b32_e32 v25, 0
	s_and_saveexec_b64 s[68:69], vcc
	s_cbranch_execz .LBB0_576
	v_add_u32_e32 v30, s22, v30
	v_ashrrev_i32_e32 v31, 31, v30
	v_lshl_add_u64 v[30:31], v[30:31], 2, s[0:1]
	flat_load_dword v25, v[30:31]

.LBB0_603:
	s_andn2_b64 vcc, exec, s[0:1]
	s_cbranch_vccnz .LBB0_611
	s_add_i32 s0, s77, 0xfffffe00
	s_lshr_b32 s52, s0, 5
	s_lshl_b32 s0, s77, 7
	s_and_b32 s58, s0, 0xf00
	s_cmpk_gt_u32 s58, 0x800
	s_cbranch_scc1 .LBB0_611
	s_movk_i32 s100, 0x100
	s_mov_b32 s101, 0
	s_mov_b64 s[42:43], s[94:95]
	s_lshl_b32 s0, s58, 13
	s_add_u32 s48, s42, s0
	s_addc_u32 s49, s43, 0
	s_add_u32 s34, s48, 0x2b00000
	s_mov_b64 s[0:1], s[94:95]
	s_addc_u32 s35, s49, 0
	s_lshl_b64 s[36:37], s[52:53], 22
	s_add_u32 s0, s0, s36
	s_addc_u32 s1, s1, s37
	s_lshl_b32 s3, s77, 8
	s_and_b32 s3, s3, 0x100
	s_lshl_b32 s36, s3, 13
	s_add_u32 s62, s0, s36
	s_addc_u32 s63, s1, 0
	s_mov_b64 s[36:37], s[94:95]
	s_mov_b64 s[0:1], s[94:95]
	v_mov_b32_e32 v140, v226
	s_mov_b32 s7, 0x7ffe0
	v_ashrrev_i32_e32 v1, 31, v140
	v_lshrrev_b32_e32 v1, 26, v1
	v_add_u32_e32 v1, v140, v1
	v_ashrrev_i32_e32 v8, 6, v1
	v_bfe_i32 v1, v140, 27, 1
	v_lshlrev_b32_e32 v0, 4, v140
	v_lshrrev_b32_e32 v1, 22, v1
	v_add_u32_e32 v1, v0, v1
	v_and_b32_e32 v1, 0xfffffc00, v1
	v_sub_u32_e32 v1, v0, v1
	v_lshrrev_b32_e32 v2, 4, v1
	v_bitop3_b32 v2, v2, v1, 32 bitop3:0x6c
	v_ashrrev_i32_e32 v1, 31, v1
	v_lshrrev_b32_e32 v1, 26, v1
	v_add_u32_e32 v1, v2, v1
	v_ashrrev_i32_e32 v9, 6, v1
	v_lshlrev_b32_e32 v3, 3, v8
	v_mul_i32_i24_e32 v4, 64, v9
	v_and_b32_e32 v3, -16, v3
	v_sub_u32_e32 v2, v2, v4
	v_add_u32_e32 v1, v9, v3
	v_lshlrev_b32_e32 v3, 5, v8
	v_ashrrev_i16_sdwa v2, v230, sext(v2) dst_sel:DWORD dst_unused:UNUSED_PAD src0_sel:DWORD src1_sel:BYTE_0
	v_and_b32_e32 v3, 32, v3
	v_bfe_i32 v10, v2, 0, 16
	v_and_b32_e32 v5, 3, v9
	v_add_lshl_u32 v3, v3, v10, 1
	v_add_u32_e32 v0, 0x2000, v0
	v_lshlrev_b32_e32 v2, 1, v1
	v_lshrrev_b32_e32 v4, 2, v1
	v_and_or_b32 v5, v1, s7, v5
	v_lshl_add_u32 v130, v1, 13, v3
	v_ashrrev_i32_e32 v1, 31, v0
	v_lshrrev_b32_e32 v1, 22, v1
	v_add_u32_e32 v1, v0, v1
	v_ashrrev_i32_e32 v11, 10, v1
	v_mul_i32_i24_e32 v1, 0x400, v11
	v_sub_u32_e32 v0, v0, v1
	v_and_b32_e32 v2, 24, v2
	v_and_b32_e32 v4, 4, v4
	v_lshrrev_b32_e32 v1, 4, v0
	v_or3_b32 v2, v5, v4, v2
	v_bitop3_b32 v0, v1, v0, 32 bitop3:0x6c
	v_lshl_add_u32 v176, v2, 13, v3
	v_ashrrev_i32_e32 v2, 31, v0
	v_lshrrev_b32_e32 v2, 26, v2
	v_add_u32_e32 v2, v0, v2
	s_add_u32 s40, s62, 0xeb00000
	v_readfirstlane_b32 s59, v140
	v_lshlrev_b32_e32 v1, 3, v11
	v_ashrrev_i32_e32 v12, 6, v2
	v_and_b32_e32 v2, 0xc0, v2
	s_addc_u32 s41, s63, 0
	s_ashr_i32 s46, s59, 6
	v_and_b32_e32 v1, -16, v1
	v_sub_u32_e32 v0, v0, v2
	v_add_u32_e32 v1, v12, v1
	v_ashrrev_i16_sdwa v0, v230, sext(v0) dst_sel:DWORD dst_unused:UNUSED_PAD src0_sel:DWORD src1_sel:BYTE_0
	s_lshl_b32 s60, s46, 10
	v_lshlrev_b32_e32 v3, 5, v11
	v_bfe_i32 v13, v0, 0, 16
	v_lshlrev_b32_e32 v0, 1, v1
	v_lshrrev_b32_e32 v2, 2, v1
	v_and_b32_e32 v4, 3, v12
	s_add_i32 s61, s60, 0
	v_and_b32_e32 v3, 32, v3
	v_and_b32_e32 v0, 24, v0
	v_and_b32_e32 v2, 4, v2
	v_and_or_b32 v4, v1, s7, v4
	s_add_i32 m0, s61, 0x10000
	v_or3_b32 v0, v4, v2, v0
	v_add_lshl_u32 v2, v3, v13, 1
	s_ashr_i32 s47, s59, 8
	global_load_lds_dwordx4 v176, s[40:41]
	s_add_i32 m0, s61, 0x12000
	v_lshl_add_u32 v134, v0, 13, v2
	s_add_u32 s62, s62, 0xec00000
	global_load_lds_dwordx4 v134, s[40:41]
	s_addc_u32 s63, s63, 0
	s_add_i32 m0, s61, 0x14000
	v_lshl_add_u32 v132, v1, 13, v2
	global_load_lds_dwordx4 v176, s[62:63]
	s_add_i32 m0, s61, 0x16000
	v_mov_b32_e32 v135, v177
	global_load_lds_dwordx4 v134, s[62:63]
	s_add_i32 s62, s61, 0x2000
	s_mov_b32 m0, s61
	s_add_u32 s68, s48, 0x2c00000
	global_load_lds_dwordx4 v130, s[34:35]
	s_mov_b32 m0, s62
	s_addc_u32 s69, s49, 0
	s_add_i32 s63, s61, 0x4000
	global_load_lds_dwordx4 v132, s[34:35]
	s_mov_b32 m0, s63
	s_add_i32 s70, s61, 0x6000
	global_load_lds_dwordx4 v130, s[68:69]
	s_mov_b32 m0, s70
	v_mov_b32_e32 v131, v177
	global_load_lds_dwordx4 v132, s[68:69]
	v_mov_b32_e32 v133, v177
	v_lshl_add_u64 v[6:7], s[40:41], 0, v[176:177]
	v_lshl_add_u64 v[4:5], s[40:41], 0, v[134:135]
	v_lshl_add_u64 v[2:3], s[34:35], 0, v[130:131]
	s_cmp_lg_u32 s47, 1
	v_lshl_add_u64 v[0:1], s[34:35], 0, v[132:133]
	s_cbranch_scc1 .LBB0_606
	s_barrier
.LBB0_606:
	v_lshrrev_b32_e32 v15, 1, v140
	v_and_b32_e32 v129, 24, v15
	v_and_b32_e32 v14, 15, v140
	v_lshlrev_b32_e32 v15, 1, v129
	s_lshl_b32 s46, s46, 5
	v_lshl_or_b32 v128, s47, 6, v14
	v_lshl_or_b32 v14, v14, 6, v15
	v_lshlrev_b32_e32 v15, 2, v140
	s_and_b32 s71, s46, 0x60
	s_add_i32 m0, s61, 0x18000
	v_lshl_add_u64 v[6:7], v[6:7], 0, s[100:101]
	v_and_b32_e32 v15, 32, v15
	s_lshl_b32 s47, s47, 13
	s_lshl_b32 s46, s71, 7
	s_waitcnt vmcnt(2)
	s_barrier
	global_load_lds_dwordx4 v[6:7], off
	v_lshl_add_u64 v[4:5], v[4:5], 0, s[100:101]
	s_add_i32 m0, s61, 0x1a000
	s_add_i32 s72, s61, 0x8000
	s_add_i32 s73, s61, 0xa000
	v_bitop3_b32 v141, v14, s46, v15 bitop3:0xde
	global_load_lds_dwordx4 v[4:5], off
	v_lshl_add_u64 v[2:3], v[2:3], 0, s[100:101]
	s_mov_b32 m0, s72
	s_add_u32 s46, s40, 0x100100
	v_bitop3_b32 v16, v14, s47, v15 bitop3:0xde
	global_load_lds_dwordx4 v[2:3], off
	v_lshl_add_u64 v[0:1], v[0:1], 0, s[100:101]
	s_mov_b32 m0, s73
	s_addc_u32 s47, s41, 0
	global_load_lds_dwordx4 v[0:1], off
	s_add_i32 m0, s61, 0x1c000
	v_lshl_add_u64 v[0:1], s[46:47], 0, v[176:177]
	global_load_lds_dwordx4 v[0:1], off
	v_lshl_add_u64 v[0:1], s[46:47], 0, v[134:135]
	s_add_i32 m0, s61, 0x1e000
	s_lshl_b32 s46, s77, 20
	global_load_lds_dwordx4 v[0:1], off
	v_lshlrev_b32_e32 v0, 16, v11
	v_and_b32_e32 v0, 0xfffe0000, v0
	s_and_b32 s46, s46, 0x1e00000
	v_lshl_add_u32 v0, v12, 13, v0
	v_and_b32_e32 v1, 1, v11
	v_lshl_or_b32 v0, v1, 6, v0
	s_add_u32 s42, s42, s46
	v_lshl_add_u32 v0, v13, 1, v0
	v_mov_b32_e32 v1, v177
	s_addc_u32 s43, s43, 0
	v_lshl_add_u64 v[136:137], s[42:43], 0, v[0:1]
	v_lshlrev_b32_e32 v0, 16, v8
	v_and_b32_e32 v0, 0xfffe0000, v0
	v_lshl_add_u32 v0, v9, 13, v0
	v_and_b32_e32 v1, 1, v8
	v_lshl_or_b32 v0, v1, 6, v0
	s_waitcnt vmcnt(6)
	v_lshl_add_u32 v0, v10, 1, v0
	v_mov_b32_e32 v1, v177
	v_lshl_add_u64 v[138:139], s[42:43], 0, v[0:1]
	v_mov_b32_e32 v0, 0
	s_mov_b32 s78, -2
	s_mov_b64 s[42:43], 0x2c00100
	v_add_u32_e32 v142, 0, v16
	v_mov_b32_e32 v1, v0
	v_mov_b32_e32 v2, v0
	v_mov_b32_e32 v3, v0
	v_mov_b32_e32 v4, v0
	v_mov_b32_e32 v5, v0
	v_mov_b32_e32 v6, v0
	v_mov_b32_e32 v7, v0
	v_mov_b32_e32 v8, v0
	v_mov_b32_e32 v9, v0
	v_mov_b32_e32 v10, v0
	v_mov_b32_e32 v11, v0
	v_mov_b32_e32 v16, v0
	v_mov_b32_e32 v17, v0
	v_mov_b32_e32 v18, v0
	v_mov_b32_e32 v19, v0
	v_mov_b32_e32 v24, v0
	v_mov_b32_e32 v25, v0
	v_mov_b32_e32 v26, v0
	v_mov_b32_e32 v27, v0
	v_mov_b32_e32 v32, v0
	v_mov_b32_e32 v33, v0
	v_mov_b32_e32 v34, v0
	v_mov_b32_e32 v35, v0
	v_mov_b32_e32 v40, v0
	v_mov_b32_e32 v41, v0
	v_mov_b32_e32 v42, v0
	v_mov_b32_e32 v43, v0
	v_mov_b32_e32 v48, v0
	v_mov_b32_e32 v49, v0
	v_mov_b32_e32 v50, v0
	v_mov_b32_e32 v51, v0
	v_mov_b32_e32 v12, v0
	v_mov_b32_e32 v13, v0
	v_mov_b32_e32 v14, v0
	v_mov_b32_e32 v15, v0
	v_mov_b32_e32 v20, v0
	v_mov_b32_e32 v21, v0
	v_mov_b32_e32 v22, v0
	v_mov_b32_e32 v23, v0
	v_mov_b32_e32 v28, v0
	v_mov_b32_e32 v29, v0
	v_mov_b32_e32 v30, v0
	v_mov_b32_e32 v31, v0
	v_mov_b32_e32 v36, v0
	v_mov_b32_e32 v37, v0
	v_mov_b32_e32 v38, v0
	v_mov_b32_e32 v39, v0
	v_mov_b32_e32 v44, v0
	v_mov_b32_e32 v45, v0
	v_mov_b32_e32 v46, v0
	v_mov_b32_e32 v47, v0
	v_mov_b32_e32 v52, v0
	v_mov_b32_e32 v53, v0
	v_mov_b32_e32 v54, v0
	v_mov_b32_e32 v55, v0
	v_mov_b32_e32 v56, v0
	v_mov_b32_e32 v57, v0
	v_mov_b32_e32 v58, v0
	v_mov_b32_e32 v59, v0
	v_mov_b32_e32 v60, v0
	v_mov_b32_e32 v61, v0
	v_mov_b32_e32 v62, v0
	v_mov_b32_e32 v63, v0
	v_mov_b32_e32 v64, v0
	v_mov_b32_e32 v65, v0
	v_mov_b32_e32 v66, v0
	v_mov_b32_e32 v67, v0
	v_mov_b32_e32 v68, v0
	v_mov_b32_e32 v69, v0
	v_mov_b32_e32 v70, v0
	v_mov_b32_e32 v71, v0
	v_mov_b32_e32 v72, v0
	v_mov_b32_e32 v73, v0
	v_mov_b32_e32 v74, v0
	v_mov_b32_e32 v75, v0
	v_mov_b32_e32 v80, v0
	v_mov_b32_e32 v81, v0
	v_mov_b32_e32 v82, v0
	v_mov_b32_e32 v83, v0
	v_mov_b32_e32 v88, v0
	v_mov_b32_e32 v89, v0
	v_mov_b32_e32 v90, v0
	v_mov_b32_e32 v91, v0
	s_waitcnt vmcnt(0)
	v_mov_b32_e32 v96, v0
	v_mov_b32_e32 v97, v0
	v_mov_b32_e32 v98, v0
	v_mov_b32_e32 v99, v0
	v_mov_b32_e32 v112, v0
	v_mov_b32_e32 v113, v0
	v_mov_b32_e32 v114, v0
	v_mov_b32_e32 v115, v0
	v_mov_b32_e32 v116, v0
	v_mov_b32_e32 v117, v0
	v_mov_b32_e32 v118, v0
	v_mov_b32_e32 v119, v0
	v_mov_b32_e32 v76, v0
	v_mov_b32_e32 v77, v0
	v_mov_b32_e32 v78, v0
	v_mov_b32_e32 v79, v0
	v_mov_b32_e32 v84, v0
	v_mov_b32_e32 v85, v0
	v_mov_b32_e32 v86, v0
	v_mov_b32_e32 v87, v0
	v_mov_b32_e32 v92, v0
	v_mov_b32_e32 v93, v0
	v_mov_b32_e32 v94, v0
	v_mov_b32_e32 v95, v0
	v_mov_b32_e32 v100, v0
	v_mov_b32_e32 v101, v0
	v_mov_b32_e32 v102, v0
	v_mov_b32_e32 v103, v0
	v_mov_b32_e32 v104, v0
	v_mov_b32_e32 v105, v0
	v_mov_b32_e32 v106, v0
	v_mov_b32_e32 v107, v0
	v_mov_b32_e32 v108, v0
	v_mov_b32_e32 v109, v0
	v_mov_b32_e32 v110, v0
	v_mov_b32_e32 v111, v0
	v_mov_b32_e32 v120, v0
	v_mov_b32_e32 v121, v0
	v_mov_b32_e32 v122, v0
	v_mov_b32_e32 v123, v0
	v_mov_b32_e32 v124, v0
	v_mov_b32_e32 v125, v0
	v_mov_b32_e32 v126, v0
	v_mov_b32_e32 v127, v0
	s_barrier
.LBB0_607:
	s_add_u32 s46, s42, 0xfd400100
	s_addc_u32 s47, s43, -1
	s_andn2_b32 s48, 0x80, s42
	s_cmp_lg_u32 s78, 28
	s_cselect_b32 s46, s46, s48
	s_cselect_b32 s47, s47, 0
	s_add_u32 s68, s34, s46
	s_addc_u32 s69, s35, s47
	s_add_i32 s48, 0, 0x10000
	s_add_u32 s46, s40, s46
	v_add_u32_e32 v143, s48, v141
	s_addc_u32 s47, s41, s47
	s_add_i32 s49, 0, 0x14000
	ds_read_b128 v[144:147], v143
	ds_read_b128 v[148:151], v143 offset:1024
	ds_read_b128 v[152:155], v143 offset:2048
	ds_read_b128 v[156:159], v143 offset:3072
	v_add_u32_e32 v143, s49, v141
	ds_read_b128 v[160:163], v143
	ds_read_b128 v[164:167], v143 offset:1024
	ds_read_b128 v[168:171], v143 offset:2048
	ds_read_b128 v[172:175], v143 offset:3072
	v_lshl_add_u64 v[186:187], v[138:139], 0, s[42:43]
	s_add_i32 m0, s61, 0xc000
	ds_read_b128 v[190:193], v142
	ds_read_b128 v[194:197], v142 offset:1024
	ds_read_b128 v[198:201], v142 offset:2048
	ds_read_b128 v[202:205], v142 offset:3072
	ds_read_b128 v[206:209], v142 offset:4096
	ds_read_b128 v[210:213], v142 offset:5120
	ds_read_b128 v[214:217], v142 offset:6144
	ds_read_b128 v[218:221], v142 offset:7168
	global_load_lds_dwordx4 v[186:187], off
	v_lshl_add_u64 v[186:187], v[136:137], 0, s[42:43]
	s_add_i32 m0, s61, 0xe000
	s_nop 0
	global_load_lds_dwordx4 v[186:187], off
	s_waitcnt vmcnt(8)
	s_waitcnt lgkmcnt(0)
	s_barrier
	s_setprio 1
	s_waitcnt lgkmcnt(0)
	v_mfma_f32_16x16x32_bf16 v[124:127], v[144:147], v[190:193], v[124:127]
	v_mfma_f32_16x16x32_bf16 v[120:123], v[152:155], v[190:193], v[120:123]
	v_mfma_f32_16x16x32_bf16 v[108:111], v[144:147], v[198:201], v[108:111]
	v_mfma_f32_16x16x32_bf16 v[104:107], v[152:155], v[198:201], v[104:107]
	v_mfma_f32_16x16x32_bf16 v[100:103], v[144:147], v[206:209], v[100:103]
	v_mfma_f32_16x16x32_bf16 v[92:95], v[152:155], v[206:209], v[92:95]
	v_mfma_f32_16x16x32_bf16 v[84:87], v[144:147], v[214:217], v[84:87]
	v_mfma_f32_16x16x32_bf16 v[76:79], v[152:155], v[214:217], v[76:79]
	v_mfma_f32_16x16x32_bf16 v[124:127], v[148:151], v[194:197], v[124:127]
	v_mfma_f32_16x16x32_bf16 v[120:123], v[156:159], v[194:197], v[120:123]
	v_mfma_f32_16x16x32_bf16 v[108:111], v[148:151], v[202:205], v[108:111]
	v_mfma_f32_16x16x32_bf16 v[104:107], v[156:159], v[202:205], v[104:107]
	v_mfma_f32_16x16x32_bf16 v[100:103], v[148:151], v[210:213], v[100:103]
	v_mfma_f32_16x16x32_bf16 v[92:95], v[156:159], v[210:213], v[92:95]
	v_mfma_f32_16x16x32_bf16 v[84:87], v[148:151], v[218:221], v[84:87]
	v_mfma_f32_16x16x32_bf16 v[76:79], v[156:159], v[218:221], v[76:79]
	s_setprio 0
	s_setprio 1
	v_mfma_f32_16x16x32_bf16 v[116:119], v[160:163], v[190:193], v[116:119]
	v_mfma_f32_16x16x32_bf16 v[112:115], v[168:171], v[190:193], v[112:115]
	v_mfma_f32_16x16x32_bf16 v[96:99], v[160:163], v[198:201], v[96:99]
	v_mfma_f32_16x16x32_bf16 v[88:91], v[168:171], v[198:201], v[88:91]
	v_mfma_f32_16x16x32_bf16 v[80:83], v[160:163], v[206:209], v[80:83]
	v_mfma_f32_16x16x32_bf16 v[72:75], v[168:171], v[206:209], v[72:75]
	v_mfma_f32_16x16x32_bf16 v[68:71], v[160:163], v[214:217], v[68:71]
	v_mfma_f32_16x16x32_bf16 v[64:67], v[168:171], v[214:217], v[64:67]
	v_mfma_f32_16x16x32_bf16 v[116:119], v[164:167], v[194:197], v[116:119]
	v_mfma_f32_16x16x32_bf16 v[112:115], v[172:175], v[194:197], v[112:115]
	v_mfma_f32_16x16x32_bf16 v[96:99], v[164:167], v[202:205], v[96:99]
	v_mfma_f32_16x16x32_bf16 v[88:91], v[172:175], v[202:205], v[88:91]
	v_mfma_f32_16x16x32_bf16 v[80:83], v[164:167], v[210:213], v[80:83]
	v_mfma_f32_16x16x32_bf16 v[72:75], v[172:175], v[210:213], v[72:75]
	v_mfma_f32_16x16x32_bf16 v[68:71], v[164:167], v[218:221], v[68:71]
	v_mfma_f32_16x16x32_bf16 v[64:67], v[172:175], v[218:221], v[64:67]
	s_setprio 0
	s_barrier
	s_add_i32 s48, s48, s60
	v_lshl_add_u64 v[186:187], s[46:47], 0, v[176:177]
	s_mov_b32 m0, s48
	ds_read_b128 v[190:193], v142 offset:16384
	ds_read_b128 v[194:197], v142 offset:17408
	ds_read_b128 v[198:201], v142 offset:18432
	ds_read_b128 v[202:205], v142 offset:19456
	ds_read_b128 v[206:209], v142 offset:20480
	ds_read_b128 v[210:213], v142 offset:21504
	ds_read_b128 v[214:217], v142 offset:22528
	ds_read_b128 v[218:221], v142 offset:23552
	global_load_lds_dwordx4 v[186:187], off
	s_add_i32 m0, s48, 0x2000
	s_add_u32 s80, s46, 0x100000
	v_lshl_add_u64 v[222:223], s[46:47], 0, v[134:135]
	s_addc_u32 s81, s47, 0
	s_add_i32 s48, s49, s60
	global_load_lds_dwordx4 v[222:223], off
	v_lshl_add_u64 v[224:225], s[80:81], 0, v[176:177]
	s_mov_b32 m0, s48
	v_lshl_add_u64 v[234:235], s[68:69], 0, v[132:133]
	global_load_lds_dwordx4 v[224:225], off
	v_lshl_add_u64 v[224:225], s[80:81], 0, v[134:135]
	s_add_i32 m0, s48, 0x2000
	s_nop 0
	global_load_lds_dwordx4 v[224:225], off
	v_lshl_add_u64 v[224:225], s[68:69], 0, v[130:131]
	s_mov_b32 m0, s61
	s_nop 0
	global_load_lds_dwordx4 v[224:225], off
	s_mov_b32 m0, s62
	s_nop 0
	global_load_lds_dwordx4 v[234:235], off
	s_waitcnt vmcnt(8)
	s_waitcnt lgkmcnt(0)
	s_barrier
	s_setprio 1
	s_waitcnt lgkmcnt(0)
	v_mfma_f32_16x16x32_bf16 v[60:63], v[144:147], v[190:193], v[60:63]
	v_mfma_f32_16x16x32_bf16 v[56:59], v[152:155], v[190:193], v[56:59]
	v_mfma_f32_16x16x32_bf16 v[52:55], v[144:147], v[198:201], v[52:55]
	v_mfma_f32_16x16x32_bf16 v[44:47], v[152:155], v[198:201], v[44:47]
	v_mfma_f32_16x16x32_bf16 v[36:39], v[144:147], v[206:209], v[36:39]
	v_mfma_f32_16x16x32_bf16 v[28:31], v[152:155], v[206:209], v[28:31]
	v_mfma_f32_16x16x32_bf16 v[20:23], v[144:147], v[214:217], v[20:23]
	v_mfma_f32_16x16x32_bf16 v[12:15], v[152:155], v[214:217], v[12:15]
	v_mfma_f32_16x16x32_bf16 v[60:63], v[148:151], v[194:197], v[60:63]
	v_mfma_f32_16x16x32_bf16 v[56:59], v[156:159], v[194:197], v[56:59]
	v_mfma_f32_16x16x32_bf16 v[52:55], v[148:151], v[202:205], v[52:55]
	v_mfma_f32_16x16x32_bf16 v[44:47], v[156:159], v[202:205], v[44:47]
	v_mfma_f32_16x16x32_bf16 v[36:39], v[148:151], v[210:213], v[36:39]
	v_mfma_f32_16x16x32_bf16 v[28:31], v[156:159], v[210:213], v[28:31]
	v_mfma_f32_16x16x32_bf16 v[20:23], v[148:151], v[218:221], v[20:23]
	v_mfma_f32_16x16x32_bf16 v[12:15], v[156:159], v[218:221], v[12:15]
	s_setprio 0
	s_setprio 1
	v_mfma_f32_16x16x32_bf16 v[48:51], v[160:163], v[190:193], v[48:51]
	v_mfma_f32_16x16x32_bf16 v[40:43], v[168:171], v[190:193], v[40:43]
	v_mfma_f32_16x16x32_bf16 v[32:35], v[160:163], v[198:201], v[32:35]
	v_mfma_f32_16x16x32_bf16 v[24:27], v[168:171], v[198:201], v[24:27]
	v_mfma_f32_16x16x32_bf16 v[16:19], v[160:163], v[206:209], v[16:19]
	v_mfma_f32_16x16x32_bf16 v[8:11], v[168:171], v[206:209], v[8:11]
	v_mfma_f32_16x16x32_bf16 v[4:7], v[160:163], v[214:217], v[4:7]
	v_mfma_f32_16x16x32_bf16 v[0:3], v[168:171], v[214:217], v[0:3]
	v_mfma_f32_16x16x32_bf16 v[48:51], v[164:167], v[194:197], v[48:51]
	v_mfma_f32_16x16x32_bf16 v[40:43], v[172:175], v[194:197], v[40:43]
	v_mfma_f32_16x16x32_bf16 v[32:35], v[164:167], v[202:205], v[32:35]
	v_mfma_f32_16x16x32_bf16 v[24:27], v[172:175], v[202:205], v[24:27]
	v_mfma_f32_16x16x32_bf16 v[16:19], v[164:167], v[210:213], v[16:19]
	v_mfma_f32_16x16x32_bf16 v[8:11], v[172:175], v[210:213], v[8:11]
	v_mfma_f32_16x16x32_bf16 v[4:7], v[164:167], v[218:221], v[4:7]
	v_mfma_f32_16x16x32_bf16 v[0:3], v[172:175], v[218:221], v[0:3]
	s_setprio 0
	s_barrier
	s_add_i32 s48, 0, 0x18000
	v_add_u32_e32 v143, s48, v141
	s_add_i32 s49, 0, 0x1c000
	ds_read_b128 v[144:147], v143
	ds_read_b128 v[148:151], v143 offset:1024
	ds_read_b128 v[152:155], v143 offset:2048
	ds_read_b128 v[156:159], v143 offset:3072
	v_add_u32_e32 v143, s49, v141
	ds_read_b128 v[160:163], v143
	ds_read_b128 v[164:167], v143 offset:1024
	ds_read_b128 v[168:171], v143 offset:2048
	ds_read_b128 v[172:175], v143 offset:3072
	s_add_u32 s68, s68, 0x100000
	s_addc_u32 s69, s69, 0
	s_mov_b32 m0, s63
	v_lshl_add_u64 v[236:237], s[68:69], 0, v[130:131]
	ds_read_b128 v[190:193], v142 offset:32768
	ds_read_b128 v[194:197], v142 offset:33792
	ds_read_b128 v[198:201], v142 offset:34816
	ds_read_b128 v[202:205], v142 offset:35840
	ds_read_b128 v[206:209], v142 offset:36864
	ds_read_b128 v[210:213], v142 offset:37888
	ds_read_b128 v[214:217], v142 offset:38912
	ds_read_b128 v[218:221], v142 offset:39936
	global_load_lds_dwordx4 v[236:237], off
	v_lshl_add_u64 v[236:237], s[68:69], 0, v[132:133]
	s_mov_b32 m0, s70
	s_nop 0
	global_load_lds_dwordx4 v[236:237], off
	s_waitcnt vmcnt(8)
	s_waitcnt lgkmcnt(0)
	s_barrier
	s_setprio 1
	s_waitcnt lgkmcnt(0)
	v_mfma_f32_16x16x32_bf16 v[124:127], v[144:147], v[190:193], v[124:127]
	v_mfma_f32_16x16x32_bf16 v[120:123], v[152:155], v[190:193], v[120:123]
	v_mfma_f32_16x16x32_bf16 v[108:111], v[144:147], v[198:201], v[108:111]
	v_mfma_f32_16x16x32_bf16 v[104:107], v[152:155], v[198:201], v[104:107]
	v_mfma_f32_16x16x32_bf16 v[100:103], v[144:147], v[206:209], v[100:103]
	v_mfma_f32_16x16x32_bf16 v[92:95], v[152:155], v[206:209], v[92:95]
	v_mfma_f32_16x16x32_bf16 v[84:87], v[144:147], v[214:217], v[84:87]
	v_mfma_f32_16x16x32_bf16 v[76:79], v[152:155], v[214:217], v[76:79]
	v_mfma_f32_16x16x32_bf16 v[124:127], v[148:151], v[194:197], v[124:127]
	v_mfma_f32_16x16x32_bf16 v[120:123], v[156:159], v[194:197], v[120:123]
	v_mfma_f32_16x16x32_bf16 v[108:111], v[148:151], v[202:205], v[108:111]
	v_mfma_f32_16x16x32_bf16 v[104:107], v[156:159], v[202:205], v[104:107]
	v_mfma_f32_16x16x32_bf16 v[100:103], v[148:151], v[210:213], v[100:103]
	v_mfma_f32_16x16x32_bf16 v[92:95], v[156:159], v[210:213], v[92:95]
	v_mfma_f32_16x16x32_bf16 v[84:87], v[148:151], v[218:221], v[84:87]
	v_mfma_f32_16x16x32_bf16 v[76:79], v[156:159], v[218:221], v[76:79]
	s_setprio 0
	s_setprio 1
	v_mfma_f32_16x16x32_bf16 v[116:119], v[160:163], v[190:193], v[116:119]
	v_mfma_f32_16x16x32_bf16 v[112:115], v[168:171], v[190:193], v[112:115]
	v_mfma_f32_16x16x32_bf16 v[96:99], v[160:163], v[198:201], v[96:99]
	v_mfma_f32_16x16x32_bf16 v[88:91], v[168:171], v[198:201], v[88:91]
	v_mfma_f32_16x16x32_bf16 v[80:83], v[160:163], v[206:209], v[80:83]
	v_mfma_f32_16x16x32_bf16 v[72:75], v[168:171], v[206:209], v[72:75]
	v_mfma_f32_16x16x32_bf16 v[68:71], v[160:163], v[214:217], v[68:71]
	v_mfma_f32_16x16x32_bf16 v[64:67], v[168:171], v[214:217], v[64:67]
	v_mfma_f32_16x16x32_bf16 v[116:119], v[164:167], v[194:197], v[116:119]
	v_mfma_f32_16x16x32_bf16 v[112:115], v[172:175], v[194:197], v[112:115]
	v_mfma_f32_16x16x32_bf16 v[96:99], v[164:167], v[202:205], v[96:99]
	v_mfma_f32_16x16x32_bf16 v[88:91], v[172:175], v[202:205], v[88:91]
	v_mfma_f32_16x16x32_bf16 v[80:83], v[164:167], v[210:213], v[80:83]
	v_mfma_f32_16x16x32_bf16 v[72:75], v[172:175], v[210:213], v[72:75]
	v_mfma_f32_16x16x32_bf16 v[68:71], v[164:167], v[218:221], v[68:71]
	v_mfma_f32_16x16x32_bf16 v[64:67], v[172:175], v[218:221], v[64:67]
	s_setprio 0
	s_barrier
	s_add_i32 s48, s48, s60
	v_lshl_add_u64 v[186:187], v[186:187], 0, s[100:101]
	s_mov_b32 m0, s48
	ds_read_b128 v[190:193], v142 offset:49152
	ds_read_b128 v[194:197], v142 offset:50176
	ds_read_b128 v[198:201], v142 offset:51200
	ds_read_b128 v[202:205], v142 offset:52224
	ds_read_b128 v[206:209], v142 offset:53248
	ds_read_b128 v[210:213], v142 offset:54272
	ds_read_b128 v[214:217], v142 offset:55296
	ds_read_b128 v[218:221], v142 offset:56320
	global_load_lds_dwordx4 v[186:187], off
	s_add_i32 m0, s48, 0x2000
	s_add_u32 s46, s46, 0x100100
	v_lshl_add_u64 v[186:187], v[222:223], 0, s[100:101]
	s_addc_u32 s47, s47, 0
	s_add_i32 s48, s49, s60
	global_load_lds_dwordx4 v[186:187], off
	v_lshl_add_u64 v[186:187], s[46:47], 0, v[176:177]
	s_mov_b32 m0, s48
	s_nop 0
	global_load_lds_dwordx4 v[186:187], off
	v_lshl_add_u64 v[186:187], s[46:47], 0, v[134:135]
	s_add_i32 m0, s48, 0x2000
	s_nop 0
	global_load_lds_dwordx4 v[186:187], off
	v_lshl_add_u64 v[186:187], v[224:225], 0, s[100:101]
	s_mov_b32 m0, s72
	s_nop 0
	global_load_lds_dwordx4 v[186:187], off
	v_lshl_add_u64 v[186:187], v[234:235], 0, s[100:101]
	s_mov_b32 m0, s73
	s_nop 0
	global_load_lds_dwordx4 v[186:187], off
	s_waitcnt vmcnt(8)
	s_waitcnt lgkmcnt(0)
	s_barrier
	s_setprio 1
	s_waitcnt lgkmcnt(0)
	v_mfma_f32_16x16x32_bf16 v[60:63], v[144:147], v[190:193], v[60:63]
	v_mfma_f32_16x16x32_bf16 v[56:59], v[152:155], v[190:193], v[56:59]
	v_mfma_f32_16x16x32_bf16 v[52:55], v[144:147], v[198:201], v[52:55]
	v_mfma_f32_16x16x32_bf16 v[44:47], v[152:155], v[198:201], v[44:47]
	v_mfma_f32_16x16x32_bf16 v[36:39], v[144:147], v[206:209], v[36:39]
	v_mfma_f32_16x16x32_bf16 v[28:31], v[152:155], v[206:209], v[28:31]
	v_mfma_f32_16x16x32_bf16 v[20:23], v[144:147], v[214:217], v[20:23]
	v_mfma_f32_16x16x32_bf16 v[12:15], v[152:155], v[214:217], v[12:15]
	v_mfma_f32_16x16x32_bf16 v[60:63], v[148:151], v[194:197], v[60:63]
	v_mfma_f32_16x16x32_bf16 v[56:59], v[156:159], v[194:197], v[56:59]
	v_mfma_f32_16x16x32_bf16 v[52:55], v[148:151], v[202:205], v[52:55]
	v_mfma_f32_16x16x32_bf16 v[44:47], v[156:159], v[202:205], v[44:47]
	v_mfma_f32_16x16x32_bf16 v[36:39], v[148:151], v[210:213], v[36:39]
	v_mfma_f32_16x16x32_bf16 v[28:31], v[156:159], v[210:213], v[28:31]
	v_mfma_f32_16x16x32_bf16 v[20:23], v[148:151], v[218:221], v[20:23]
	v_mfma_f32_16x16x32_bf16 v[12:15], v[156:159], v[218:221], v[12:15]
	s_setprio 0
	s_setprio 1
	v_mfma_f32_16x16x32_bf16 v[48:51], v[160:163], v[190:193], v[48:51]
	v_mfma_f32_16x16x32_bf16 v[40:43], v[168:171], v[190:193], v[40:43]
	v_mfma_f32_16x16x32_bf16 v[32:35], v[160:163], v[198:201], v[32:35]
	v_mfma_f32_16x16x32_bf16 v[24:27], v[168:171], v[198:201], v[24:27]
	v_mfma_f32_16x16x32_bf16 v[16:19], v[160:163], v[206:209], v[16:19]
	v_mfma_f32_16x16x32_bf16 v[8:11], v[168:171], v[206:209], v[8:11]
	v_mfma_f32_16x16x32_bf16 v[4:7], v[160:163], v[214:217], v[4:7]
	v_mfma_f32_16x16x32_bf16 v[0:3], v[168:171], v[214:217], v[0:3]
	v_mfma_f32_16x16x32_bf16 v[48:51], v[164:167], v[194:197], v[48:51]
	v_mfma_f32_16x16x32_bf16 v[40:43], v[172:175], v[194:197], v[40:43]
	v_mfma_f32_16x16x32_bf16 v[32:35], v[164:167], v[202:205], v[32:35]
	v_mfma_f32_16x16x32_bf16 v[24:27], v[172:175], v[202:205], v[24:27]
	v_mfma_f32_16x16x32_bf16 v[16:19], v[164:167], v[210:213], v[16:19]
	v_mfma_f32_16x16x32_bf16 v[8:11], v[172:175], v[210:213], v[8:11]
	v_mfma_f32_16x16x32_bf16 v[4:7], v[164:167], v[218:221], v[4:7]
	v_mfma_f32_16x16x32_bf16 v[0:3], v[172:175], v[218:221], v[0:3]
	s_setprio 0
	s_barrier
	s_add_i32 s78, s78, 2
	s_add_u32 s42, s42, 0x200
	s_addc_u32 s43, s43, 0
	s_cmp_gt_u32 s78, 29
	s_cbranch_scc0 .LBB0_607
	s_cmpk_lt_u32 s59, 0x100
	s_cbranch_scc0 .Ldfl_a
	s_barrier
.Ldfl_a:
	s_bitcmp1_b32 s42, 7
	s_cbranch_scc1 .Ldfl_epi
	s_cmpk_eq_u32 s58, 0x800
	s_cbranch_scc1 .Ldfl_xepi
	s_add_i32 s46, s77, 0xfffffe80
	s_lshl_b32 s46, s46, 18
	s_add_u32 s48, s94, s46
	s_addc_u32 s49, s95, 0
	s_add_u32 s48, s48, 0x11b00000
	s_addc_u32 s49, s49, 0
	v_lshrrev_b32_e32 v144, 6, v140
	v_and_b32_e32 v145, 63, v140
	v_lshlrev_b32_e32 v145, 4, v145
	v_lshl_add_u32 v144, v144, 15, v145
	global_store_dwordx4 v144, v[0:3], s[48:49] offset:0
	global_store_dwordx4 v144, v[4:7], s[48:49] offset:1024
	global_store_dwordx4 v144, v[8:11], s[48:49] offset:2048
	global_store_dwordx4 v144, v[12:15], s[48:49] offset:3072
	s_add_u32 s48, s48, 0x1000
	s_addc_u32 s49, s49, 0
	global_store_dwordx4 v144, v[16:19], s[48:49] offset:0
	global_store_dwordx4 v144, v[20:23], s[48:49] offset:1024
	global_store_dwordx4 v144, v[24:27], s[48:49] offset:2048
	global_store_dwordx4 v144, v[28:31], s[48:49] offset:3072
	s_add_u32 s48, s48, 0x1000
	s_addc_u32 s49, s49, 0
	global_store_dwordx4 v144, v[32:35], s[48:49] offset:0
	global_store_dwordx4 v144, v[36:39], s[48:49] offset:1024
	global_store_dwordx4 v144, v[40:43], s[48:49] offset:2048
	global_store_dwordx4 v144, v[44:47], s[48:49] offset:3072
	s_add_u32 s48, s48, 0x1000
	s_addc_u32 s49, s49, 0
	global_store_dwordx4 v144, v[48:51], s[48:49] offset:0
	global_store_dwordx4 v144, v[52:55], s[48:49] offset:1024
	global_store_dwordx4 v144, v[56:59], s[48:49] offset:2048
	global_store_dwordx4 v144, v[60:63], s[48:49] offset:3072
	s_add_u32 s48, s48, 0x1000
	s_addc_u32 s49, s49, 0
	global_store_dwordx4 v144, v[64:67], s[48:49] offset:0
	global_store_dwordx4 v144, v[68:71], s[48:49] offset:1024
	global_store_dwordx4 v144, v[72:75], s[48:49] offset:2048
	global_store_dwordx4 v144, v[76:79], s[48:49] offset:3072
	s_add_u32 s48, s48, 0x1000
	s_addc_u32 s49, s49, 0
	global_store_dwordx4 v144, v[80:83], s[48:49] offset:0
	global_store_dwordx4 v144, v[84:87], s[48:49] offset:1024
	global_store_dwordx4 v144, v[88:91], s[48:49] offset:2048
	global_store_dwordx4 v144, v[92:95], s[48:49] offset:3072
	s_add_u32 s48, s48, 0x1000
	s_addc_u32 s49, s49, 0
	global_store_dwordx4 v144, v[96:99], s[48:49] offset:0
	global_store_dwordx4 v144, v[100:103], s[48:49] offset:1024
	global_store_dwordx4 v144, v[104:107], s[48:49] offset:2048
	global_store_dwordx4 v144, v[108:111], s[48:49] offset:3072
	s_add_u32 s48, s48, 0x1000
	s_addc_u32 s49, s49, 0
	global_store_dwordx4 v144, v[112:115], s[48:49] offset:0
	global_store_dwordx4 v144, v[116:119], s[48:49] offset:1024
	global_store_dwordx4 v144, v[120:123], s[48:49] offset:2048
	global_store_dwordx4 v144, v[124:127], s[48:49] offset:3072
	s_cmpk_lt_u32 s59, 0x100
	s_cbranch_scc1 .Ldfl_b
	s_barrier
.Ldfl_b:
	s_mov_b32 s78, -2
	s_mov_b64 s[42:43], 0x2c00180
	s_branch .LBB0_607
.Ldfl_epi:
	s_add_i32 s46, s77, 0xfffffe80
	s_lshl_b32 s46, s46, 18
	s_add_u32 s48, s94, s46
	s_addc_u32 s49, s95, 0
	s_add_u32 s48, s48, 0x11b00000
	s_addc_u32 s49, s49, 0
	v_lshrrev_b32_e32 v144, 6, v140
	v_and_b32_e32 v145, 63, v140
	v_lshlrev_b32_e32 v145, 4, v145
	v_lshl_add_u32 v144, v144, 15, v145
	s_lshl_b32 s46, s52, 11
	s_lshl_b32 s47, s3, 2
	s_add_i32 s46, s46, s47
	s_add_i32 s46, s46, 0x34000
	s_add_u32 s46, s94, s46
	s_addc_u32 s47, s95, 0
	v_or_b32_e32 v145, s71, v129
	v_lshlrev_b32_e32 v146, 2, v145
	global_load_dwordx4 v[152:155], v146, s[46:47] offset:0
	global_load_dwordx4 v[156:159], v146, s[46:47] offset:16
	global_load_dwordx4 v[160:163], v146, s[46:47] offset:512
	global_load_dwordx4 v[164:167], v146, s[46:47] offset:528
	v_and_b32_e32 v147, 1, v140
	v_lshlrev_b32_e32 v147, 31, v147
	v_lshlrev_b32_e32 v148, 11, v128
	v_lshl_add_u32 v148, v145, 1, v148
	s_lshl_b32 s34, s52, 12
	s_addk_i32 s34, 0x4000
	s_add_i32 s36, s34, 0xf81
	s_sub_i32 s36, s36, s58
	s_or_b32 s34, s34, s58
	s_lshl_b32 s34, s34, 11
	s_lshl_b32 s36, s36, 11
	s_lshl_b32 s0, s3, 1
	s_add_i32 s0, s0, 0x4b00400
	s_add_i32 s34, s34, s0
	s_add_i32 s36, s36, s0
	s_add_u32 s34, s94, s34
	s_addc_u32 s35, s95, 0
	s_add_u32 s36, s94, s36
	s_addc_u32 s37, s95, 0
	v_sub_u32_e32 v149, 127, v128
	v_lshlrev_b32_e32 v149, 11, v149
	v_lshl_add_u32 v149, v145, 1, v149
	v_or_b32_e32 v150, s58, v128
	v_cmp_ne_u32_e32 vcc, 0, v150
	s_mov_b64 s[68:69], vcc
	s_add_u32 s46, s48, 0x7000
	s_addc_u32 s47, s49, 0
	global_load_dwordx4 v[190:193], v144, s[46:47] offset:3072 sc1
	global_load_dwordx4 v[194:197], v144, s[46:47] offset:2048 sc1
	global_load_dwordx4 v[198:201], v144, s[46:47] offset:1024 sc1
	global_load_dwordx4 v[202:205], v144, s[46:47] offset:0 sc1
	s_add_u32 s46, s48, 0x6000
	s_addc_u32 s47, s49, 0
	global_load_dwordx4 v[206:209], v144, s[46:47] offset:3072 sc1
	global_load_dwordx4 v[210:213], v144, s[46:47] offset:2048 sc1
	global_load_dwordx4 v[214:217], v144, s[46:47] offset:0 sc1
	s_add_u32 s46, s48, 0x5000
	s_addc_u32 s47, s49, 0
	global_load_dwordx4 v[218:221], v144, s[46:47] offset:2048 sc1
	s_add_u32 s46, s48, 0x6000
	s_addc_u32 s47, s49, 0
	global_load_dwordx4 v[168:171], v144, s[46:47] offset:1024 sc1
	s_add_u32 s46, s48, 0x5000
	s_addc_u32 s47, s49, 0
	global_load_dwordx4 v[172:175], v144, s[46:47] offset:3072 sc1
	global_load_dwordx4 v[222:225], v144, s[46:47] offset:0 sc1
	s_add_u32 s46, s48, 0x4000
	s_addc_u32 s47, s49, 0
	global_load_dwordx4 v[234:237], v144, s[46:47] offset:2048 sc1
	s_waitcnt vmcnt(10)
	v_xor_b32_e32 v152, v147, v152
	v_xor_b32_e32 v153, v147, v153
	v_xor_b32_e32 v154, v147, v154
	v_xor_b32_e32 v155, v147, v155
	v_xor_b32_e32 v156, v147, v156
	v_xor_b32_e32 v157, v147, v157
	v_xor_b32_e32 v158, v147, v158
	v_xor_b32_e32 v159, v147, v159
	v_xor_b32_e32 v160, v147, v160
	v_xor_b32_e32 v161, v147, v161
	v_xor_b32_e32 v162, v147, v162
	v_xor_b32_e32 v163, v147, v163
	v_xor_b32_e32 v164, v147, v164
	v_xor_b32_e32 v165, v147, v165
	v_xor_b32_e32 v166, v147, v166
	v_xor_b32_e32 v167, v147, v167
	s_mov_b64 s[40:41], s[34:35]
	s_mov_b64 s[42:43], s[36:37]
	v_fma_f32 v190, v190, 2.0, -v124
	v_fma_f32 v191, v191, 2.0, -v125
	v_fma_f32 v192, v192, 2.0, -v126
	v_fma_f32 v193, v193, 2.0, -v127
	v_fma_f32 v194, v194, 2.0, -v120
	v_fma_f32 v195, v195, 2.0, -v121
	v_fma_f32 v196, v196, 2.0, -v122
	v_fma_f32 v197, v197, 2.0, -v123
	v_add_f32_e32 v190, v190, v152
	v_add_f32_e32 v191, v191, v153
	v_add_f32_e32 v192, v192, v154
	v_add_f32_e32 v193, v193, v155
	v_add_f32_e32 v194, v194, v156
	v_add_f32_e32 v195, v195, v157
	v_add_f32_e32 v196, v196, v158
	v_add_f32_e32 v197, v197, v159
	v_mul_f32_e32 v190, s56, v190
	v_mul_f32_e32 v191, s56, v191
	v_mul_f32_e32 v192, s56, v192
	v_mul_f32_e32 v193, s56, v193
	v_mul_f32_e32 v194, s56, v194
	v_mul_f32_e32 v195, s56, v195
	v_mul_f32_e32 v196, s56, v196
	v_mul_f32_e32 v197, s56, v197
	v_cvt_pk_bf16_f32 v190, v190, v191
	v_cvt_pk_bf16_f32 v191, v192, v193
	v_cvt_pk_bf16_f32 v192, v194, v195
	v_cvt_pk_bf16_f32 v193, v196, v197
	s_and_saveexec_b64 s[80:81], s[68:69]
	global_store_dwordx4 v149, v[190:193], s[42:43] offset:0
	s_mov_b64 exec, s[80:81]
	v_add_f32_e32 v124, v124, v152
	v_add_f32_e32 v125, v125, v153
	v_add_f32_e32 v126, v126, v154
	v_add_f32_e32 v127, v127, v155
	v_add_f32_e32 v120, v120, v156
	v_add_f32_e32 v121, v121, v157
	v_add_f32_e32 v122, v122, v158
	v_add_f32_e32 v123, v123, v159
	v_mul_f32_e32 v124, s56, v124
	v_mul_f32_e32 v125, s56, v125
	v_mul_f32_e32 v126, s56, v126
	v_mul_f32_e32 v127, s56, v127
	v_mul_f32_e32 v120, s56, v120
	v_mul_f32_e32 v121, s56, v121
	v_mul_f32_e32 v122, s56, v122
	v_mul_f32_e32 v123, s56, v123
	v_cvt_pk_bf16_f32 v124, v124, v125
	v_cvt_pk_bf16_f32 v125, v126, v127
	v_cvt_pk_bf16_f32 v126, v120, v121
	v_cvt_pk_bf16_f32 v127, v122, v123
	global_store_dwordx4 v148, v[124:127], s[40:41] offset:0
	s_add_u32 s46, s48, 0x5000
	s_addc_u32 s47, s49, 0
	global_load_dwordx4 v[190:193], v144, s[46:47] offset:1024 sc1
	s_add_u32 s46, s48, 0x4000
	s_addc_u32 s47, s49, 0
	global_load_dwordx4 v[194:197], v144, s[46:47] offset:3072 sc1
	s_waitcnt vmcnt(12)
	v_fma_f32 v198, v198, 2.0, -v116
	v_fma_f32 v199, v199, 2.0, -v117
	v_fma_f32 v200, v200, 2.0, -v118
	v_fma_f32 v201, v201, 2.0, -v119
	v_fma_f32 v202, v202, 2.0, -v112
	v_fma_f32 v203, v203, 2.0, -v113
	v_fma_f32 v204, v204, 2.0, -v114
	v_fma_f32 v205, v205, 2.0, -v115
	v_add_f32_e32 v198, v198, v160
	v_add_f32_e32 v199, v199, v161
	v_add_f32_e32 v200, v200, v162
	v_add_f32_e32 v201, v201, v163
	v_add_f32_e32 v202, v202, v164
	v_add_f32_e32 v203, v203, v165
	v_add_f32_e32 v204, v204, v166
	v_add_f32_e32 v205, v205, v167
	v_mul_f32_e32 v198, s56, v198
	v_mul_f32_e32 v199, s56, v199
	v_mul_f32_e32 v200, s56, v200
	v_mul_f32_e32 v201, s56, v201
	v_mul_f32_e32 v202, s56, v202
	v_mul_f32_e32 v203, s56, v203
	v_mul_f32_e32 v204, s56, v204
	v_mul_f32_e32 v205, s56, v205
	v_cvt_pk_bf16_f32 v198, v198, v199
	v_cvt_pk_bf16_f32 v199, v200, v201
	v_cvt_pk_bf16_f32 v200, v202, v203
	v_cvt_pk_bf16_f32 v201, v204, v205
	s_and_saveexec_b64 s[80:81], s[68:69]
	global_store_dwordx4 v149, v[198:201], s[42:43] offset:256
	s_mov_b64 exec, s[80:81]
	v_add_f32_e32 v116, v116, v160
	v_add_f32_e32 v117, v117, v161
	v_add_f32_e32 v118, v118, v162
	v_add_f32_e32 v119, v119, v163
	v_add_f32_e32 v112, v112, v164
	v_add_f32_e32 v113, v113, v165
	v_add_f32_e32 v114, v114, v166
	v_add_f32_e32 v115, v115, v167
	v_mul_f32_e32 v116, s56, v116
	v_mul_f32_e32 v117, s56, v117
	v_mul_f32_e32 v118, s56, v118
	v_mul_f32_e32 v119, s56, v119
	v_mul_f32_e32 v112, s56, v112
	v_mul_f32_e32 v113, s56, v113
	v_mul_f32_e32 v114, s56, v114
	v_mul_f32_e32 v115, s56, v115
	v_cvt_pk_bf16_f32 v116, v116, v117
	v_cvt_pk_bf16_f32 v117, v118, v119
	v_cvt_pk_bf16_f32 v118, v112, v113
	v_cvt_pk_bf16_f32 v119, v114, v115
	global_store_dwordx4 v148, v[116:119], s[40:41] offset:256
	global_load_dwordx4 v[124:127], v144, s[46:47] offset:1024 sc1
	global_load_dwordx4 v[120:123], v144, s[46:47] offset:0 sc1
	s_waitcnt vmcnt(14)
	s_add_u32 s40, s34, 0x8000
	s_addc_u32 s41, s35, 0
	s_sub_u32 s42, s36, 0x8000
	s_subb_u32 s43, s37, 0
	v_fma_f32 v206, v206, 2.0, -v108
	v_fma_f32 v207, v207, 2.0, -v109
	v_fma_f32 v208, v208, 2.0, -v110
	v_fma_f32 v209, v209, 2.0, -v111
	v_fma_f32 v210, v210, 2.0, -v104
	v_fma_f32 v211, v211, 2.0, -v105
	v_fma_f32 v212, v212, 2.0, -v106
	v_fma_f32 v213, v213, 2.0, -v107
	v_add_f32_e32 v206, v206, v152
	v_add_f32_e32 v207, v207, v153
	v_add_f32_e32 v208, v208, v154
	v_add_f32_e32 v209, v209, v155
	v_add_f32_e32 v210, v210, v156
	v_add_f32_e32 v211, v211, v157
	v_add_f32_e32 v212, v212, v158
	v_add_f32_e32 v213, v213, v159
	v_mul_f32_e32 v206, s56, v206
	v_mul_f32_e32 v207, s56, v207
	v_mul_f32_e32 v208, s56, v208
	v_mul_f32_e32 v209, s56, v209
	v_mul_f32_e32 v210, s56, v210
	v_mul_f32_e32 v211, s56, v211
	v_mul_f32_e32 v212, s56, v212
	v_mul_f32_e32 v213, s56, v213
	v_cvt_pk_bf16_f32 v206, v206, v207
	v_cvt_pk_bf16_f32 v207, v208, v209
	v_cvt_pk_bf16_f32 v208, v210, v211
	v_cvt_pk_bf16_f32 v209, v212, v213
	global_store_dwordx4 v149, v[206:209], s[42:43] offset:0
	v_add_f32_e32 v108, v108, v152
	v_add_f32_e32 v109, v109, v153
	v_add_f32_e32 v110, v110, v154
	v_add_f32_e32 v111, v111, v155
	v_add_f32_e32 v104, v104, v156
	v_add_f32_e32 v105, v105, v157
	v_add_f32_e32 v106, v106, v158
	v_add_f32_e32 v107, v107, v159
	v_mul_f32_e32 v108, s56, v108
	v_mul_f32_e32 v109, s56, v109
	v_mul_f32_e32 v110, s56, v110
	v_mul_f32_e32 v111, s56, v111
	v_mul_f32_e32 v104, s56, v104
	v_mul_f32_e32 v105, s56, v105
	v_mul_f32_e32 v106, s56, v106
	v_mul_f32_e32 v107, s56, v107
	v_cvt_pk_bf16_f32 v108, v108, v109
	v_cvt_pk_bf16_f32 v109, v110, v111
	v_cvt_pk_bf16_f32 v110, v104, v105
	v_cvt_pk_bf16_f32 v111, v106, v107
	global_store_dwordx4 v148, v[108:111], s[40:41] offset:0
	s_add_u32 s46, s48, 0x3000
	s_addc_u32 s47, s49, 0
	global_load_dwordx4 v[198:201], v144, s[46:47] offset:3072 sc1
	global_load_dwordx4 v[202:205], v144, s[46:47] offset:2048 sc1
	s_waitcnt vmcnt(16)
	v_fma_f32 v214, v214, 2.0, -v96
	v_fma_f32 v215, v215, 2.0, -v97
	v_fma_f32 v216, v216, 2.0, -v98
	v_fma_f32 v217, v217, 2.0, -v99
	v_fma_f32 v218, v218, 2.0, -v88
	v_fma_f32 v219, v219, 2.0, -v89
	v_fma_f32 v220, v220, 2.0, -v90
	v_fma_f32 v221, v221, 2.0, -v91
	v_add_f32_e32 v214, v214, v160
	v_add_f32_e32 v215, v215, v161
	v_add_f32_e32 v216, v216, v162
	v_add_f32_e32 v217, v217, v163
	v_add_f32_e32 v218, v218, v164
	v_add_f32_e32 v219, v219, v165
	v_add_f32_e32 v220, v220, v166
	v_add_f32_e32 v221, v221, v167
	v_mul_f32_e32 v214, s56, v214
	v_mul_f32_e32 v215, s56, v215
	v_mul_f32_e32 v216, s56, v216
	v_mul_f32_e32 v217, s56, v217
	v_mul_f32_e32 v218, s56, v218
	v_mul_f32_e32 v219, s56, v219
	v_mul_f32_e32 v220, s56, v220
	v_mul_f32_e32 v221, s56, v221
	v_cvt_pk_bf16_f32 v214, v214, v215
	v_cvt_pk_bf16_f32 v215, v216, v217
	v_cvt_pk_bf16_f32 v216, v218, v219
	v_cvt_pk_bf16_f32 v217, v220, v221
	global_store_dwordx4 v149, v[214:217], s[42:43] offset:256
	v_add_f32_e32 v96, v96, v160
	v_add_f32_e32 v97, v97, v161
	v_add_f32_e32 v98, v98, v162
	v_add_f32_e32 v99, v99, v163
	v_add_f32_e32 v88, v88, v164
	v_add_f32_e32 v89, v89, v165
	v_add_f32_e32 v90, v90, v166
	v_add_f32_e32 v91, v91, v167
	v_mul_f32_e32 v96, s56, v96
	v_mul_f32_e32 v97, s56, v97
	v_mul_f32_e32 v98, s56, v98
	v_mul_f32_e32 v99, s56, v99
	v_mul_f32_e32 v88, s56, v88
	v_mul_f32_e32 v89, s56, v89
	v_mul_f32_e32 v90, s56, v90
	v_mul_f32_e32 v91, s56, v91
	v_cvt_pk_bf16_f32 v96, v96, v97
	v_cvt_pk_bf16_f32 v97, v98, v99
	v_cvt_pk_bf16_f32 v98, v88, v89
	v_cvt_pk_bf16_f32 v99, v90, v91
	global_store_dwordx4 v148, v[96:99], s[40:41] offset:256
	global_load_dwordx4 v[116:119], v144, s[46:47] offset:0 sc1
	s_add_u32 s46, s48, 0x2000
	s_addc_u32 s47, s49, 0
	global_load_dwordx4 v[112:115], v144, s[46:47] offset:2048 sc1
	s_waitcnt vmcnt(18)
	s_add_u32 s40, s34, 0x10000
	s_addc_u32 s41, s35, 0
	s_sub_u32 s42, s36, 0x10000
	s_subb_u32 s43, s37, 0
	v_fma_f32 v168, v168, 2.0, -v100
	v_fma_f32 v169, v169, 2.0, -v101
	v_fma_f32 v170, v170, 2.0, -v102
	v_fma_f32 v171, v171, 2.0, -v103
	v_fma_f32 v172, v172, 2.0, -v92
	v_fma_f32 v173, v173, 2.0, -v93
	v_fma_f32 v174, v174, 2.0, -v94
	v_fma_f32 v175, v175, 2.0, -v95
	v_add_f32_e32 v168, v168, v152
	v_add_f32_e32 v169, v169, v153
	v_add_f32_e32 v170, v170, v154
	v_add_f32_e32 v171, v171, v155
	v_add_f32_e32 v172, v172, v156
	v_add_f32_e32 v173, v173, v157
	v_add_f32_e32 v174, v174, v158
	v_add_f32_e32 v175, v175, v159
	v_mul_f32_e32 v168, s56, v168
	v_mul_f32_e32 v169, s56, v169
	v_mul_f32_e32 v170, s56, v170
	v_mul_f32_e32 v171, s56, v171
	v_mul_f32_e32 v172, s56, v172
	v_mul_f32_e32 v173, s56, v173
	v_mul_f32_e32 v174, s56, v174
	v_mul_f32_e32 v175, s56, v175
	v_cvt_pk_bf16_f32 v168, v168, v169
	v_cvt_pk_bf16_f32 v169, v170, v171
	v_cvt_pk_bf16_f32 v170, v172, v173
	v_cvt_pk_bf16_f32 v171, v174, v175
	global_store_dwordx4 v149, v[168:171], s[42:43] offset:0
	v_add_f32_e32 v100, v100, v152
	v_add_f32_e32 v101, v101, v153
	v_add_f32_e32 v102, v102, v154
	v_add_f32_e32 v103, v103, v155
	v_add_f32_e32 v92, v92, v156
	v_add_f32_e32 v93, v93, v157
	v_add_f32_e32 v94, v94, v158
	v_add_f32_e32 v95, v95, v159
	v_mul_f32_e32 v100, s56, v100
	v_mul_f32_e32 v101, s56, v101
	v_mul_f32_e32 v102, s56, v102
	v_mul_f32_e32 v103, s56, v103
	v_mul_f32_e32 v92, s56, v92
	v_mul_f32_e32 v93, s56, v93
	v_mul_f32_e32 v94, s56, v94
	v_mul_f32_e32 v95, s56, v95
	v_cvt_pk_bf16_f32 v100, v100, v101
	v_cvt_pk_bf16_f32 v101, v102, v103
	v_cvt_pk_bf16_f32 v102, v92, v93
	v_cvt_pk_bf16_f32 v103, v94, v95
	global_store_dwordx4 v148, v[100:103], s[40:41] offset:0
	s_add_u32 s46, s48, 0x3000
	s_addc_u32 s47, s49, 0
	global_load_dwordx4 v[206:209], v144, s[46:47] offset:1024 sc1
	s_add_u32 s46, s48, 0x2000
	s_addc_u32 s47, s49, 0
	global_load_dwordx4 v[210:213], v144, s[46:47] offset:3072 sc1
	s_waitcnt vmcnt(20)
	v_fma_f32 v222, v222, 2.0, -v80
	v_fma_f32 v223, v223, 2.0, -v81
	v_fma_f32 v224, v224, 2.0, -v82
	v_fma_f32 v225, v225, 2.0, -v83
	v_fma_f32 v234, v234, 2.0, -v72
	v_fma_f32 v235, v235, 2.0, -v73
	v_fma_f32 v236, v236, 2.0, -v74
	v_fma_f32 v237, v237, 2.0, -v75
	v_add_f32_e32 v222, v222, v160
	v_add_f32_e32 v223, v223, v161
	v_add_f32_e32 v224, v224, v162
	v_add_f32_e32 v225, v225, v163
	v_add_f32_e32 v234, v234, v164
	v_add_f32_e32 v235, v235, v165
	v_add_f32_e32 v236, v236, v166
	v_add_f32_e32 v237, v237, v167
	v_mul_f32_e32 v222, s56, v222
	v_mul_f32_e32 v223, s56, v223
	v_mul_f32_e32 v224, s56, v224
	v_mul_f32_e32 v225, s56, v225
	v_mul_f32_e32 v234, s56, v234
	v_mul_f32_e32 v235, s56, v235
	v_mul_f32_e32 v236, s56, v236
	v_mul_f32_e32 v237, s56, v237
	v_cvt_pk_bf16_f32 v222, v222, v223
	v_cvt_pk_bf16_f32 v223, v224, v225
	v_cvt_pk_bf16_f32 v224, v234, v235
	v_cvt_pk_bf16_f32 v225, v236, v237
	global_store_dwordx4 v149, v[222:225], s[42:43] offset:256
	v_add_f32_e32 v80, v80, v160
	v_add_f32_e32 v81, v81, v161
	v_add_f32_e32 v82, v82, v162
	v_add_f32_e32 v83, v83, v163
	v_add_f32_e32 v72, v72, v164
	v_add_f32_e32 v73, v73, v165
	v_add_f32_e32 v74, v74, v166
	v_add_f32_e32 v75, v75, v167
	v_mul_f32_e32 v80, s56, v80
	v_mul_f32_e32 v81, s56, v81
	v_mul_f32_e32 v82, s56, v82
	v_mul_f32_e32 v83, s56, v83
	v_mul_f32_e32 v72, s56, v72
	v_mul_f32_e32 v73, s56, v73
	v_mul_f32_e32 v74, s56, v74
	v_mul_f32_e32 v75, s56, v75
	v_cvt_pk_bf16_f32 v80, v80, v81
	v_cvt_pk_bf16_f32 v81, v82, v83
	v_cvt_pk_bf16_f32 v82, v72, v73
	v_cvt_pk_bf16_f32 v83, v74, v75
	global_store_dwordx4 v148, v[80:83], s[40:41] offset:256
	global_load_dwordx4 v[108:111], v144, s[46:47] offset:0 sc1
	s_add_u32 s46, s48, 0x1000
	s_addc_u32 s47, s49, 0
	global_load_dwordx4 v[104:107], v144, s[46:47] offset:2048 sc1
	s_waitcnt vmcnt(20)
	s_add_u32 s40, s34, 0x18000
	s_addc_u32 s41, s35, 0
	s_sub_u32 s42, s36, 0x18000
	s_subb_u32 s43, s37, 0
	v_fma_f32 v190, v190, 2.0, -v84
	v_fma_f32 v191, v191, 2.0, -v85
	v_fma_f32 v192, v192, 2.0, -v86
	v_fma_f32 v193, v193, 2.0, -v87
	v_fma_f32 v194, v194, 2.0, -v76
	v_fma_f32 v195, v195, 2.0, -v77
	v_fma_f32 v196, v196, 2.0, -v78
	v_fma_f32 v197, v197, 2.0, -v79
	v_add_f32_e32 v190, v190, v152
	v_add_f32_e32 v191, v191, v153
	v_add_f32_e32 v192, v192, v154
	v_add_f32_e32 v193, v193, v155
	v_add_f32_e32 v194, v194, v156
	v_add_f32_e32 v195, v195, v157
	v_add_f32_e32 v196, v196, v158
	v_add_f32_e32 v197, v197, v159
	v_mul_f32_e32 v190, s56, v190
	v_mul_f32_e32 v191, s56, v191
	v_mul_f32_e32 v192, s56, v192
	v_mul_f32_e32 v193, s56, v193
	v_mul_f32_e32 v194, s56, v194
	v_mul_f32_e32 v195, s56, v195
	v_mul_f32_e32 v196, s56, v196
	v_mul_f32_e32 v197, s56, v197
	v_cvt_pk_bf16_f32 v190, v190, v191
	v_cvt_pk_bf16_f32 v191, v192, v193
	v_cvt_pk_bf16_f32 v192, v194, v195
	v_cvt_pk_bf16_f32 v193, v196, v197
	global_store_dwordx4 v149, v[190:193], s[42:43] offset:0
	v_add_f32_e32 v84, v84, v152
	v_add_f32_e32 v85, v85, v153
	v_add_f32_e32 v86, v86, v154
	v_add_f32_e32 v87, v87, v155
	v_add_f32_e32 v76, v76, v156
	v_add_f32_e32 v77, v77, v157
	v_add_f32_e32 v78, v78, v158
	v_add_f32_e32 v79, v79, v159
	v_mul_f32_e32 v84, s56, v84
	v_mul_f32_e32 v85, s56, v85
	v_mul_f32_e32 v86, s56, v86
	v_mul_f32_e32 v87, s56, v87
	v_mul_f32_e32 v76, s56, v76
	v_mul_f32_e32 v77, s56, v77
	v_mul_f32_e32 v78, s56, v78
	v_mul_f32_e32 v79, s56, v79
	v_cvt_pk_bf16_f32 v84, v84, v85
	v_cvt_pk_bf16_f32 v85, v86, v87
	v_cvt_pk_bf16_f32 v86, v76, v77
	v_cvt_pk_bf16_f32 v87, v78, v79
	global_store_dwordx4 v148, v[84:87], s[40:41] offset:0
	s_add_u32 s46, s48, 0x2000
	s_addc_u32 s47, s49, 0
	global_load_dwordx4 v[214:217], v144, s[46:47] offset:1024 sc1
	s_add_u32 s46, s48, 0x1000
	s_addc_u32 s47, s49, 0
	global_load_dwordx4 v[218:221], v144, s[46:47] offset:3072 sc1
	s_waitcnt vmcnt(20)
	v_fma_f32 v124, v124, 2.0, -v68
	v_fma_f32 v125, v125, 2.0, -v69
	v_fma_f32 v126, v126, 2.0, -v70
	v_fma_f32 v127, v127, 2.0, -v71
	v_fma_f32 v120, v120, 2.0, -v64
	v_fma_f32 v121, v121, 2.0, -v65
	v_fma_f32 v122, v122, 2.0, -v66
	v_fma_f32 v123, v123, 2.0, -v67
	v_add_f32_e32 v124, v124, v160
	v_add_f32_e32 v125, v125, v161
	v_add_f32_e32 v126, v126, v162
	v_add_f32_e32 v127, v127, v163
	v_add_f32_e32 v120, v120, v164
	v_add_f32_e32 v121, v121, v165
	v_add_f32_e32 v122, v122, v166
	v_add_f32_e32 v123, v123, v167
	v_mul_f32_e32 v124, s56, v124
	v_mul_f32_e32 v125, s56, v125
	v_mul_f32_e32 v126, s56, v126
	v_mul_f32_e32 v127, s56, v127
	v_mul_f32_e32 v120, s56, v120
	v_mul_f32_e32 v121, s56, v121
	v_mul_f32_e32 v122, s56, v122
	v_mul_f32_e32 v123, s56, v123
	v_cvt_pk_bf16_f32 v124, v124, v125
	v_cvt_pk_bf16_f32 v125, v126, v127
	v_cvt_pk_bf16_f32 v126, v120, v121
	v_cvt_pk_bf16_f32 v127, v122, v123
	global_store_dwordx4 v149, v[124:127], s[42:43] offset:256
	v_add_f32_e32 v68, v68, v160
	v_add_f32_e32 v69, v69, v161
	v_add_f32_e32 v70, v70, v162
	v_add_f32_e32 v71, v71, v163
	v_add_f32_e32 v64, v64, v164
	v_add_f32_e32 v65, v65, v165
	v_add_f32_e32 v66, v66, v166
	v_add_f32_e32 v67, v67, v167
	v_mul_f32_e32 v68, s56, v68
	v_mul_f32_e32 v69, s56, v69
	v_mul_f32_e32 v70, s56, v70
	v_mul_f32_e32 v71, s56, v71
	v_mul_f32_e32 v64, s56, v64
	v_mul_f32_e32 v65, s56, v65
	v_mul_f32_e32 v66, s56, v66
	v_mul_f32_e32 v67, s56, v67
	v_cvt_pk_bf16_f32 v68, v68, v69
	v_cvt_pk_bf16_f32 v69, v70, v71
	v_cvt_pk_bf16_f32 v70, v64, v65
	v_cvt_pk_bf16_f32 v71, v66, v67
	global_store_dwordx4 v148, v[68:71], s[40:41] offset:256
	global_load_dwordx4 v[96:99], v144, s[46:47] offset:0 sc1
	s_add_u32 s46, s48, 0x0
	s_addc_u32 s47, s49, 0
	global_load_dwordx4 v[88:91], v144, s[46:47] offset:2048 sc1
	s_waitcnt vmcnt(20)
	s_add_u32 s40, s34, 0x40000
	s_addc_u32 s41, s35, 0
	s_sub_u32 s42, s36, 0x40000
	s_subb_u32 s43, s37, 0
	v_fma_f32 v198, v198, 2.0, -v60
	v_fma_f32 v199, v199, 2.0, -v61
	v_fma_f32 v200, v200, 2.0, -v62
	v_fma_f32 v201, v201, 2.0, -v63
	v_fma_f32 v202, v202, 2.0, -v56
	v_fma_f32 v203, v203, 2.0, -v57
	v_fma_f32 v204, v204, 2.0, -v58
	v_fma_f32 v205, v205, 2.0, -v59
	v_add_f32_e32 v198, v198, v152
	v_add_f32_e32 v199, v199, v153
	v_add_f32_e32 v200, v200, v154
	v_add_f32_e32 v201, v201, v155
	v_add_f32_e32 v202, v202, v156
	v_add_f32_e32 v203, v203, v157
	v_add_f32_e32 v204, v204, v158
	v_add_f32_e32 v205, v205, v159
	v_mul_f32_e32 v198, s56, v198
	v_mul_f32_e32 v199, s56, v199
	v_mul_f32_e32 v200, s56, v200
	v_mul_f32_e32 v201, s56, v201
	v_mul_f32_e32 v202, s56, v202
	v_mul_f32_e32 v203, s56, v203
	v_mul_f32_e32 v204, s56, v204
	v_mul_f32_e32 v205, s56, v205
	v_cvt_pk_bf16_f32 v198, v198, v199
	v_cvt_pk_bf16_f32 v199, v200, v201
	v_cvt_pk_bf16_f32 v200, v202, v203
	v_cvt_pk_bf16_f32 v201, v204, v205
	global_store_dwordx4 v149, v[198:201], s[42:43] offset:0
	v_add_f32_e32 v60, v60, v152
	v_add_f32_e32 v61, v61, v153
	v_add_f32_e32 v62, v62, v154
	v_add_f32_e32 v63, v63, v155
	v_add_f32_e32 v56, v56, v156
	v_add_f32_e32 v57, v57, v157
	v_add_f32_e32 v58, v58, v158
	v_add_f32_e32 v59, v59, v159
	v_mul_f32_e32 v60, s56, v60
	v_mul_f32_e32 v61, s56, v61
	v_mul_f32_e32 v62, s56, v62
	v_mul_f32_e32 v63, s56, v63
	v_mul_f32_e32 v56, s56, v56
	v_mul_f32_e32 v57, s56, v57
	v_mul_f32_e32 v58, s56, v58
	v_mul_f32_e32 v59, s56, v59
	v_cvt_pk_bf16_f32 v60, v60, v61
	v_cvt_pk_bf16_f32 v61, v62, v63
	v_cvt_pk_bf16_f32 v62, v56, v57
	v_cvt_pk_bf16_f32 v63, v58, v59
	global_store_dwordx4 v148, v[60:63], s[40:41] offset:0
	s_add_u32 s46, s48, 0x1000
	s_addc_u32 s47, s49, 0
	global_load_dwordx4 v[168:171], v144, s[46:47] offset:1024 sc1
	s_add_u32 s46, s48, 0x0
	s_addc_u32 s47, s49, 0
	global_load_dwordx4 v[172:175], v144, s[46:47] offset:3072 sc1
	s_waitcnt vmcnt(20)
	v_fma_f32 v116, v116, 2.0, -v48
	v_fma_f32 v117, v117, 2.0, -v49
	v_fma_f32 v118, v118, 2.0, -v50
	v_fma_f32 v119, v119, 2.0, -v51
	v_fma_f32 v112, v112, 2.0, -v40
	v_fma_f32 v113, v113, 2.0, -v41
	v_fma_f32 v114, v114, 2.0, -v42
	v_fma_f32 v115, v115, 2.0, -v43
	v_add_f32_e32 v116, v116, v160
	v_add_f32_e32 v117, v117, v161
	v_add_f32_e32 v118, v118, v162
	v_add_f32_e32 v119, v119, v163
	v_add_f32_e32 v112, v112, v164
	v_add_f32_e32 v113, v113, v165
	v_add_f32_e32 v114, v114, v166
	v_add_f32_e32 v115, v115, v167
	v_mul_f32_e32 v116, s56, v116
	v_mul_f32_e32 v117, s56, v117
	v_mul_f32_e32 v118, s56, v118
	v_mul_f32_e32 v119, s56, v119
	v_mul_f32_e32 v112, s56, v112
	v_mul_f32_e32 v113, s56, v113
	v_mul_f32_e32 v114, s56, v114
	v_mul_f32_e32 v115, s56, v115
	v_cvt_pk_bf16_f32 v116, v116, v117
	v_cvt_pk_bf16_f32 v117, v118, v119
	v_cvt_pk_bf16_f32 v118, v112, v113
	v_cvt_pk_bf16_f32 v119, v114, v115
	global_store_dwordx4 v149, v[116:119], s[42:43] offset:256
	v_add_f32_e32 v48, v48, v160
	v_add_f32_e32 v49, v49, v161
	v_add_f32_e32 v50, v50, v162
	v_add_f32_e32 v51, v51, v163
	v_add_f32_e32 v40, v40, v164
	v_add_f32_e32 v41, v41, v165
	v_add_f32_e32 v42, v42, v166
	v_add_f32_e32 v43, v43, v167
	v_mul_f32_e32 v48, s56, v48
	v_mul_f32_e32 v49, s56, v49
	v_mul_f32_e32 v50, s56, v50
	v_mul_f32_e32 v51, s56, v51
	v_mul_f32_e32 v40, s56, v40
	v_mul_f32_e32 v41, s56, v41
	v_mul_f32_e32 v42, s56, v42
	v_mul_f32_e32 v43, s56, v43
	v_cvt_pk_bf16_f32 v48, v48, v49
	v_cvt_pk_bf16_f32 v49, v50, v51
	v_cvt_pk_bf16_f32 v50, v40, v41
	v_cvt_pk_bf16_f32 v51, v42, v43
	global_store_dwordx4 v148, v[48:51], s[40:41] offset:256
	global_load_dwordx4 v[100:103], v144, s[46:47] offset:1024 sc1
	global_load_dwordx4 v[92:95], v144, s[46:47] offset:0 sc1
	s_waitcnt vmcnt(20)
	s_add_u32 s40, s34, 0x48000
	s_addc_u32 s41, s35, 0
	s_sub_u32 s42, s36, 0x48000
	s_subb_u32 s43, s37, 0
	v_fma_f32 v206, v206, 2.0, -v52
	v_fma_f32 v207, v207, 2.0, -v53
	v_fma_f32 v208, v208, 2.0, -v54
	v_fma_f32 v209, v209, 2.0, -v55
	v_fma_f32 v210, v210, 2.0, -v44
	v_fma_f32 v211, v211, 2.0, -v45
	v_fma_f32 v212, v212, 2.0, -v46
	v_fma_f32 v213, v213, 2.0, -v47
	v_add_f32_e32 v206, v206, v152
	v_add_f32_e32 v207, v207, v153
	v_add_f32_e32 v208, v208, v154
	v_add_f32_e32 v209, v209, v155
	v_add_f32_e32 v210, v210, v156
	v_add_f32_e32 v211, v211, v157
	v_add_f32_e32 v212, v212, v158
	v_add_f32_e32 v213, v213, v159
	v_mul_f32_e32 v206, s56, v206
	v_mul_f32_e32 v207, s56, v207
	v_mul_f32_e32 v208, s56, v208
	v_mul_f32_e32 v209, s56, v209
	v_mul_f32_e32 v210, s56, v210
	v_mul_f32_e32 v211, s56, v211
	v_mul_f32_e32 v212, s56, v212
	v_mul_f32_e32 v213, s56, v213
	v_cvt_pk_bf16_f32 v206, v206, v207
	v_cvt_pk_bf16_f32 v207, v208, v209
	v_cvt_pk_bf16_f32 v208, v210, v211
	v_cvt_pk_bf16_f32 v209, v212, v213
	global_store_dwordx4 v149, v[206:209], s[42:43] offset:0
	v_add_f32_e32 v52, v52, v152
	v_add_f32_e32 v53, v53, v153
	v_add_f32_e32 v54, v54, v154
	v_add_f32_e32 v55, v55, v155
	v_add_f32_e32 v44, v44, v156
	v_add_f32_e32 v45, v45, v157
	v_add_f32_e32 v46, v46, v158
	v_add_f32_e32 v47, v47, v159
	v_mul_f32_e32 v52, s56, v52
	v_mul_f32_e32 v53, s56, v53
	v_mul_f32_e32 v54, s56, v54
	v_mul_f32_e32 v55, s56, v55
	v_mul_f32_e32 v44, s56, v44
	v_mul_f32_e32 v45, s56, v45
	v_mul_f32_e32 v46, s56, v46
	v_mul_f32_e32 v47, s56, v47
	v_cvt_pk_bf16_f32 v52, v52, v53
	v_cvt_pk_bf16_f32 v53, v54, v55
	v_cvt_pk_bf16_f32 v54, v44, v45
	v_cvt_pk_bf16_f32 v55, v46, v47
	global_store_dwordx4 v148, v[52:55], s[40:41] offset:0
	s_waitcnt vmcnt(18)
	v_fma_f32 v108, v108, 2.0, -v32
	v_fma_f32 v109, v109, 2.0, -v33
	v_fma_f32 v110, v110, 2.0, -v34
	v_fma_f32 v111, v111, 2.0, -v35
	v_fma_f32 v104, v104, 2.0, -v24
	v_fma_f32 v105, v105, 2.0, -v25
	v_fma_f32 v106, v106, 2.0, -v26
	v_fma_f32 v107, v107, 2.0, -v27
	v_add_f32_e32 v108, v108, v160
	v_add_f32_e32 v109, v109, v161
	v_add_f32_e32 v110, v110, v162
	v_add_f32_e32 v111, v111, v163
	v_add_f32_e32 v104, v104, v164
	v_add_f32_e32 v105, v105, v165
	v_add_f32_e32 v106, v106, v166
	v_add_f32_e32 v107, v107, v167
	v_mul_f32_e32 v108, s56, v108
	v_mul_f32_e32 v109, s56, v109
	v_mul_f32_e32 v110, s56, v110
	v_mul_f32_e32 v111, s56, v111
	v_mul_f32_e32 v104, s56, v104
	v_mul_f32_e32 v105, s56, v105
	v_mul_f32_e32 v106, s56, v106
	v_mul_f32_e32 v107, s56, v107
	v_cvt_pk_bf16_f32 v108, v108, v109
	v_cvt_pk_bf16_f32 v109, v110, v111
	v_cvt_pk_bf16_f32 v110, v104, v105
	v_cvt_pk_bf16_f32 v111, v106, v107
	global_store_dwordx4 v149, v[108:111], s[42:43] offset:256
	v_add_f32_e32 v32, v32, v160
	v_add_f32_e32 v33, v33, v161
	v_add_f32_e32 v34, v34, v162
	v_add_f32_e32 v35, v35, v163
	v_add_f32_e32 v24, v24, v164
	v_add_f32_e32 v25, v25, v165
	v_add_f32_e32 v26, v26, v166
	v_add_f32_e32 v27, v27, v167
	v_mul_f32_e32 v32, s56, v32
	v_mul_f32_e32 v33, s56, v33
	v_mul_f32_e32 v34, s56, v34
	v_mul_f32_e32 v35, s56, v35
	v_mul_f32_e32 v24, s56, v24
	v_mul_f32_e32 v25, s56, v25
	v_mul_f32_e32 v26, s56, v26
	v_mul_f32_e32 v27, s56, v27
	v_cvt_pk_bf16_f32 v32, v32, v33
	v_cvt_pk_bf16_f32 v33, v34, v35
	v_cvt_pk_bf16_f32 v34, v24, v25
	v_cvt_pk_bf16_f32 v35, v26, v27
	global_store_dwordx4 v148, v[32:35], s[40:41] offset:256
	s_waitcnt vmcnt(16)
	s_add_u32 s40, s34, 0x50000
	s_addc_u32 s41, s35, 0
	s_sub_u32 s42, s36, 0x50000
	s_subb_u32 s43, s37, 0
	v_fma_f32 v214, v214, 2.0, -v36
	v_fma_f32 v215, v215, 2.0, -v37
	v_fma_f32 v216, v216, 2.0, -v38
	v_fma_f32 v217, v217, 2.0, -v39
	v_fma_f32 v218, v218, 2.0, -v28
	v_fma_f32 v219, v219, 2.0, -v29
	v_fma_f32 v220, v220, 2.0, -v30
	v_fma_f32 v221, v221, 2.0, -v31
	v_add_f32_e32 v214, v214, v152
	v_add_f32_e32 v215, v215, v153
	v_add_f32_e32 v216, v216, v154
	v_add_f32_e32 v217, v217, v155
	v_add_f32_e32 v218, v218, v156
	v_add_f32_e32 v219, v219, v157
	v_add_f32_e32 v220, v220, v158
	v_add_f32_e32 v221, v221, v159
	v_mul_f32_e32 v214, s56, v214
	v_mul_f32_e32 v215, s56, v215
	v_mul_f32_e32 v216, s56, v216
	v_mul_f32_e32 v217, s56, v217
	v_mul_f32_e32 v218, s56, v218
	v_mul_f32_e32 v219, s56, v219
	v_mul_f32_e32 v220, s56, v220
	v_mul_f32_e32 v221, s56, v221
	v_cvt_pk_bf16_f32 v214, v214, v215
	v_cvt_pk_bf16_f32 v215, v216, v217
	v_cvt_pk_bf16_f32 v216, v218, v219
	v_cvt_pk_bf16_f32 v217, v220, v221
	global_store_dwordx4 v149, v[214:217], s[42:43] offset:0
	v_add_f32_e32 v36, v36, v152
	v_add_f32_e32 v37, v37, v153
	v_add_f32_e32 v38, v38, v154
	v_add_f32_e32 v39, v39, v155
	v_add_f32_e32 v28, v28, v156
	v_add_f32_e32 v29, v29, v157
	v_add_f32_e32 v30, v30, v158
	v_add_f32_e32 v31, v31, v159
	v_mul_f32_e32 v36, s56, v36
	v_mul_f32_e32 v37, s56, v37
	v_mul_f32_e32 v38, s56, v38
	v_mul_f32_e32 v39, s56, v39
	v_mul_f32_e32 v28, s56, v28
	v_mul_f32_e32 v29, s56, v29
	v_mul_f32_e32 v30, s56, v30
	v_mul_f32_e32 v31, s56, v31
	v_cvt_pk_bf16_f32 v36, v36, v37
	v_cvt_pk_bf16_f32 v37, v38, v39
	v_cvt_pk_bf16_f32 v38, v28, v29
	v_cvt_pk_bf16_f32 v39, v30, v31
	global_store_dwordx4 v148, v[36:39], s[40:41] offset:0
	s_waitcnt vmcnt(14)
	v_fma_f32 v96, v96, 2.0, -v16
	v_fma_f32 v97, v97, 2.0, -v17
	v_fma_f32 v98, v98, 2.0, -v18
	v_fma_f32 v99, v99, 2.0, -v19
	v_fma_f32 v88, v88, 2.0, -v8
	v_fma_f32 v89, v89, 2.0, -v9
	v_fma_f32 v90, v90, 2.0, -v10
	v_fma_f32 v91, v91, 2.0, -v11
	v_add_f32_e32 v96, v96, v160
	v_add_f32_e32 v97, v97, v161
	v_add_f32_e32 v98, v98, v162
	v_add_f32_e32 v99, v99, v163
	v_add_f32_e32 v88, v88, v164
	v_add_f32_e32 v89, v89, v165
	v_add_f32_e32 v90, v90, v166
	v_add_f32_e32 v91, v91, v167
	v_mul_f32_e32 v96, s56, v96
	v_mul_f32_e32 v97, s56, v97
	v_mul_f32_e32 v98, s56, v98
	v_mul_f32_e32 v99, s56, v99
	v_mul_f32_e32 v88, s56, v88
	v_mul_f32_e32 v89, s56, v89
	v_mul_f32_e32 v90, s56, v90
	v_mul_f32_e32 v91, s56, v91
	v_cvt_pk_bf16_f32 v96, v96, v97
	v_cvt_pk_bf16_f32 v97, v98, v99
	v_cvt_pk_bf16_f32 v98, v88, v89
	v_cvt_pk_bf16_f32 v99, v90, v91
	global_store_dwordx4 v149, v[96:99], s[42:43] offset:256
	v_add_f32_e32 v16, v16, v160
	v_add_f32_e32 v17, v17, v161
	v_add_f32_e32 v18, v18, v162
	v_add_f32_e32 v19, v19, v163
	v_add_f32_e32 v8, v8, v164
	v_add_f32_e32 v9, v9, v165
	v_add_f32_e32 v10, v10, v166
	v_add_f32_e32 v11, v11, v167
	v_mul_f32_e32 v16, s56, v16
	v_mul_f32_e32 v17, s56, v17
	v_mul_f32_e32 v18, s56, v18
	v_mul_f32_e32 v19, s56, v19
	v_mul_f32_e32 v8, s56, v8
	v_mul_f32_e32 v9, s56, v9
	v_mul_f32_e32 v10, s56, v10
	v_mul_f32_e32 v11, s56, v11
	v_cvt_pk_bf16_f32 v16, v16, v17
	v_cvt_pk_bf16_f32 v17, v18, v19
	v_cvt_pk_bf16_f32 v18, v8, v9
	v_cvt_pk_bf16_f32 v19, v10, v11
	global_store_dwordx4 v148, v[16:19], s[40:41] offset:256
	s_waitcnt vmcnt(12)
	s_add_u32 s40, s34, 0x58000
	s_addc_u32 s41, s35, 0
	s_sub_u32 s42, s36, 0x58000
	s_subb_u32 s43, s37, 0
	v_fma_f32 v168, v168, 2.0, -v20
	v_fma_f32 v169, v169, 2.0, -v21
	v_fma_f32 v170, v170, 2.0, -v22
	v_fma_f32 v171, v171, 2.0, -v23
	v_fma_f32 v172, v172, 2.0, -v12
	v_fma_f32 v173, v173, 2.0, -v13
	v_fma_f32 v174, v174, 2.0, -v14
	v_fma_f32 v175, v175, 2.0, -v15
	v_add_f32_e32 v168, v168, v152
	v_add_f32_e32 v169, v169, v153
	v_add_f32_e32 v170, v170, v154
	v_add_f32_e32 v171, v171, v155
	v_add_f32_e32 v172, v172, v156
	v_add_f32_e32 v173, v173, v157
	v_add_f32_e32 v174, v174, v158
	v_add_f32_e32 v175, v175, v159
	v_mul_f32_e32 v168, s56, v168
	v_mul_f32_e32 v169, s56, v169
	v_mul_f32_e32 v170, s56, v170
	v_mul_f32_e32 v171, s56, v171
	v_mul_f32_e32 v172, s56, v172
	v_mul_f32_e32 v173, s56, v173
	v_mul_f32_e32 v174, s56, v174
	v_mul_f32_e32 v175, s56, v175
	v_cvt_pk_bf16_f32 v168, v168, v169
	v_cvt_pk_bf16_f32 v169, v170, v171
	v_cvt_pk_bf16_f32 v170, v172, v173
	v_cvt_pk_bf16_f32 v171, v174, v175
	global_store_dwordx4 v149, v[168:171], s[42:43] offset:0
	v_add_f32_e32 v20, v20, v152
	v_add_f32_e32 v21, v21, v153
	v_add_f32_e32 v22, v22, v154
	v_add_f32_e32 v23, v23, v155
	v_add_f32_e32 v12, v12, v156
	v_add_f32_e32 v13, v13, v157
	v_add_f32_e32 v14, v14, v158
	v_add_f32_e32 v15, v15, v159
	v_mul_f32_e32 v20, s56, v20
	v_mul_f32_e32 v21, s56, v21
	v_mul_f32_e32 v22, s56, v22
	v_mul_f32_e32 v23, s56, v23
	v_mul_f32_e32 v12, s56, v12
	v_mul_f32_e32 v13, s56, v13
	v_mul_f32_e32 v14, s56, v14
	v_mul_f32_e32 v15, s56, v15
	v_cvt_pk_bf16_f32 v20, v20, v21
	v_cvt_pk_bf16_f32 v21, v22, v23
	v_cvt_pk_bf16_f32 v22, v12, v13
	v_cvt_pk_bf16_f32 v23, v14, v15
	global_store_dwordx4 v148, v[20:23], s[40:41] offset:0
	s_waitcnt vmcnt(10)
	v_fma_f32 v100, v100, 2.0, -v4
	v_fma_f32 v101, v101, 2.0, -v5
	v_fma_f32 v102, v102, 2.0, -v6
	v_fma_f32 v103, v103, 2.0, -v7
	v_fma_f32 v92, v92, 2.0, -v0
	v_fma_f32 v93, v93, 2.0, -v1
	v_fma_f32 v94, v94, 2.0, -v2
	v_fma_f32 v95, v95, 2.0, -v3
	v_add_f32_e32 v100, v100, v160
	v_add_f32_e32 v101, v101, v161
	v_add_f32_e32 v102, v102, v162
	v_add_f32_e32 v103, v103, v163
	v_add_f32_e32 v92, v92, v164
	v_add_f32_e32 v93, v93, v165
	v_add_f32_e32 v94, v94, v166
	v_add_f32_e32 v95, v95, v167
	v_mul_f32_e32 v100, s56, v100
	v_mul_f32_e32 v101, s56, v101
	v_mul_f32_e32 v102, s56, v102
	v_mul_f32_e32 v103, s56, v103
	v_mul_f32_e32 v92, s56, v92
	v_mul_f32_e32 v93, s56, v93
	v_mul_f32_e32 v94, s56, v94
	v_mul_f32_e32 v95, s56, v95
	v_cvt_pk_bf16_f32 v100, v100, v101
	v_cvt_pk_bf16_f32 v101, v102, v103
	v_cvt_pk_bf16_f32 v102, v92, v93
	v_cvt_pk_bf16_f32 v103, v94, v95
	global_store_dwordx4 v149, v[100:103], s[42:43] offset:256
	v_add_f32_e32 v4, v4, v160
	v_add_f32_e32 v5, v5, v161
	v_add_f32_e32 v6, v6, v162
	v_add_f32_e32 v7, v7, v163
	v_add_f32_e32 v0, v0, v164
	v_add_f32_e32 v1, v1, v165
	v_add_f32_e32 v2, v2, v166
	v_add_f32_e32 v3, v3, v167
	v_mul_f32_e32 v4, s56, v4
	v_mul_f32_e32 v5, s56, v5
	v_mul_f32_e32 v6, s56, v6
	v_mul_f32_e32 v7, s56, v7
	v_mul_f32_e32 v0, s56, v0
	v_mul_f32_e32 v1, s56, v1
	v_mul_f32_e32 v2, s56, v2
	v_mul_f32_e32 v3, s56, v3
	v_cvt_pk_bf16_f32 v4, v4, v5
	v_cvt_pk_bf16_f32 v5, v6, v7
	v_cvt_pk_bf16_f32 v6, v0, v1
	v_cvt_pk_bf16_f32 v7, v2, v3
	global_store_dwordx4 v148, v[4:7], s[40:41] offset:256
	s_branch .Ldfl_end
.Ldfl_xepi:
	s_lshl_b32 s46, s52, 11
	s_lshl_b32 s47, s3, 2
	s_add_i32 s46, s46, s47
	s_add_i32 s46, s46, 0x34000
	s_add_u32 s46, s94, s46
	s_addc_u32 s47, s95, 0
	v_or_b32_e32 v145, s71, v129
	v_lshlrev_b32_e32 v146, 2, v145
	global_load_dwordx4 v[152:155], v146, s[46:47] offset:0
	global_load_dwordx4 v[156:159], v146, s[46:47] offset:16
	global_load_dwordx4 v[160:163], v146, s[46:47] offset:512
	global_load_dwordx4 v[164:167], v146, s[46:47] offset:528
	v_and_b32_e32 v147, 1, v140
	v_lshlrev_b32_e32 v147, 31, v147
	v_lshlrev_b32_e32 v148, 11, v128
	v_lshl_add_u32 v148, v145, 1, v148
	s_lshl_b32 s34, s52, 12
	s_addk_i32 s34, 0x4000
	s_add_i32 s36, s34, 0xf81
	s_sub_i32 s36, s36, s58
	s_or_b32 s34, s34, s58
	s_lshl_b32 s34, s34, 11
	s_lshl_b32 s36, s36, 11
	s_lshl_b32 s0, s3, 1
	s_add_i32 s0, s0, 0x4b00400
	s_add_i32 s34, s34, s0
	s_add_i32 s36, s36, s0
	s_add_u32 s34, s94, s34
	s_addc_u32 s35, s95, 0
	s_add_u32 s36, s94, s36
	s_addc_u32 s37, s95, 0
	s_waitcnt vmcnt(0)
	v_xor_b32_e32 v152, v147, v152
	v_xor_b32_e32 v153, v147, v153
	v_xor_b32_e32 v154, v147, v154
	v_xor_b32_e32 v155, v147, v155
	v_xor_b32_e32 v156, v147, v156
	v_xor_b32_e32 v157, v147, v157
	v_xor_b32_e32 v158, v147, v158
	v_xor_b32_e32 v159, v147, v159
	v_xor_b32_e32 v160, v147, v160
	v_xor_b32_e32 v161, v147, v161
	v_xor_b32_e32 v162, v147, v162
	v_xor_b32_e32 v163, v147, v163
	v_xor_b32_e32 v164, v147, v164
	v_xor_b32_e32 v165, v147, v165
	v_xor_b32_e32 v166, v147, v166
	v_xor_b32_e32 v167, v147, v167
	v_cmp_eq_u32_e32 vcc, 0, v128
	s_and_saveexec_b64 s[80:81], vcc
	v_add_f32_e32 v124, v124, v152
	v_add_f32_e32 v125, v125, v153
	v_add_f32_e32 v126, v126, v154
	v_add_f32_e32 v127, v127, v155
	v_add_f32_e32 v120, v120, v156
	v_add_f32_e32 v121, v121, v157
	v_add_f32_e32 v122, v122, v158
	v_add_f32_e32 v123, v123, v159
	v_mul_f32_e32 v124, s56, v124
	v_mul_f32_e32 v125, s56, v125
	v_mul_f32_e32 v126, s56, v126
	v_mul_f32_e32 v127, s56, v127
	v_mul_f32_e32 v120, s56, v120
	v_mul_f32_e32 v121, s56, v121
	v_mul_f32_e32 v122, s56, v122
	v_mul_f32_e32 v123, s56, v123
	v_cvt_pk_bf16_f32 v124, v124, v125
	v_cvt_pk_bf16_f32 v125, v126, v127
	v_cvt_pk_bf16_f32 v126, v120, v121
	v_cvt_pk_bf16_f32 v127, v122, v123
	global_store_dwordx4 v148, v[124:127], s[34:35] offset:0
	v_add_f32_e32 v116, v116, v160
	v_add_f32_e32 v117, v117, v161
	v_add_f32_e32 v118, v118, v162
	v_add_f32_e32 v119, v119, v163
	v_add_f32_e32 v112, v112, v164
	v_add_f32_e32 v113, v113, v165
	v_add_f32_e32 v114, v114, v166
	v_add_f32_e32 v115, v115, v167
	v_mul_f32_e32 v116, s56, v116
	v_mul_f32_e32 v117, s56, v117
	v_mul_f32_e32 v118, s56, v118
	v_mul_f32_e32 v119, s56, v119
	v_mul_f32_e32 v112, s56, v112
	v_mul_f32_e32 v113, s56, v113
	v_mul_f32_e32 v114, s56, v114
	v_mul_f32_e32 v115, s56, v115
	v_cvt_pk_bf16_f32 v116, v116, v117
	v_cvt_pk_bf16_f32 v117, v118, v119
	v_cvt_pk_bf16_f32 v118, v112, v113
	v_cvt_pk_bf16_f32 v119, v114, v115
	global_store_dwordx4 v148, v[116:119], s[34:35] offset:256
	s_mov_b64 exec, s[80:81]
